# v18 + non-temporal (nt) hint on the once-read f32 weight loads of all weight-conversion loops
# baseline (speedup 1.0000x reference)
.LBB0_15:
	s_add_i32 s4, s12, 0xdb80
	s_and_b32 s8, s4, 0xffff
	s_mul_i32 s8, s8, 0xaaab
	s_lshr_b32 s9, s8, 16
	s_lshr_b32 s8, s8, 23
	s_mulk_i32 s8, 0xc0
	s_load_dwordx16 s[48:63], s[0:1], 0x40
	s_sub_i32 s8, s4, s8
	s_lshl_b32 s8, s8, 6
	s_and_b32 s8, s8, 0xffc0
	s_and_b32 s4, s9, 0xff80
	v_add_u32_e32 v6, s8, v140
	s_waitcnt lgkmcnt(0)
	v_lshl_add_u64 v[2:3], v[6:7], 2, s[48:49]
	s_mul_i32 s10, s4, 0x1e040
	s_mov_b32 s11, s5
	v_lshl_add_u64 v[2:3], v[2:3], 0, s[10:11]
	s_mov_b32 s9, 0x1e000
	v_add_co_u32_e32 v12, vcc, s9, v2
	s_mov_b32 s9, 0x3c000
	s_nop 0
	v_addc_co_u32_e32 v13, vcc, 0, v3, vcc
	global_load_dword v4, v[2:3], off nt
	global_load_dword v5, v[12:13], off offset:64
	v_add_co_u32_e32 v12, vcc, s9, v2
	s_mov_b32 s9, 0x5a000
	s_nop 0
	v_addc_co_u32_e32 v13, vcc, 0, v3, vcc
	global_load_dword v6, v[12:13], off offset:128
	v_add_co_u32_e32 v12, vcc, s9, v2
	s_mov_b32 s9, 0x78000
	s_nop 0
	v_addc_co_u32_e32 v13, vcc, 0, v3, vcc
	global_load_dword v11, v[12:13], off offset:192
	v_add_co_u32_e32 v12, vcc, s9, v2
	s_mov_b32 s9, 0x96000
	s_nop 0
	v_addc_co_u32_e32 v13, vcc, 0, v3, vcc
	v_add_co_u32_e32 v14, vcc, s9, v2
	s_mov_b32 s9, 0xb4000
	s_nop 0
	v_addc_co_u32_e32 v15, vcc, 0, v3, vcc
	global_load_dword v12, v[12:13], off offset:256
	v_readlane_b32 s10, v248, 46
	global_load_dword v13, v[14:15], off offset:320
	v_add_co_u32_e32 v14, vcc, s9, v2
	s_mov_b32 s9, 0xd2000
	s_nop 0
	v_addc_co_u32_e32 v15, vcc, 0, v3, vcc
	v_add_co_u32_e32 v16, vcc, s9, v2
	s_mov_b32 s9, 0xf0000
	s_nop 0
	v_addc_co_u32_e32 v17, vcc, 0, v3, vcc
	global_load_dword v14, v[14:15], off offset:384
	v_readlane_b32 s11, v248, 47
	global_load_dword v15, v[16:17], off offset:448
	v_add_co_u32_e32 v16, vcc, s9, v2
	s_mov_b32 s9, 0x10e000
	s_nop 0
	v_addc_co_u32_e32 v17, vcc, 0, v3, vcc
	v_add_co_u32_e32 v18, vcc, s9, v2
	s_mov_b32 s9, 0x12c000
	s_nop 0
	v_addc_co_u32_e32 v19, vcc, 0, v3, vcc
	global_load_dword v16, v[16:17], off offset:512
	s_nop 0
	global_load_dword v17, v[18:19], off offset:576
	v_add_co_u32_e32 v18, vcc, s9, v2
	s_mov_b32 s9, 0x14a000
	s_nop 0
	v_addc_co_u32_e32 v19, vcc, 0, v3, vcc
	v_add_co_u32_e32 v20, vcc, s9, v2
	s_mov_b32 s9, 0x168000
	s_nop 0
	v_addc_co_u32_e32 v21, vcc, 0, v3, vcc
	global_load_dword v18, v[18:19], off offset:640
	s_nop 0
	global_load_dword v19, v[20:21], off offset:704
	v_add_co_u32_e32 v20, vcc, s9, v2
	s_mov_b32 s9, 0x186000
	s_nop 0
	v_addc_co_u32_e32 v21, vcc, 0, v3, vcc
	v_add_co_u32_e32 v22, vcc, s9, v2
	s_mov_b32 s9, 0x1a4000
	s_nop 0
	v_addc_co_u32_e32 v23, vcc, 0, v3, vcc
	global_load_dword v20, v[20:21], off offset:768
	s_nop 0
	global_load_dword v21, v[22:23], off offset:832
	v_add_co_u32_e32 v22, vcc, s9, v2
	s_mov_b32 s9, 0x1c2000
	s_nop 0
	v_addc_co_u32_e32 v23, vcc, 0, v3, vcc
	v_add_co_u32_e32 v24, vcc, s9, v2
	s_mov_b32 s9, 0x1e0000
	s_nop 0
	v_addc_co_u32_e32 v25, vcc, 0, v3, vcc
	v_add_co_u32_e32 v26, vcc, s9, v2
	s_mov_b32 s9, 0x1fe000
	s_nop 0
	v_addc_co_u32_e32 v27, vcc, 0, v3, vcc
	global_load_dword v22, v[22:23], off offset:896
	s_nop 0
	global_load_dword v24, v[24:25], off offset:960
	s_nop 0
	global_load_dword v23, v[26:27], off offset:1024
	v_add_co_u32_e32 v26, vcc, s9, v2
	s_mov_b32 s9, 0x21c000
	s_nop 0
	v_addc_co_u32_e32 v27, vcc, 0, v3, vcc
	global_load_dword v25, v[26:27], off offset:1088
	v_add_co_u32_e32 v26, vcc, s9, v2
	s_mov_b32 s9, 0x23a000
	s_nop 0
	v_addc_co_u32_e32 v27, vcc, 0, v3, vcc
	v_add_co_u32_e32 v28, vcc, s9, v2
	s_mov_b32 s9, 0x258000
	s_nop 0
	v_addc_co_u32_e32 v29, vcc, 0, v3, vcc
	global_load_dword v26, v[26:27], off offset:1152
	s_nop 0
	global_load_dword v27, v[28:29], off offset:1216
	v_add_co_u32_e32 v28, vcc, s9, v2
	s_mov_b32 s9, 0x276000
	s_nop 0
	v_addc_co_u32_e32 v29, vcc, 0, v3, vcc
	v_add_co_u32_e32 v30, vcc, s9, v2
	s_mov_b32 s9, 0x294000
	s_nop 0
	v_addc_co_u32_e32 v31, vcc, 0, v3, vcc
	global_load_dword v28, v[28:29], off offset:1280
	s_nop 0
	global_load_dword v29, v[30:31], off offset:1344
	v_add_co_u32_e32 v30, vcc, s9, v2
	s_mov_b32 s9, 0x2b2000
	s_nop 0
	v_addc_co_u32_e32 v31, vcc, 0, v3, vcc
	v_add_co_u32_e32 v32, vcc, s9, v2
	s_mov_b32 s9, 0x2d0000
	s_nop 0
	v_addc_co_u32_e32 v33, vcc, 0, v3, vcc
	global_load_dword v30, v[30:31], off offset:1408
	s_nop 0
	global_load_dword v31, v[32:33], off offset:1472
	v_add_co_u32_e32 v32, vcc, s9, v2
	s_mov_b32 s9, 0x2ee000
	s_nop 0
	v_addc_co_u32_e32 v33, vcc, 0, v3, vcc
	v_add_co_u32_e32 v34, vcc, s9, v2
	s_mov_b32 s9, 0x30c000
	s_nop 0
	v_addc_co_u32_e32 v35, vcc, 0, v3, vcc
	global_load_dword v32, v[32:33], off offset:1536
	s_nop 0
	global_load_dword v33, v[34:35], off offset:1600
	v_add_co_u32_e32 v34, vcc, s9, v2
	s_mov_b32 s9, 0x32a000
	s_nop 0
	v_addc_co_u32_e32 v35, vcc, 0, v3, vcc
	v_add_co_u32_e32 v36, vcc, s9, v2
	s_mov_b32 s9, 0x348000
	s_nop 0
	v_addc_co_u32_e32 v37, vcc, 0, v3, vcc
	global_load_dword v34, v[34:35], off offset:1664
	s_nop 0
	global_load_dword v35, v[36:37], off offset:1728
	v_add_co_u32_e32 v36, vcc, s9, v2
	s_mov_b32 s9, 0x366000
	s_nop 0
	v_addc_co_u32_e32 v37, vcc, 0, v3, vcc
	v_add_co_u32_e32 v38, vcc, s9, v2
	s_mov_b32 s9, 0x384000
	s_nop 0
	v_addc_co_u32_e32 v39, vcc, 0, v3, vcc
	global_load_dword v36, v[36:37], off offset:1792
	s_nop 0
	global_load_dword v37, v[38:39], off offset:1856
	v_add_co_u32_e32 v38, vcc, s9, v2
	s_mov_b32 s9, 0x3a2000
	s_nop 0
	v_addc_co_u32_e32 v39, vcc, 0, v3, vcc
	v_add_co_u32_e32 v40, vcc, s9, v2
	s_mov_b32 s9, 0x3c0000
	s_nop 0
	v_addc_co_u32_e32 v41, vcc, 0, v3, vcc
	v_add_co_u32_e32 v42, vcc, s9, v2
	s_mov_b32 s9, 0x3de000
	s_nop 0
	v_addc_co_u32_e32 v43, vcc, 0, v3, vcc
	global_load_dword v38, v[38:39], off offset:1920
	s_nop 0
	global_load_dword v40, v[40:41], off offset:1984
	s_nop 0
	global_load_dword v39, v[42:43], off offset:2048
	v_add_co_u32_e32 v42, vcc, s9, v2
	s_mov_b32 s9, 0x3fc000
	s_nop 0
	v_addc_co_u32_e32 v43, vcc, 0, v3, vcc
	global_load_dword v41, v[42:43], off offset:2112
	v_add_co_u32_e32 v42, vcc, s9, v2
	s_mov_b32 s9, 0x41a000
	s_nop 0
	v_addc_co_u32_e32 v43, vcc, 0, v3, vcc
	v_add_co_u32_e32 v44, vcc, s9, v2
	s_mov_b32 s9, 0x438000
	s_nop 0
	v_addc_co_u32_e32 v45, vcc, 0, v3, vcc
	global_load_dword v42, v[42:43], off offset:2176
	s_nop 0
	global_load_dword v43, v[44:45], off offset:2240
	v_add_co_u32_e32 v44, vcc, s9, v2
	s_mov_b32 s9, 0x456000
	s_nop 0
	v_addc_co_u32_e32 v45, vcc, 0, v3, vcc
	v_add_co_u32_e32 v46, vcc, s9, v2
	s_mov_b32 s9, 0x474000
	s_nop 0
	v_addc_co_u32_e32 v47, vcc, 0, v3, vcc
	global_load_dword v44, v[44:45], off offset:2304
	s_nop 0
	global_load_dword v45, v[46:47], off offset:2368
	v_add_co_u32_e32 v46, vcc, s9, v2
	s_mov_b32 s9, 0x492000
	s_nop 0
	v_addc_co_u32_e32 v47, vcc, 0, v3, vcc
	v_add_co_u32_e32 v48, vcc, s9, v2
	s_mov_b32 s9, 0x4b0000
	s_nop 0
	v_addc_co_u32_e32 v49, vcc, 0, v3, vcc
	global_load_dword v46, v[46:47], off offset:2432
	s_nop 0
	global_load_dword v47, v[48:49], off offset:2496
	v_add_co_u32_e32 v48, vcc, s9, v2
	s_mov_b32 s9, 0x4ce000
	s_nop 0
	v_addc_co_u32_e32 v49, vcc, 0, v3, vcc
	v_add_co_u32_e32 v50, vcc, s9, v2
	s_mov_b32 s9, 0x4ec000
	s_nop 0
	v_addc_co_u32_e32 v51, vcc, 0, v3, vcc
	global_load_dword v48, v[48:49], off offset:2560
	s_nop 0
	global_load_dword v49, v[50:51], off offset:2624
	v_add_co_u32_e32 v50, vcc, s9, v2
	s_mov_b32 s9, 0x50a000
	s_nop 0
	v_addc_co_u32_e32 v51, vcc, 0, v3, vcc
	v_add_co_u32_e32 v52, vcc, s9, v2
	s_mov_b32 s9, 0x528000
	s_nop 0
	v_addc_co_u32_e32 v53, vcc, 0, v3, vcc
	global_load_dword v50, v[50:51], off offset:2688
	s_nop 0
	global_load_dword v51, v[52:53], off offset:2752
	v_add_co_u32_e32 v52, vcc, s9, v2
	s_mov_b32 s9, 0x546000
	s_nop 0
	v_addc_co_u32_e32 v53, vcc, 0, v3, vcc
	v_add_co_u32_e32 v54, vcc, s9, v2
	s_mov_b32 s9, 0x564000
	s_nop 0
	v_addc_co_u32_e32 v55, vcc, 0, v3, vcc
	global_load_dword v52, v[52:53], off offset:2816
	s_nop 0
	global_load_dword v53, v[54:55], off offset:2880
	v_add_co_u32_e32 v54, vcc, s9, v2
	s_mov_b32 s9, 0x582000
	s_nop 0
	v_addc_co_u32_e32 v55, vcc, 0, v3, vcc
	v_add_co_u32_e32 v56, vcc, s9, v2
	s_mov_b32 s9, 0x5a0000
	s_nop 0
	v_addc_co_u32_e32 v57, vcc, 0, v3, vcc
	v_add_co_u32_e32 v58, vcc, s9, v2
	s_mov_b32 s9, 0x5be000
	s_nop 0
	v_addc_co_u32_e32 v59, vcc, 0, v3, vcc
	global_load_dword v54, v[54:55], off offset:2944
	s_nop 0
	global_load_dword v56, v[56:57], off offset:3008
	s_nop 0
	global_load_dword v55, v[58:59], off offset:3072
	v_add_co_u32_e32 v58, vcc, s9, v2
	s_mov_b32 s9, 0x5dc000
	s_nop 0
	v_addc_co_u32_e32 v59, vcc, 0, v3, vcc
	global_load_dword v57, v[58:59], off offset:3136
	v_add_co_u32_e32 v58, vcc, s9, v2
	s_mov_b32 s9, 0x5fa000
	s_nop 0
	v_addc_co_u32_e32 v59, vcc, 0, v3, vcc
	v_add_co_u32_e32 v60, vcc, s9, v2
	s_mov_b32 s9, 0x618000
	s_nop 0
	v_addc_co_u32_e32 v61, vcc, 0, v3, vcc
	global_load_dword v58, v[58:59], off offset:3200
	s_nop 0
	global_load_dword v59, v[60:61], off offset:3264
	v_add_co_u32_e32 v60, vcc, s9, v2
	s_mov_b32 s9, 0x636000
	s_nop 0
	v_addc_co_u32_e32 v61, vcc, 0, v3, vcc
	v_add_co_u32_e32 v62, vcc, s9, v2
	s_mov_b32 s9, 0x654000
	s_nop 0
	v_addc_co_u32_e32 v63, vcc, 0, v3, vcc
	global_load_dword v60, v[60:61], off offset:3328
	s_nop 0
	global_load_dword v61, v[62:63], off offset:3392
	v_add_co_u32_e32 v62, vcc, s9, v2
	s_mov_b32 s9, 0x672000
	s_nop 0
	v_addc_co_u32_e32 v63, vcc, 0, v3, vcc
	v_add_co_u32_e32 v64, vcc, s9, v2
	s_mov_b32 s9, 0x690000
	s_nop 0
	v_addc_co_u32_e32 v65, vcc, 0, v3, vcc
	global_load_dword v62, v[62:63], off offset:3456
	s_nop 0
	global_load_dword v63, v[64:65], off offset:3520
	v_add_co_u32_e32 v64, vcc, s9, v2
	s_mov_b32 s9, 0x6ae000
	s_nop 0
	v_addc_co_u32_e32 v65, vcc, 0, v3, vcc
	v_add_co_u32_e32 v66, vcc, s9, v2
	s_mov_b32 s9, 0x6cc000
	s_nop 0
	v_addc_co_u32_e32 v67, vcc, 0, v3, vcc
	global_load_dword v64, v[64:65], off offset:3584
	s_nop 0
	global_load_dword v65, v[66:67], off offset:3648
	v_add_co_u32_e32 v66, vcc, s9, v2
	s_mov_b32 s9, 0x6ea000
	s_nop 0
	v_addc_co_u32_e32 v67, vcc, 0, v3, vcc
	v_add_co_u32_e32 v68, vcc, s9, v2
	s_mov_b32 s9, 0x708000
	s_nop 0
	v_addc_co_u32_e32 v69, vcc, 0, v3, vcc
	global_load_dword v66, v[66:67], off offset:3712
	s_nop 0
	global_load_dword v67, v[68:69], off offset:3776
	v_add_co_u32_e32 v68, vcc, s9, v2
	s_mov_b32 s9, 0x726000
	s_nop 0
	v_addc_co_u32_e32 v69, vcc, 0, v3, vcc
	v_add_co_u32_e32 v70, vcc, s9, v2
	s_mov_b32 s9, 0x744000
	s_nop 0
	v_addc_co_u32_e32 v71, vcc, 0, v3, vcc
	global_load_dword v68, v[68:69], off offset:3840
	s_nop 0
	global_load_dword v69, v[70:71], off offset:3904
	v_add_co_u32_e32 v70, vcc, s9, v2
	s_mov_b32 s9, 0x762000
	s_nop 0
	v_addc_co_u32_e32 v71, vcc, 0, v3, vcc
	v_add_co_u32_e32 v72, vcc, s9, v2
	s_mov_b32 s9, 0x781000
	s_nop 0
	v_addc_co_u32_e32 v73, vcc, 0, v3, vcc
	v_add_co_u32_e32 v74, vcc, s9, v2
	s_mov_b32 s9, 0x79f000
	s_nop 0
	v_addc_co_u32_e32 v75, vcc, 0, v3, vcc
	global_load_dword v70, v[70:71], off offset:3968
	s_nop 0
	global_load_dword v72, v[72:73], off offset:4032
	s_nop 0
	global_load_dword v71, v[74:75], off nt
	v_add_co_u32_e32 v74, vcc, s9, v2
	s_mov_b32 s9, 0x7bd000
	s_nop 0
	v_addc_co_u32_e32 v75, vcc, 0, v3, vcc
	global_load_dword v73, v[74:75], off offset:64
	v_add_co_u32_e32 v74, vcc, s9, v2
	s_mov_b32 s9, 0x7db000
	s_nop 0
	v_addc_co_u32_e32 v75, vcc, 0, v3, vcc
	v_add_co_u32_e32 v76, vcc, s9, v2
	s_mov_b32 s9, 0x7f9000
	s_nop 0
	v_addc_co_u32_e32 v77, vcc, 0, v3, vcc
	global_load_dword v74, v[74:75], off offset:128
	s_nop 0
	global_load_dword v75, v[76:77], off offset:192
	v_add_co_u32_e32 v76, vcc, s9, v2
	s_mov_b32 s9, 0x817000
	s_nop 0
	v_addc_co_u32_e32 v77, vcc, 0, v3, vcc
	v_add_co_u32_e32 v78, vcc, s9, v2
	s_mov_b32 s9, 0x835000
	s_nop 0
	v_addc_co_u32_e32 v79, vcc, 0, v3, vcc
	global_load_dword v76, v[76:77], off offset:256
	s_nop 0
	global_load_dword v77, v[78:79], off offset:320
	v_add_co_u32_e32 v78, vcc, s9, v2
	s_mov_b32 s9, 0x853000
	s_nop 0
	v_addc_co_u32_e32 v79, vcc, 0, v3, vcc
	v_add_co_u32_e32 v80, vcc, s9, v2
	s_mov_b32 s9, 0x871000
	s_nop 0
	v_addc_co_u32_e32 v81, vcc, 0, v3, vcc
	global_load_dword v78, v[78:79], off offset:384
	s_nop 0
	global_load_dword v79, v[80:81], off offset:448
	v_add_co_u32_e32 v80, vcc, s9, v2
	s_mov_b32 s9, 0x88f000
	s_nop 0
	v_addc_co_u32_e32 v81, vcc, 0, v3, vcc
	v_add_co_u32_e32 v82, vcc, s9, v2
	s_mov_b32 s9, 0x8ad000
	s_nop 0
	v_addc_co_u32_e32 v83, vcc, 0, v3, vcc
	global_load_dword v80, v[80:81], off offset:512
	s_nop 0
	global_load_dword v81, v[82:83], off offset:576
	v_add_co_u32_e32 v82, vcc, s9, v2
	s_mov_b32 s9, 0x8cb000
	s_nop 0
	v_addc_co_u32_e32 v83, vcc, 0, v3, vcc
	v_add_co_u32_e32 v84, vcc, s9, v2
	s_mov_b32 s9, 0x8e9000
	s_nop 0
	v_addc_co_u32_e32 v85, vcc, 0, v3, vcc
	global_load_dword v82, v[82:83], off offset:640
	s_nop 0
	global_load_dword v83, v[84:85], off offset:704
	v_add_co_u32_e32 v84, vcc, s9, v2
	s_mov_b32 s9, 0x907000
	s_nop 0
	v_addc_co_u32_e32 v85, vcc, 0, v3, vcc
	v_add_co_u32_e32 v86, vcc, s9, v2
	s_mov_b32 s9, 0x925000
	s_nop 0
	v_addc_co_u32_e32 v87, vcc, 0, v3, vcc
	global_load_dword v84, v[84:85], off offset:768
	s_nop 0
	global_load_dword v85, v[86:87], off offset:832
	v_add_co_u32_e32 v86, vcc, s9, v2
	s_mov_b32 s9, 0x943000
	s_nop 0
	v_addc_co_u32_e32 v87, vcc, 0, v3, vcc
	v_add_co_u32_e32 v88, vcc, s9, v2
	s_mov_b32 s9, 0x961000
	s_nop 0
	v_addc_co_u32_e32 v89, vcc, 0, v3, vcc
	v_add_co_u32_e32 v90, vcc, s9, v2
	s_mov_b32 s9, 0x97f000
	s_nop 0
	v_addc_co_u32_e32 v91, vcc, 0, v3, vcc
	global_load_dword v86, v[86:87], off offset:896
	s_nop 0
	global_load_dword v88, v[88:89], off offset:960
	s_nop 0
	global_load_dword v87, v[90:91], off offset:1024
	v_add_co_u32_e32 v90, vcc, s9, v2
	s_mov_b32 s9, 0x99d000
	s_nop 0
	v_addc_co_u32_e32 v91, vcc, 0, v3, vcc
	global_load_dword v89, v[90:91], off offset:1088
	v_add_co_u32_e32 v90, vcc, s9, v2
	s_mov_b32 s9, 0x9bb000
	s_nop 0
	v_addc_co_u32_e32 v91, vcc, 0, v3, vcc
	v_add_co_u32_e32 v92, vcc, s9, v2
	s_mov_b32 s9, 0x9d9000
	s_nop 0
	v_addc_co_u32_e32 v93, vcc, 0, v3, vcc
	global_load_dword v90, v[90:91], off offset:1152
	s_nop 0
	global_load_dword v91, v[92:93], off offset:1216
	v_add_co_u32_e32 v92, vcc, s9, v2
	s_mov_b32 s9, 0x9f7000
	s_nop 0
	v_addc_co_u32_e32 v93, vcc, 0, v3, vcc
	v_add_co_u32_e32 v94, vcc, s9, v2
	s_mov_b32 s9, 0xa15000
	s_nop 0
	v_addc_co_u32_e32 v95, vcc, 0, v3, vcc
	global_load_dword v92, v[92:93], off offset:1280
	s_nop 0
	global_load_dword v93, v[94:95], off offset:1344
	v_add_co_u32_e32 v94, vcc, s9, v2
	s_mov_b32 s9, 0xa33000
	s_nop 0
	v_addc_co_u32_e32 v95, vcc, 0, v3, vcc
	v_add_co_u32_e32 v96, vcc, s9, v2
	s_mov_b32 s9, 0xa51000
	s_nop 0
	v_addc_co_u32_e32 v97, vcc, 0, v3, vcc
	global_load_dword v94, v[94:95], off offset:1408
	s_nop 0
	global_load_dword v95, v[96:97], off offset:1472
	v_add_co_u32_e32 v96, vcc, s9, v2
	s_mov_b32 s9, 0xa6f000
	s_nop 0
	v_addc_co_u32_e32 v97, vcc, 0, v3, vcc
	v_add_co_u32_e32 v98, vcc, s9, v2
	s_mov_b32 s9, 0xa8d000
	s_nop 0
	v_addc_co_u32_e32 v99, vcc, 0, v3, vcc
	global_load_dword v96, v[96:97], off offset:1536
	s_nop 0
	global_load_dword v97, v[98:99], off offset:1600
	v_add_co_u32_e32 v98, vcc, s9, v2
	s_mov_b32 s9, 0xaab000
	s_nop 0
	v_addc_co_u32_e32 v99, vcc, 0, v3, vcc
	v_add_co_u32_e32 v100, vcc, s9, v2
	s_mov_b32 s9, 0xac9000
	s_nop 0
	v_addc_co_u32_e32 v101, vcc, 0, v3, vcc
	global_load_dword v98, v[98:99], off offset:1664
	s_nop 0
	global_load_dword v99, v[100:101], off offset:1728
	v_add_co_u32_e32 v100, vcc, s9, v2
	s_mov_b32 s9, 0xae7000
	s_nop 0
	v_addc_co_u32_e32 v101, vcc, 0, v3, vcc
	v_add_co_u32_e32 v102, vcc, s9, v2
	s_mov_b32 s9, 0xb05000
	s_nop 0
	v_addc_co_u32_e32 v103, vcc, 0, v3, vcc
	global_load_dword v100, v[100:101], off offset:1792
	s_nop 0
	global_load_dword v101, v[102:103], off offset:1856
	v_add_co_u32_e32 v102, vcc, s9, v2
	s_mov_b32 s9, 0xb23000
	s_nop 0
	v_addc_co_u32_e32 v103, vcc, 0, v3, vcc
	v_add_co_u32_e32 v104, vcc, s9, v2
	s_mov_b32 s9, 0xb41000
	s_nop 0
	v_addc_co_u32_e32 v105, vcc, 0, v3, vcc
	v_add_co_u32_e32 v106, vcc, s9, v2
	s_mov_b32 s9, 0xb5f000
	s_nop 0
	v_addc_co_u32_e32 v107, vcc, 0, v3, vcc
	global_load_dword v102, v[102:103], off offset:1920
	s_nop 0
	global_load_dword v104, v[104:105], off offset:1984
	s_nop 0
	global_load_dword v103, v[106:107], off offset:2048
	v_add_co_u32_e32 v106, vcc, s9, v2
	s_mov_b32 s9, 0xb7d000
	s_nop 0
	v_addc_co_u32_e32 v107, vcc, 0, v3, vcc
	global_load_dword v105, v[106:107], off offset:2112
	v_add_co_u32_e32 v106, vcc, s9, v2
	s_mov_b32 s9, 0xb9b000
	s_nop 0
	v_addc_co_u32_e32 v107, vcc, 0, v3, vcc
	v_add_co_u32_e32 v108, vcc, s9, v2
	s_mov_b32 s9, 0xbb9000
	s_nop 0
	v_addc_co_u32_e32 v109, vcc, 0, v3, vcc
	global_load_dword v106, v[106:107], off offset:2176
	s_nop 0
	global_load_dword v107, v[108:109], off offset:2240
	v_add_co_u32_e32 v108, vcc, s9, v2
	s_mov_b32 s9, 0xbd7000
	s_nop 0
	v_addc_co_u32_e32 v109, vcc, 0, v3, vcc
	v_add_co_u32_e32 v110, vcc, s9, v2
	s_mov_b32 s9, 0xbf5000
	s_nop 0
	v_addc_co_u32_e32 v111, vcc, 0, v3, vcc
	global_load_dword v108, v[108:109], off offset:2304
	s_nop 0
	global_load_dword v109, v[110:111], off offset:2368
	v_add_co_u32_e32 v110, vcc, s9, v2
	s_mov_b32 s9, 0xc13000
	s_nop 0
	v_addc_co_u32_e32 v111, vcc, 0, v3, vcc
	v_add_co_u32_e32 v112, vcc, s9, v2
	s_mov_b32 s9, 0xc31000
	s_nop 0
	v_addc_co_u32_e32 v113, vcc, 0, v3, vcc
	global_load_dword v110, v[110:111], off offset:2432
	s_nop 0
	global_load_dword v111, v[112:113], off offset:2496
	v_add_co_u32_e32 v112, vcc, s9, v2
	s_mov_b32 s9, 0xc4f000
	s_nop 0
	v_addc_co_u32_e32 v113, vcc, 0, v3, vcc
	v_add_co_u32_e32 v114, vcc, s9, v2
	s_mov_b32 s9, 0xc6d000
	s_nop 0
	v_addc_co_u32_e32 v115, vcc, 0, v3, vcc
	global_load_dword v112, v[112:113], off offset:2560
	s_nop 0
	global_load_dword v113, v[114:115], off offset:2624
	v_add_co_u32_e32 v114, vcc, s9, v2
	s_mov_b32 s9, 0xc8b000
	s_nop 0
	v_addc_co_u32_e32 v115, vcc, 0, v3, vcc
	v_add_co_u32_e32 v116, vcc, s9, v2
	s_mov_b32 s9, 0xca9000
	s_nop 0
	v_addc_co_u32_e32 v117, vcc, 0, v3, vcc
	global_load_dword v114, v[114:115], off offset:2688
	s_nop 0
	global_load_dword v1, v[116:117], off offset:2752
	v_add_co_u32_e32 v116, vcc, s9, v2
	s_mov_b32 s9, 0xcc7000
	s_nop 0
	v_addc_co_u32_e32 v117, vcc, 0, v3, vcc
	global_load_dword v115, v[116:117], off offset:2816
	v_add_co_u32_e32 v116, vcc, s9, v2
	s_mov_b32 s9, 0xce5000
	s_nop 0
	v_addc_co_u32_e32 v117, vcc, 0, v3, vcc
	global_load_dword v118, v[116:117], off offset:2880
	v_add_co_u32_e32 v116, vcc, s9, v2
	s_mov_b32 s9, 0xd03000
	s_nop 0
	v_addc_co_u32_e32 v117, vcc, 0, v3, vcc
	global_load_dword v119, v[116:117], off offset:2944
	v_add_co_u32_e32 v116, vcc, s9, v2
	s_mov_b32 s9, 0xd21000
	s_nop 0
	v_addc_co_u32_e32 v117, vcc, 0, v3, vcc
	global_load_dword v120, v[116:117], off offset:3008
	v_add_co_u32_e32 v116, vcc, s9, v2
	s_mov_b32 s9, 0xd3f000
	s_nop 0
	v_addc_co_u32_e32 v117, vcc, 0, v3, vcc
	global_load_dword v121, v[116:117], off offset:3072
	v_add_co_u32_e32 v116, vcc, s9, v2
	s_mov_b32 s9, 0xd5d000
	s_nop 0
	v_addc_co_u32_e32 v117, vcc, 0, v3, vcc
	global_load_dword v122, v[116:117], off offset:3136
	v_add_co_u32_e32 v116, vcc, s9, v2
	v_readfirstlane_b32 s9, v0
	s_nop 0
	v_addc_co_u32_e32 v117, vcc, 0, v3, vcc
	global_load_dword v123, v[116:117], off offset:3200
	v_add_co_u32_e32 v116, vcc, s15, v2
	s_lshl_b32 s9, s9, 8
	s_nop 0
	v_addc_co_u32_e32 v117, vcc, 0, v3, vcc
	global_load_dword v124, v[116:117], off offset:3264
	v_add_co_u32_e32 v116, vcc, s16, v2
	s_and_b32 s9, s9, 0x7fffc000
	s_nop 0
	v_addc_co_u32_e32 v117, vcc, 0, v3, vcc
	global_load_dword v125, v[116:117], off offset:3328
	v_add_co_u32_e32 v116, vcc, s17, v2
	s_add_i32 s9, s9, 0
	s_nop 0
	v_addc_co_u32_e32 v117, vcc, 0, v3, vcc
	global_load_dword v126, v[116:117], off offset:3392
	v_add_co_u32_e32 v116, vcc, s18, v2
	v_add_u32_e32 v135, s9, v141
	s_nop 0
	v_addc_co_u32_e32 v117, vcc, 0, v3, vcc
	global_load_dword v127, v[116:117], off offset:3456
	v_add_co_u32_e32 v116, vcc, s19, v2
	s_waitcnt vmcnt(11)
	v_mul_f32_e32 v1, 0x42800000, v1
	v_addc_co_u32_e32 v117, vcc, 0, v3, vcc
	global_load_dword v128, v[116:117], off offset:3520
	v_add_co_u32_e32 v116, vcc, s20, v2
	s_nop 1
	v_addc_co_u32_e32 v117, vcc, 0, v3, vcc
	global_load_dword v129, v[116:117], off offset:3584
	v_add_co_u32_e32 v116, vcc, s21, v2
	s_nop 1
	v_addc_co_u32_e32 v117, vcc, 0, v3, vcc
	global_load_dword v130, v[116:117], off offset:3648
	v_add_co_u32_e32 v116, vcc, s22, v2
	s_nop 1
	v_addc_co_u32_e32 v117, vcc, 0, v3, vcc
	global_load_dword v131, v[116:117], off offset:3712
	v_add_co_u32_e32 v116, vcc, s23, v2
	s_nop 1
	v_addc_co_u32_e32 v117, vcc, 0, v3, vcc
	global_load_dword v132, v[116:117], off offset:3776
	v_add_co_u32_e32 v116, vcc, s24, v2
	s_nop 1
	v_addc_co_u32_e32 v117, vcc, 0, v3, vcc
	global_load_dword v133, v[116:117], off offset:3840
	v_add_co_u32_e32 v116, vcc, s25, v2
	s_nop 1
	v_addc_co_u32_e32 v117, vcc, 0, v3, vcc
	global_load_dword v134, v[116:117], off offset:3904
	v_add_co_u32_e32 v116, vcc, s26, v2
	s_nop 1
	v_addc_co_u32_e32 v117, vcc, 0, v3, vcc
	v_add_co_u32_e32 v2, vcc, s27, v2
	global_load_dword v116, v[116:117], off offset:3968
	s_nop 0
	v_addc_co_u32_e32 v3, vcc, 0, v3, vcc
	global_load_dword v117, v[2:3], off offset:4032
	v_mul_f32_e32 v3, 0x42800000, v4
	v_mul_f32_e32 v4, 0x42800000, v5
	v_mov_b32_e32 v2, v7
	v_cvt_pk_fp8_f32 v2, v3, v4
	v_mul_f32_e32 v5, 0x42800000, v6
	v_mul_f32_e32 v6, 0x42800000, v11
	v_mul_f32_e32 v4, 0x42800000, v12
	v_cvt_pk_fp8_f32 v2, v5, v6 op_sel:[0,0,1]
	v_mul_f32_e32 v5, 0x42800000, v13
	v_mov_b32_e32 v3, v7
	v_cvt_pk_fp8_f32 v3, v4, v5
	v_mul_f32_e32 v6, 0x42800000, v14
	v_mul_f32_e32 v11, 0x42800000, v15
	v_mul_f32_e32 v5, 0x42800000, v16
	v_cvt_pk_fp8_f32 v3, v6, v11 op_sel:[0,0,1]
	v_mul_f32_e32 v6, 0x42800000, v17
	v_mov_b32_e32 v4, v7
	v_cvt_pk_fp8_f32 v4, v5, v6
	v_mul_f32_e32 v11, 0x42800000, v18
	v_mul_f32_e32 v12, 0x42800000, v19
	v_mul_f32_e32 v6, 0x42800000, v20
	v_cvt_pk_fp8_f32 v4, v11, v12 op_sel:[0,0,1]
	v_mul_f32_e32 v11, 0x42800000, v21
	v_mov_b32_e32 v5, v7
	v_cvt_pk_fp8_f32 v5, v6, v11
	v_mul_f32_e32 v12, 0x42800000, v22
	v_mul_f32_e32 v13, 0x42800000, v24
	v_mul_f32_e32 v6, 0x42800000, v27
	v_cvt_pk_fp8_f32 v5, v12, v13 op_sel:[0,0,1]
	v_mul_f32_e32 v11, 0x42800000, v31
	v_mul_f32_e32 v12, 0x42800000, v35
	v_mul_f32_e32 v13, 0x42800000, v40
	ds_write_b128 v135, v[2:5]
	v_mul_f32_e32 v3, 0x42800000, v23
	v_mul_f32_e32 v4, 0x42800000, v25
	v_mov_b32_e32 v2, v7
	v_cvt_pk_fp8_f32 v2, v3, v4
	v_mul_f32_e32 v5, 0x42800000, v26
	v_mul_f32_e32 v4, 0x42800000, v28
	v_mov_b32_e32 v3, v7
	v_cvt_pk_fp8_f32 v2, v5, v6 op_sel:[0,0,1]
	v_mul_f32_e32 v5, 0x42800000, v29
	v_cvt_pk_fp8_f32 v3, v4, v5
	v_mul_f32_e32 v6, 0x42800000, v30
	v_mul_f32_e32 v5, 0x42800000, v32
	v_mov_b32_e32 v4, v7
	v_cvt_pk_fp8_f32 v3, v6, v11 op_sel:[0,0,1]
	v_mul_f32_e32 v6, 0x42800000, v33
	v_cvt_pk_fp8_f32 v4, v5, v6
	v_mul_f32_e32 v11, 0x42800000, v34
	v_mul_f32_e32 v6, 0x42800000, v36
	v_mov_b32_e32 v5, v7
	v_cvt_pk_fp8_f32 v4, v11, v12 op_sel:[0,0,1]
	v_mul_f32_e32 v11, 0x42800000, v37
	v_cvt_pk_fp8_f32 v5, v6, v11
	v_mul_f32_e32 v12, 0x42800000, v38
	v_mul_f32_e32 v6, 0x42800000, v43
	v_mul_f32_e32 v11, 0x42800000, v47
	v_cvt_pk_fp8_f32 v5, v12, v13 op_sel:[0,0,1]
	v_mul_f32_e32 v12, 0x42800000, v51
	v_mul_f32_e32 v13, 0x42800000, v56
	ds_write_b128 v135, v[2:5] offset:16
	v_mul_f32_e32 v3, 0x42800000, v39
	v_mul_f32_e32 v4, 0x42800000, v41
	v_mov_b32_e32 v2, v7
	v_cvt_pk_fp8_f32 v2, v3, v4
	v_mul_f32_e32 v5, 0x42800000, v42
	v_mul_f32_e32 v4, 0x42800000, v44
	v_mov_b32_e32 v3, v7
	v_cvt_pk_fp8_f32 v2, v5, v6 op_sel:[0,0,1]
	v_mul_f32_e32 v5, 0x42800000, v45
	v_cvt_pk_fp8_f32 v3, v4, v5
	v_mul_f32_e32 v6, 0x42800000, v46
	v_mul_f32_e32 v5, 0x42800000, v48
	v_mov_b32_e32 v4, v7
	v_cvt_pk_fp8_f32 v3, v6, v11 op_sel:[0,0,1]
	v_mul_f32_e32 v6, 0x42800000, v49
	v_cvt_pk_fp8_f32 v4, v5, v6
	v_mul_f32_e32 v11, 0x42800000, v50
	v_mul_f32_e32 v6, 0x42800000, v52
	v_mov_b32_e32 v5, v7
	v_cvt_pk_fp8_f32 v4, v11, v12 op_sel:[0,0,1]
	v_mul_f32_e32 v11, 0x42800000, v53
	v_cvt_pk_fp8_f32 v5, v6, v11
	v_mul_f32_e32 v12, 0x42800000, v54
	v_mul_f32_e32 v6, 0x42800000, v59
	v_mul_f32_e32 v11, 0x42800000, v63
	v_cvt_pk_fp8_f32 v5, v12, v13 op_sel:[0,0,1]
	v_mul_f32_e32 v12, 0x42800000, v67
	v_mul_f32_e32 v13, 0x42800000, v72
	ds_write_b128 v135, v[2:5] offset:32
	v_mul_f32_e32 v3, 0x42800000, v55
	v_mul_f32_e32 v4, 0x42800000, v57
	v_mov_b32_e32 v2, v7
	v_cvt_pk_fp8_f32 v2, v3, v4
	v_mul_f32_e32 v5, 0x42800000, v58
	v_mul_f32_e32 v4, 0x42800000, v60
	v_mov_b32_e32 v3, v7
	v_cvt_pk_fp8_f32 v2, v5, v6 op_sel:[0,0,1]
	v_mul_f32_e32 v5, 0x42800000, v61
	v_cvt_pk_fp8_f32 v3, v4, v5
	v_mul_f32_e32 v6, 0x42800000, v62
	v_mul_f32_e32 v5, 0x42800000, v64
	v_mov_b32_e32 v4, v7
	v_cvt_pk_fp8_f32 v3, v6, v11 op_sel:[0,0,1]
	v_mul_f32_e32 v6, 0x42800000, v65
	v_cvt_pk_fp8_f32 v4, v5, v6
	v_mul_f32_e32 v11, 0x42800000, v66
	v_mul_f32_e32 v6, 0x42800000, v68
	v_mov_b32_e32 v5, v7
	v_cvt_pk_fp8_f32 v4, v11, v12 op_sel:[0,0,1]
	v_mul_f32_e32 v11, 0x42800000, v69
	v_cvt_pk_fp8_f32 v5, v6, v11
	v_mul_f32_e32 v12, 0x42800000, v70
	v_mul_f32_e32 v6, 0x42800000, v75
	v_mul_f32_e32 v11, 0x42800000, v79
	v_cvt_pk_fp8_f32 v5, v12, v13 op_sel:[0,0,1]
	v_mul_f32_e32 v12, 0x42800000, v83
	v_mul_f32_e32 v13, 0x42800000, v88
	ds_write_b128 v135, v[2:5] offset:48
	v_mul_f32_e32 v3, 0x42800000, v71
	v_mul_f32_e32 v4, 0x42800000, v73
	v_mov_b32_e32 v2, v7
	v_cvt_pk_fp8_f32 v2, v3, v4
	v_mul_f32_e32 v5, 0x42800000, v74
	v_mul_f32_e32 v4, 0x42800000, v76
	v_mov_b32_e32 v3, v7
	v_cvt_pk_fp8_f32 v2, v5, v6 op_sel:[0,0,1]
	v_mul_f32_e32 v5, 0x42800000, v77
	v_cvt_pk_fp8_f32 v3, v4, v5
	v_mul_f32_e32 v6, 0x42800000, v78
	v_mul_f32_e32 v5, 0x42800000, v80
	v_mov_b32_e32 v4, v7
	v_cvt_pk_fp8_f32 v3, v6, v11 op_sel:[0,0,1]
	v_mul_f32_e32 v6, 0x42800000, v81
	v_cvt_pk_fp8_f32 v4, v5, v6
	v_mul_f32_e32 v11, 0x42800000, v82
	v_mul_f32_e32 v6, 0x42800000, v84
	v_mov_b32_e32 v5, v7
	v_cvt_pk_fp8_f32 v4, v11, v12 op_sel:[0,0,1]
	v_mul_f32_e32 v11, 0x42800000, v85
	v_cvt_pk_fp8_f32 v5, v6, v11
	v_mul_f32_e32 v12, 0x42800000, v86
	v_mul_f32_e32 v6, 0x42800000, v91
	v_mul_f32_e32 v11, 0x42800000, v95
	v_cvt_pk_fp8_f32 v5, v12, v13 op_sel:[0,0,1]
	v_mul_f32_e32 v12, 0x42800000, v99
	v_mul_f32_e32 v13, 0x42800000, v104
	ds_write_b128 v135, v[2:5] offset:64
	v_mul_f32_e32 v3, 0x42800000, v87
	v_mul_f32_e32 v4, 0x42800000, v89
	v_mov_b32_e32 v2, v7
	v_cvt_pk_fp8_f32 v2, v3, v4
	v_mul_f32_e32 v5, 0x42800000, v90
	v_mul_f32_e32 v4, 0x42800000, v92
	v_mov_b32_e32 v3, v7
	v_cvt_pk_fp8_f32 v2, v5, v6 op_sel:[0,0,1]
	v_mul_f32_e32 v5, 0x42800000, v93
	v_cvt_pk_fp8_f32 v3, v4, v5
	v_mul_f32_e32 v6, 0x42800000, v94
	v_mul_f32_e32 v5, 0x42800000, v96
	v_mov_b32_e32 v4, v7
	v_cvt_pk_fp8_f32 v3, v6, v11 op_sel:[0,0,1]
	v_mul_f32_e32 v6, 0x42800000, v97
	v_cvt_pk_fp8_f32 v4, v5, v6
	v_mul_f32_e32 v11, 0x42800000, v98
	v_mul_f32_e32 v6, 0x42800000, v100
	v_mov_b32_e32 v5, v7
	v_cvt_pk_fp8_f32 v4, v11, v12 op_sel:[0,0,1]
	v_mul_f32_e32 v11, 0x42800000, v101
	v_cvt_pk_fp8_f32 v5, v6, v11
	v_mul_f32_e32 v12, 0x42800000, v102
	v_mul_f32_e32 v6, 0x42800000, v107
	v_mul_f32_e32 v11, 0x42800000, v111
	v_cvt_pk_fp8_f32 v5, v12, v13 op_sel:[0,0,1]
	s_waitcnt vmcnt(16)
	v_mul_f32_e32 v12, 0x42800000, v120
	ds_write_b128 v135, v[2:5] offset:80
	v_mul_f32_e32 v3, 0x42800000, v103
	v_mul_f32_e32 v4, 0x42800000, v105
	v_mov_b32_e32 v2, v7
	v_cvt_pk_fp8_f32 v2, v3, v4
	v_mul_f32_e32 v5, 0x42800000, v106
	v_mul_f32_e32 v4, 0x42800000, v108
	v_mov_b32_e32 v3, v7
	v_cvt_pk_fp8_f32 v2, v5, v6 op_sel:[0,0,1]
	v_mul_f32_e32 v5, 0x42800000, v109
	v_cvt_pk_fp8_f32 v3, v4, v5
	v_mul_f32_e32 v6, 0x42800000, v110
	v_mul_f32_e32 v5, 0x42800000, v112
	v_mov_b32_e32 v4, v7
	v_cvt_pk_fp8_f32 v3, v6, v11 op_sel:[0,0,1]
	v_mul_f32_e32 v6, 0x42800000, v113
	v_cvt_pk_fp8_f32 v4, v5, v6
	v_mul_f32_e32 v11, 0x42800000, v114
	v_mul_f32_e32 v6, 0x42800000, v118
	v_mov_b32_e32 v5, v7
	v_cvt_pk_fp8_f32 v4, v11, v1 op_sel:[0,0,1]
	v_mul_f32_e32 v1, 0x42800000, v115
	v_cvt_pk_fp8_f32 v5, v1, v6
	v_mul_f32_e32 v11, 0x42800000, v119
	s_waitcnt vmcnt(15)
	v_mul_f32_e32 v1, 0x42800000, v121
	s_waitcnt vmcnt(8)
	v_mul_f32_e32 v6, 0x42800000, v128
	v_cvt_pk_fp8_f32 v5, v11, v12 op_sel:[0,0,1]
	s_waitcnt vmcnt(4)
	v_mul_f32_e32 v11, 0x42800000, v132
	s_waitcnt vmcnt(0)
	v_mul_f32_e32 v12, 0x42800000, v117
	ds_write_b128 v135, v[2:5] offset:96
	v_mul_f32_e32 v3, 0x42800000, v122
	v_mov_b32_e32 v2, v7
	v_cvt_pk_fp8_f32 v2, v1, v3
	v_mul_f32_e32 v4, 0x42800000, v123
	v_mul_f32_e32 v5, 0x42800000, v124
	v_mul_f32_e32 v1, 0x42800000, v125
	v_cvt_pk_fp8_f32 v2, v4, v5 op_sel:[0,0,1]
	v_mul_f32_e32 v4, 0x42800000, v126
	v_mov_b32_e32 v3, v7
	v_cvt_pk_fp8_f32 v3, v1, v4
	v_mul_f32_e32 v5, 0x42800000, v127
	v_mul_f32_e32 v1, 0x42800000, v129
	v_mov_b32_e32 v4, v7
	v_cvt_pk_fp8_f32 v3, v5, v6 op_sel:[0,0,1]
	v_mul_f32_e32 v5, 0x42800000, v130
	v_cvt_pk_fp8_f32 v4, v1, v5
	v_mul_f32_e32 v6, 0x42800000, v131
	v_mul_f32_e32 v1, 0x42800000, v133
	v_mov_b32_e32 v5, v7
	v_cvt_pk_fp8_f32 v4, v6, v11 op_sel:[0,0,1]
	v_mul_f32_e32 v6, 0x42800000, v134
	v_cvt_pk_fp8_f32 v5, v1, v6
	v_mul_f32_e32 v11, 0x42800000, v116
	v_add_u32_e32 v1, s9, v139
	v_cvt_pk_fp8_f32 v5, v11, v12 op_sel:[0,0,1]
	ds_write_b128 v135, v[2:5] offset:112
	v_add_u32_e32 v2, s8, v138
	v_ashrrev_i32_e32 v3, 31, v2
	v_lshlrev_b64 v[2:3], 12, v[2:3]
	v_lshl_add_u64 v[2:3], s[10:11], 0, v[2:3]
	v_lshl_add_u64 v[2:3], v[2:3], 0, s[4:5]
	v_lshl_add_u64 v[12:13], v[2:3], 0, v[8:9]
	ds_read_b128 v[2:5], v1
	v_add_co_u32_e32 v14, vcc, s28, v12
	s_nop 1
	v_addc_co_u32_e32 v15, vcc, 0, v13, vcc
	s_waitcnt lgkmcnt(0)
	global_store_dwordx4 v[12:13], v[2:5], off
	ds_read_b128 v[2:5], v1 offset:1024
	s_waitcnt lgkmcnt(0)
	global_store_dwordx4 v[14:15], v[2:5], off
	ds_read_b128 v[2:5], v1 offset:2048
	v_add_co_u32_e32 v14, vcc, s29, v12
	s_nop 1
	v_addc_co_u32_e32 v15, vcc, 0, v13, vcc
	s_waitcnt lgkmcnt(0)
	global_store_dwordx4 v[14:15], v[2:5], off
	ds_read_b128 v[2:5], v1 offset:3072
	v_add_co_u32_e32 v14, vcc, s30, v12
	s_nop 1
	v_addc_co_u32_e32 v15, vcc, 0, v13, vcc
	s_waitcnt lgkmcnt(0)
	global_store_dwordx4 v[14:15], v[2:5], off
	ds_read_b128 v[2:5], v1 offset:4096
	v_add_co_u32_e32 v14, vcc, s31, v12
	s_nop 1
	v_addc_co_u32_e32 v15, vcc, 0, v13, vcc
	s_waitcnt lgkmcnt(0)
	global_store_dwordx4 v[14:15], v[2:5], off
	ds_read_b128 v[2:5], v1 offset:5120
	v_add_co_u32_e32 v14, vcc, 0x28000, v12
	s_nop 1
	v_addc_co_u32_e32 v15, vcc, 0, v13, vcc
	s_waitcnt lgkmcnt(0)
	global_store_dwordx4 v[14:15], v[2:5], off
	ds_read_b128 v[2:5], v1 offset:6144
	v_add_co_u32_e32 v14, vcc, 0x30000, v12
	s_nop 1
	v_addc_co_u32_e32 v15, vcc, 0, v13, vcc
	s_waitcnt lgkmcnt(0)
	global_store_dwordx4 v[14:15], v[2:5], off
	ds_read_b128 v[2:5], v1 offset:7168
	v_add_co_u32_e32 v12, vcc, 0x38000, v12
	s_nop 1
	v_addc_co_u32_e32 v13, vcc, 0, v13, vcc
	s_waitcnt lgkmcnt(0)
	global_store_dwordx4 v[12:13], v[2:5], off
	s_cbranch_execnz .LBB0_12

.LBB0_22:
	s_or_b64 exec, exec, s[8:9]
	s_load_dwordx16 s[48:63], s[0:1], 0x40
	s_lshl_b32 s8, s47, 6
	v_max_i32_e32 v6, 0, v11
	s_or_b32 s9, s8, 1
	s_or_b32 s47, s8, 61
	s_waitcnt lgkmcnt(0)
	v_lshl_add_u64 v[120:121], v[6:7], 2, s[48:49]
	v_mad_i64_i32 v[4:5], s[10:11], s9, v142, v[120:121]
	s_or_b32 s9, s8, 2
	v_mad_i64_i32 v[16:17], s[10:11], s9, v142, v[120:121]
	s_or_b32 s9, s8, 3
	v_mad_i64_i32 v[2:3], s[10:11], s8, v142, v[120:121]
	v_mad_i64_i32 v[18:19], s[10:11], s9, v142, v[120:121]
	s_or_b32 s9, s8, 4
	global_load_dwordx2 v[14:15], v[2:3], off nt
	global_load_dwordx2 v[12:13], v[4:5], off nt
	s_nop 0
	global_load_dwordx2 v[4:5], v[16:17], off nt
	global_load_dwordx2 v[2:3], v[18:19], off nt
	v_mad_i64_i32 v[16:17], s[10:11], s9, v142, v[120:121]
	s_or_b32 s9, s8, 5
	v_mad_i64_i32 v[18:19], s[10:11], s9, v142, v[120:121]
	s_or_b32 s9, s8, 6
	v_mad_i64_i32 v[20:21], s[10:11], s9, v142, v[120:121]
	s_or_b32 s9, s8, 7
	v_mad_i64_i32 v[22:23], s[10:11], s9, v142, v[120:121]
	s_or_b32 s9, s8, 8
	global_load_dwordx2 v[28:29], v[16:17], off nt
	global_load_dwordx2 v[24:25], v[18:19], off nt
	s_nop 0
	global_load_dwordx2 v[20:21], v[20:21], off nt
	s_nop 0
	global_load_dwordx2 v[16:17], v[22:23], off nt
	v_mad_i64_i32 v[18:19], s[10:11], s9, v142, v[120:121]
	s_or_b32 s9, s8, 9
	v_mad_i64_i32 v[22:23], s[10:11], s9, v142, v[120:121]
	s_or_b32 s9, s8, 10
	v_mad_i64_i32 v[32:33], s[10:11], s9, v142, v[120:121]
	s_or_b32 s9, s8, 11
	v_mad_i64_i32 v[34:35], s[10:11], s9, v142, v[120:121]
	s_or_b32 s9, s8, 12
	global_load_dwordx2 v[30:31], v[18:19], off nt
	global_load_dwordx2 v[26:27], v[22:23], off nt
	s_nop 0
	global_load_dwordx2 v[22:23], v[32:33], off nt
	global_load_dwordx2 v[18:19], v[34:35], off nt
	v_mad_i64_i32 v[32:33], s[10:11], s9, v142, v[120:121]
	s_or_b32 s9, s8, 13
	v_mad_i64_i32 v[34:35], s[10:11], s9, v142, v[120:121]
	s_or_b32 s9, s8, 14
	v_mad_i64_i32 v[36:37], s[10:11], s9, v142, v[120:121]
	s_or_b32 s9, s8, 15
	v_mad_i64_i32 v[38:39], s[10:11], s9, v142, v[120:121]
	s_or_b32 s9, s8, 16
	global_load_dwordx2 v[44:45], v[32:33], off nt
	global_load_dwordx2 v[40:41], v[34:35], off nt
	s_nop 0
	global_load_dwordx2 v[36:37], v[36:37], off nt
	s_nop 0
	global_load_dwordx2 v[32:33], v[38:39], off nt
	v_mad_i64_i32 v[34:35], s[10:11], s9, v142, v[120:121]
	s_or_b32 s9, s8, 17
	v_mad_i64_i32 v[38:39], s[10:11], s9, v142, v[120:121]
	s_or_b32 s9, s8, 18
	v_mad_i64_i32 v[48:49], s[10:11], s9, v142, v[120:121]
	s_or_b32 s9, s8, 19
	v_mad_i64_i32 v[50:51], s[10:11], s9, v142, v[120:121]
	s_or_b32 s9, s8, 20
	global_load_dwordx2 v[46:47], v[34:35], off nt
	global_load_dwordx2 v[42:43], v[38:39], off nt
	s_nop 0
	global_load_dwordx2 v[38:39], v[48:49], off nt
	global_load_dwordx2 v[34:35], v[50:51], off nt
	v_mad_i64_i32 v[48:49], s[10:11], s9, v142, v[120:121]
	s_or_b32 s9, s8, 21
	v_mad_i64_i32 v[50:51], s[10:11], s9, v142, v[120:121]
	s_or_b32 s9, s8, 22
	v_mad_i64_i32 v[52:53], s[10:11], s9, v142, v[120:121]
	s_or_b32 s9, s8, 23
	v_mad_i64_i32 v[54:55], s[10:11], s9, v142, v[120:121]
	s_or_b32 s9, s8, 24
	global_load_dwordx2 v[60:61], v[48:49], off nt
	global_load_dwordx2 v[56:57], v[50:51], off nt
	s_nop 0
	global_load_dwordx2 v[52:53], v[52:53], off nt
	s_nop 0
	global_load_dwordx2 v[48:49], v[54:55], off nt
	v_mad_i64_i32 v[50:51], s[10:11], s9, v142, v[120:121]
	s_or_b32 s9, s8, 25
	v_mad_i64_i32 v[54:55], s[10:11], s9, v142, v[120:121]
	s_or_b32 s9, s8, 26
	v_mad_i64_i32 v[64:65], s[10:11], s9, v142, v[120:121]
	s_or_b32 s9, s8, 27
	v_mad_i64_i32 v[66:67], s[10:11], s9, v142, v[120:121]
	s_or_b32 s9, s8, 28
	global_load_dwordx2 v[62:63], v[50:51], off nt
	global_load_dwordx2 v[58:59], v[54:55], off nt
	s_nop 0
	global_load_dwordx2 v[54:55], v[64:65], off nt
	global_load_dwordx2 v[50:51], v[66:67], off nt
	v_mad_i64_i32 v[64:65], s[10:11], s9, v142, v[120:121]
	s_or_b32 s9, s8, 29
	v_mad_i64_i32 v[66:67], s[10:11], s9, v142, v[120:121]
	s_or_b32 s9, s8, 30
	v_mad_i64_i32 v[68:69], s[10:11], s9, v142, v[120:121]
	s_or_b32 s9, s8, 31
	v_mad_i64_i32 v[70:71], s[10:11], s9, v142, v[120:121]
	s_or_b32 s9, s8, 32
	global_load_dwordx2 v[76:77], v[64:65], off nt
	global_load_dwordx2 v[72:73], v[66:67], off nt
	s_nop 0
	global_load_dwordx2 v[68:69], v[68:69], off nt
	s_nop 0
	global_load_dwordx2 v[64:65], v[70:71], off nt
	v_mad_i64_i32 v[66:67], s[10:11], s9, v142, v[120:121]
	s_or_b32 s9, s8, 33
	v_mad_i64_i32 v[70:71], s[10:11], s9, v142, v[120:121]
	s_or_b32 s9, s8, 34
	v_mad_i64_i32 v[80:81], s[10:11], s9, v142, v[120:121]
	s_or_b32 s9, s8, 35
	v_mad_i64_i32 v[82:83], s[10:11], s9, v142, v[120:121]
	s_or_b32 s9, s8, 36
	global_load_dwordx2 v[78:79], v[66:67], off nt
	global_load_dwordx2 v[74:75], v[70:71], off nt
	s_nop 0
	global_load_dwordx2 v[70:71], v[80:81], off nt
	global_load_dwordx2 v[66:67], v[82:83], off nt
	v_mad_i64_i32 v[80:81], s[10:11], s9, v142, v[120:121]
	s_or_b32 s9, s8, 37
	v_mad_i64_i32 v[82:83], s[10:11], s9, v142, v[120:121]
	s_or_b32 s9, s8, 38
	v_mad_i64_i32 v[84:85], s[10:11], s9, v142, v[120:121]
	s_or_b32 s9, s8, 39
	v_mad_i64_i32 v[86:87], s[10:11], s9, v142, v[120:121]
	s_or_b32 s9, s8, 40
	global_load_dwordx2 v[92:93], v[80:81], off nt
	global_load_dwordx2 v[88:89], v[82:83], off nt
	s_nop 0
	global_load_dwordx2 v[84:85], v[84:85], off nt
	s_nop 0
	global_load_dwordx2 v[80:81], v[86:87], off nt
	v_mad_i64_i32 v[82:83], s[10:11], s9, v142, v[120:121]
	s_or_b32 s9, s8, 41
	v_mad_i64_i32 v[86:87], s[10:11], s9, v142, v[120:121]
	s_or_b32 s9, s8, 42
	v_mad_i64_i32 v[96:97], s[10:11], s9, v142, v[120:121]
	s_or_b32 s9, s8, 43
	v_mad_i64_i32 v[98:99], s[10:11], s9, v142, v[120:121]
	s_or_b32 s9, s8, 44
	global_load_dwordx2 v[94:95], v[82:83], off nt
	global_load_dwordx2 v[90:91], v[86:87], off nt
	s_nop 0
	global_load_dwordx2 v[86:87], v[96:97], off nt
	global_load_dwordx2 v[82:83], v[98:99], off nt
	v_mad_i64_i32 v[96:97], s[10:11], s9, v142, v[120:121]
	s_or_b32 s9, s8, 45
	v_mad_i64_i32 v[98:99], s[10:11], s9, v142, v[120:121]
	s_or_b32 s9, s8, 46
	v_mad_i64_i32 v[100:101], s[10:11], s9, v142, v[120:121]
	s_or_b32 s9, s8, 47
	v_mad_i64_i32 v[102:103], s[10:11], s9, v142, v[120:121]
	s_or_b32 s9, s8, 48
	global_load_dwordx2 v[108:109], v[96:97], off nt
	global_load_dwordx2 v[104:105], v[98:99], off nt
	s_nop 0
	global_load_dwordx2 v[100:101], v[100:101], off nt
	s_nop 0
	global_load_dwordx2 v[96:97], v[102:103], off nt
	v_mad_i64_i32 v[98:99], s[10:11], s9, v142, v[120:121]
	s_or_b32 s9, s8, 49
	v_mad_i64_i32 v[102:103], s[10:11], s9, v142, v[120:121]
	s_or_b32 s9, s8, 50
	v_mad_i64_i32 v[112:113], s[10:11], s9, v142, v[120:121]
	s_or_b32 s9, s8, 51
	v_mad_i64_i32 v[114:115], s[10:11], s9, v142, v[120:121]
	s_or_b32 s9, s8, 52
	global_load_dwordx2 v[110:111], v[98:99], off nt
	global_load_dwordx2 v[106:107], v[102:103], off nt
	s_nop 0
	global_load_dwordx2 v[102:103], v[112:113], off nt
	global_load_dwordx2 v[98:99], v[114:115], off nt
	v_mad_i64_i32 v[112:113], s[10:11], s9, v142, v[120:121]
	s_or_b32 s9, s8, 53
	v_mad_i64_i32 v[114:115], s[10:11], s9, v142, v[120:121]
	s_or_b32 s9, s8, 54
	v_mad_i64_i32 v[116:117], s[10:11], s9, v142, v[120:121]
	s_or_b32 s9, s8, 55
	v_mad_i64_i32 v[118:119], s[10:11], s9, v142, v[120:121]
	s_or_b32 s9, s8, 56
	global_load_dwordx2 v[128:129], v[112:113], off nt
	global_load_dwordx2 v[122:123], v[114:115], off nt
	s_nop 0
	global_load_dwordx2 v[116:117], v[116:117], off nt
	s_nop 0
	global_load_dwordx2 v[112:113], v[118:119], off nt
	v_mad_i64_i32 v[114:115], s[10:11], s9, v142, v[120:121]
	s_or_b32 s9, s8, 57
	v_mad_i64_i32 v[118:119], s[10:11], s9, v142, v[120:121]
	s_or_b32 s9, s8, 58
	v_mad_i64_i32 v[126:127], s[10:11], s9, v142, v[120:121]
	s_or_b32 s9, s8, 59
	v_mad_i64_i32 v[132:133], s[10:11], s9, v142, v[120:121]
	s_or_b32 s9, s8, 60
	s_or_b32 s48, s8, 62
	s_or_b32 s49, s8, 63
	global_load_dwordx2 v[130:131], v[114:115], off nt
	global_load_dwordx2 v[124:125], v[118:119], off nt
	s_nop 0
	global_load_dwordx2 v[118:119], v[126:127], off nt
	global_load_dwordx2 v[114:115], v[132:133], off nt
	v_mad_i64_i32 v[126:127], s[10:11], s9, v142, v[120:121]
	v_mad_i64_i32 v[132:133], s[10:11], s47, v142, v[120:121]
	v_mad_i64_i32 v[144:145], s[10:11], s48, v142, v[120:121]
	v_mad_i64_i32 v[120:121], s[10:11], s49, v142, v[120:121]
	global_load_dwordx2 v[134:135], v[126:127], off nt
	s_nop 0
	global_load_dwordx2 v[132:133], v[132:133], off nt
	s_nop 0
	global_load_dwordx2 v[126:127], v[144:145], off nt
	s_nop 0
	global_load_dwordx2 v[120:121], v[120:121], off nt
	v_cmp_gt_i32_e32 vcc, 0, v11
	s_ashr_i32 s9, s8, 31
	s_and_saveexec_b64 s[10:11], vcc
	s_cbranch_execz .LBB0_11
	s_waitcnt vmcnt(0)
	v_mov_b32_e32 v120, 0
	v_mov_b32_e32 v121, v120
	v_mov_b32_e32 v126, v120
	v_mov_b32_e32 v127, v120
	v_mov_b32_e32 v132, v120
	v_mov_b32_e32 v133, v120
	v_mov_b32_e32 v134, v120
	v_mov_b32_e32 v135, v120
	v_mov_b32_e32 v114, v120
	v_mov_b32_e32 v115, v120
	v_mov_b32_e32 v118, v120
	v_mov_b32_e32 v119, v120
	v_mov_b32_e32 v124, v120
	v_mov_b32_e32 v125, v120
	v_mov_b32_e32 v130, v120
	v_mov_b32_e32 v131, v120
	v_mov_b32_e32 v112, v120
	v_mov_b32_e32 v113, v120
	v_mov_b32_e32 v116, v120
	v_mov_b32_e32 v117, v120
	v_mov_b32_e32 v122, v120
	v_mov_b32_e32 v123, v120
	v_mov_b32_e32 v128, v120
	v_mov_b32_e32 v129, v120
	v_mov_b32_e32 v98, v120
	v_mov_b32_e32 v99, v120
	v_mov_b32_e32 v102, v120
	v_mov_b32_e32 v103, v120
	v_mov_b32_e32 v106, v120
	v_mov_b32_e32 v107, v120
	v_mov_b32_e32 v110, v120
	v_mov_b32_e32 v111, v120
	v_mov_b32_e32 v96, v120
	v_mov_b32_e32 v97, v120
	v_mov_b32_e32 v100, v120
	v_mov_b32_e32 v101, v120
	v_mov_b32_e32 v104, v120
	v_mov_b32_e32 v105, v120
	v_mov_b32_e32 v108, v120
	v_mov_b32_e32 v109, v120
	v_mov_b32_e32 v82, v120
	v_mov_b32_e32 v83, v120
	v_mov_b32_e32 v86, v120
	v_mov_b32_e32 v87, v120
	v_mov_b32_e32 v90, v120
	v_mov_b32_e32 v91, v120
	v_mov_b32_e32 v94, v120
	v_mov_b32_e32 v95, v120
	v_mov_b32_e32 v80, v120
	v_mov_b32_e32 v81, v120
	v_mov_b32_e32 v84, v120
	v_mov_b32_e32 v85, v120
	v_mov_b32_e32 v88, v120
	v_mov_b32_e32 v89, v120
	v_mov_b32_e32 v92, v120
	v_mov_b32_e32 v93, v120
	v_mov_b32_e32 v66, v120
	v_mov_b32_e32 v67, v120
	v_mov_b32_e32 v70, v120
	v_mov_b32_e32 v71, v120
	v_mov_b32_e32 v74, v120
	v_mov_b32_e32 v75, v120
	v_mov_b32_e32 v78, v120
	v_mov_b32_e32 v79, v120
	v_mov_b32_e32 v64, v120
	v_mov_b32_e32 v65, v120
	v_mov_b32_e32 v68, v120
	v_mov_b32_e32 v69, v120
	v_mov_b32_e32 v72, v120
	v_mov_b32_e32 v73, v120
	v_mov_b32_e32 v76, v120
	v_mov_b32_e32 v77, v120
	v_mov_b32_e32 v50, v120
	v_mov_b32_e32 v51, v120
	v_mov_b32_e32 v54, v120
	v_mov_b32_e32 v55, v120
	v_mov_b32_e32 v58, v120
	v_mov_b32_e32 v59, v120
	v_mov_b32_e32 v62, v120
	v_mov_b32_e32 v63, v120
	v_mov_b32_e32 v48, v120
	v_mov_b32_e32 v49, v120
	v_mov_b32_e32 v52, v120
	v_mov_b32_e32 v53, v120
	v_mov_b32_e32 v56, v120
	v_mov_b32_e32 v57, v120
	v_mov_b32_e32 v60, v120
	v_mov_b32_e32 v61, v120
	v_mov_b32_e32 v34, v120
	v_mov_b32_e32 v35, v120
	v_mov_b32_e32 v38, v120
	v_mov_b32_e32 v39, v120
	v_mov_b32_e32 v42, v120
	v_mov_b32_e32 v43, v120
	v_mov_b32_e32 v46, v120
	v_mov_b32_e32 v47, v120
	v_mov_b32_e32 v32, v120
	v_mov_b32_e32 v33, v120
	v_mov_b32_e32 v36, v120
	v_mov_b32_e32 v37, v120
	v_mov_b32_e32 v40, v120
	v_mov_b32_e32 v41, v120
	v_mov_b32_e32 v44, v120
	v_mov_b32_e32 v45, v120
	v_mov_b32_e32 v18, v120
	v_mov_b32_e32 v19, v120
	v_mov_b32_e32 v22, v120
	v_mov_b32_e32 v23, v120
	v_mov_b32_e32 v26, v120
	v_mov_b32_e32 v27, v120
	v_mov_b32_e32 v30, v120
	v_mov_b32_e32 v31, v120
	v_mov_b32_e32 v16, v120
	v_mov_b32_e32 v17, v120
	v_mov_b32_e32 v20, v120
	v_mov_b32_e32 v21, v120
	v_mov_b32_e32 v24, v120
	v_mov_b32_e32 v25, v120
	v_mov_b32_e32 v28, v120
	v_mov_b32_e32 v29, v120
	v_mov_b32_e32 v2, v120
	v_mov_b32_e32 v3, v120
	v_mov_b32_e32 v4, v120
	v_mov_b32_e32 v5, v120
	v_mov_b32_e32 v12, v120
	v_mov_b32_e32 v13, v120
	v_mov_b32_e32 v14, v120
	v_mov_b32_e32 v15, v120
	s_branch .LBB0_11

.LBB0_320:
	s_cmpk_gt_i32 s13, 0x247f
	s_mov_b64 s[6:7], -1
	s_cbranch_scc0 .LBB0_333
	s_cmpk_gt_u32 s13, 0x3c7f
	s_cbranch_scc0 .LBB0_330
	s_cmpk_gt_u32 s13, 0x487f
	s_cbranch_scc0 .LBB0_326
	s_and_b32 s7, s11, 0xf80
	s_and_b32 s6, s12, 0x7fffffc0
	v_add_u32_e32 v140, s7, v7
	v_readlane_b32 s8, v252, 15
	s_add_i32 s6, s6, 0xffff6f00
	v_max_i32_e32 v2, 0, v140
	v_mov_b32_e32 v3, v34
	v_readlane_b32 s9, v252, 16
	v_lshl_add_u64 v[2:3], v[2:3], 2, s[26:27]
	s_mov_b32 s15, s9
	s_lshl_b32 s14, s6, 12
	v_lshl_add_u64 v[128:129], s[14:15], 2, v[2:3]
	v_add_co_u32_e32 v2, vcc, 0x4000, v128
	v_writelane_b32 v252, s8, 15
	s_nop 0
	v_addc_co_u32_e32 v3, vcc, 0, v129, vcc
	v_add_co_u32_e32 v4, vcc, 0x8000, v128
	v_writelane_b32 v252, s9, 16
	s_nop 0
	v_addc_co_u32_e32 v5, vcc, 0, v129, vcc
	v_add_co_u32_e32 v14, vcc, 0xc000, v128
	s_mov_b32 s8, 0x10000
	s_nop 0
	v_addc_co_u32_e32 v15, vcc, 0, v129, vcc
	global_load_dwordx2 v[12:13], v[128:129], off nt
	global_load_dwordx2 v[10:11], v[2:3], off nt
	s_nop 0
	global_load_dwordx2 v[2:3], v[4:5], off nt
	s_nop 0
	global_load_dwordx2 v[4:5], v[14:15], off nt
	v_add_co_u32_e32 v14, vcc, s8, v128
	s_mov_b32 s8, 0x14000
	s_nop 0
	v_addc_co_u32_e32 v15, vcc, 0, v129, vcc
	v_add_co_u32_e32 v16, vcc, s8, v128
	s_mov_b32 s8, 0x18000
	s_nop 0
	v_addc_co_u32_e32 v17, vcc, 0, v129, vcc
	v_add_co_u32_e32 v22, vcc, s8, v128
	s_mov_b32 s8, 0x1c000
	s_nop 0
	v_addc_co_u32_e32 v23, vcc, 0, v129, vcc
	v_add_co_u32_e32 v24, vcc, s8, v128
	s_mov_b32 s8, 0x20000
	s_nop 0
	v_addc_co_u32_e32 v25, vcc, 0, v129, vcc
	global_load_dwordx2 v[20:21], v[14:15], off nt
	global_load_dwordx2 v[18:19], v[16:17], off nt
	s_nop 0
	global_load_dwordx2 v[14:15], v[22:23], off nt
	global_load_dwordx2 v[16:17], v[24:25], off nt
	v_add_co_u32_e32 v22, vcc, s8, v128
	s_mov_b32 s8, 0x24000
	s_nop 0
	v_addc_co_u32_e32 v23, vcc, 0, v129, vcc
	v_add_co_u32_e32 v24, vcc, s8, v128
	s_mov_b32 s8, 0x28000
	s_nop 0
	v_addc_co_u32_e32 v25, vcc, 0, v129, vcc
	v_add_co_u32_e32 v30, vcc, s8, v128
	s_mov_b32 s8, 0x2c000
	s_nop 0
	v_addc_co_u32_e32 v31, vcc, 0, v129, vcc
	v_add_co_u32_e32 v32, vcc, s8, v128
	s_mov_b32 s8, 0x30000
	s_nop 0
	v_addc_co_u32_e32 v33, vcc, 0, v129, vcc
	global_load_dwordx2 v[28:29], v[22:23], off nt
	global_load_dwordx2 v[26:27], v[24:25], off nt
	s_nop 0
	global_load_dwordx2 v[22:23], v[30:31], off nt
	global_load_dwordx2 v[24:25], v[32:33], off nt
	v_add_co_u32_e32 v30, vcc, s8, v128
	s_mov_b32 s8, 0x34000
	s_nop 0
	v_addc_co_u32_e32 v31, vcc, 0, v129, vcc
	v_add_co_u32_e32 v32, vcc, s8, v128
	s_mov_b32 s8, 0x38000
	s_nop 0
	v_addc_co_u32_e32 v33, vcc, 0, v129, vcc
	v_add_co_u32_e32 v40, vcc, s8, v128
	s_mov_b32 s8, 0x3c000
	s_nop 0
	v_addc_co_u32_e32 v41, vcc, 0, v129, vcc
	v_add_co_u32_e32 v42, vcc, s8, v128
	s_mov_b32 s8, 0x40000
	s_nop 0
	v_addc_co_u32_e32 v43, vcc, 0, v129, vcc
	global_load_dwordx2 v[38:39], v[30:31], off nt
	global_load_dwordx2 v[36:37], v[32:33], off nt
	s_nop 0
	global_load_dwordx2 v[30:31], v[40:41], off nt
	global_load_dwordx2 v[32:33], v[42:43], off nt
	v_add_co_u32_e32 v40, vcc, s8, v128
	s_mov_b32 s8, 0x44000
	s_nop 0
	v_addc_co_u32_e32 v41, vcc, 0, v129, vcc
	v_add_co_u32_e32 v42, vcc, s8, v128
	s_mov_b32 s8, 0x48000
	s_nop 0
	v_addc_co_u32_e32 v43, vcc, 0, v129, vcc
	v_add_co_u32_e32 v48, vcc, s8, v128
	s_mov_b32 s8, 0x4c000
	s_nop 0
	v_addc_co_u32_e32 v49, vcc, 0, v129, vcc
	v_add_co_u32_e32 v50, vcc, s8, v128
	s_mov_b32 s8, 0x50000
	s_nop 0
	v_addc_co_u32_e32 v51, vcc, 0, v129, vcc
	global_load_dwordx2 v[46:47], v[40:41], off nt
	global_load_dwordx2 v[44:45], v[42:43], off nt
	s_nop 0
	global_load_dwordx2 v[40:41], v[48:49], off nt
	global_load_dwordx2 v[42:43], v[50:51], off nt
	v_add_co_u32_e32 v48, vcc, s8, v128
	s_mov_b32 s8, 0x54000
	s_nop 0
	v_addc_co_u32_e32 v49, vcc, 0, v129, vcc
	v_add_co_u32_e32 v50, vcc, s8, v128
	s_mov_b32 s8, 0x58000
	s_nop 0
	v_addc_co_u32_e32 v51, vcc, 0, v129, vcc
	v_add_co_u32_e32 v56, vcc, s8, v128
	s_mov_b32 s8, 0x5c000
	s_nop 0
	v_addc_co_u32_e32 v57, vcc, 0, v129, vcc
	v_add_co_u32_e32 v58, vcc, s8, v128
	s_mov_b32 s8, 0x60000
	s_nop 0
	v_addc_co_u32_e32 v59, vcc, 0, v129, vcc
	global_load_dwordx2 v[54:55], v[48:49], off nt
	global_load_dwordx2 v[52:53], v[50:51], off nt
	s_nop 0
	global_load_dwordx2 v[48:49], v[56:57], off nt
	global_load_dwordx2 v[50:51], v[58:59], off nt
	v_add_co_u32_e32 v56, vcc, s8, v128
	s_mov_b32 s8, 0x64000
	s_nop 0
	v_addc_co_u32_e32 v57, vcc, 0, v129, vcc
	v_add_co_u32_e32 v58, vcc, s8, v128
	s_mov_b32 s8, 0x68000
	s_nop 0
	v_addc_co_u32_e32 v59, vcc, 0, v129, vcc
	v_add_co_u32_e32 v64, vcc, s8, v128
	s_mov_b32 s8, 0x6c000
	s_nop 0
	v_addc_co_u32_e32 v65, vcc, 0, v129, vcc
	v_add_co_u32_e32 v66, vcc, s8, v128
	s_mov_b32 s8, 0x70000
	s_nop 0
	v_addc_co_u32_e32 v67, vcc, 0, v129, vcc
	global_load_dwordx2 v[62:63], v[56:57], off nt
	global_load_dwordx2 v[60:61], v[58:59], off nt
	s_nop 0
	global_load_dwordx2 v[56:57], v[64:65], off nt
	global_load_dwordx2 v[58:59], v[66:67], off nt
	v_add_co_u32_e32 v64, vcc, s8, v128
	s_mov_b32 s8, 0x74000
	s_nop 0
	v_addc_co_u32_e32 v65, vcc, 0, v129, vcc
	v_add_co_u32_e32 v66, vcc, s8, v128
	s_mov_b32 s8, 0x78000
	s_nop 0
	v_addc_co_u32_e32 v67, vcc, 0, v129, vcc
	v_add_co_u32_e32 v72, vcc, s8, v128
	s_mov_b32 s8, 0x7c000
	s_nop 0
	v_addc_co_u32_e32 v73, vcc, 0, v129, vcc
	v_add_co_u32_e32 v74, vcc, s8, v128
	s_mov_b32 s8, 0x80000
	s_nop 0
	v_addc_co_u32_e32 v75, vcc, 0, v129, vcc
	global_load_dwordx2 v[70:71], v[64:65], off nt
	global_load_dwordx2 v[68:69], v[66:67], off nt
	s_nop 0
	global_load_dwordx2 v[64:65], v[72:73], off nt
	global_load_dwordx2 v[66:67], v[74:75], off nt
	v_add_co_u32_e32 v72, vcc, s8, v128
	s_mov_b32 s8, 0x84000
	s_nop 0
	v_addc_co_u32_e32 v73, vcc, 0, v129, vcc
	v_add_co_u32_e32 v74, vcc, s8, v128
	s_mov_b32 s8, 0x88000
	s_nop 0
	v_addc_co_u32_e32 v75, vcc, 0, v129, vcc
	v_add_co_u32_e32 v80, vcc, s8, v128
	s_mov_b32 s8, 0x8c000
	s_nop 0
	v_addc_co_u32_e32 v81, vcc, 0, v129, vcc
	v_add_co_u32_e32 v82, vcc, s8, v128
	s_mov_b32 s8, 0x90000
	s_nop 0
	v_addc_co_u32_e32 v83, vcc, 0, v129, vcc
	global_load_dwordx2 v[78:79], v[72:73], off nt
	global_load_dwordx2 v[76:77], v[74:75], off nt
	s_nop 0
	global_load_dwordx2 v[72:73], v[80:81], off nt
	global_load_dwordx2 v[74:75], v[82:83], off nt
	v_add_co_u32_e32 v80, vcc, s8, v128
	s_mov_b32 s8, 0x94000
	s_nop 0
	v_addc_co_u32_e32 v81, vcc, 0, v129, vcc
	v_add_co_u32_e32 v82, vcc, s8, v128
	s_mov_b32 s8, 0x98000
	s_nop 0
	v_addc_co_u32_e32 v83, vcc, 0, v129, vcc
	v_add_co_u32_e32 v88, vcc, s8, v128
	s_mov_b32 s8, 0x9c000
	s_nop 0
	v_addc_co_u32_e32 v89, vcc, 0, v129, vcc
	v_add_co_u32_e32 v90, vcc, s8, v128
	s_mov_b32 s8, 0xa0000
	s_nop 0
	v_addc_co_u32_e32 v91, vcc, 0, v129, vcc
	global_load_dwordx2 v[86:87], v[80:81], off nt
	global_load_dwordx2 v[84:85], v[82:83], off nt
	s_nop 0
	global_load_dwordx2 v[80:81], v[88:89], off nt
	global_load_dwordx2 v[82:83], v[90:91], off nt
	v_add_co_u32_e32 v88, vcc, s8, v128
	s_mov_b32 s8, 0xa4000
	s_nop 0
	v_addc_co_u32_e32 v89, vcc, 0, v129, vcc
	v_add_co_u32_e32 v90, vcc, s8, v128
	s_mov_b32 s8, 0xa8000
	s_nop 0
	v_addc_co_u32_e32 v91, vcc, 0, v129, vcc
	v_add_co_u32_e32 v96, vcc, s8, v128
	s_mov_b32 s8, 0xac000
	s_nop 0
	v_addc_co_u32_e32 v97, vcc, 0, v129, vcc
	v_add_co_u32_e32 v98, vcc, s8, v128
	s_mov_b32 s8, 0xb0000
	s_nop 0
	v_addc_co_u32_e32 v99, vcc, 0, v129, vcc
	global_load_dwordx2 v[94:95], v[88:89], off nt
	global_load_dwordx2 v[92:93], v[90:91], off nt
	s_nop 0
	global_load_dwordx2 v[88:89], v[96:97], off nt
	global_load_dwordx2 v[90:91], v[98:99], off nt
	v_add_co_u32_e32 v96, vcc, s8, v128
	s_mov_b32 s8, 0xb4000
	s_nop 0
	v_addc_co_u32_e32 v97, vcc, 0, v129, vcc
	v_add_co_u32_e32 v98, vcc, s8, v128
	s_mov_b32 s8, 0xb8000
	s_nop 0
	v_addc_co_u32_e32 v99, vcc, 0, v129, vcc
	v_add_co_u32_e32 v104, vcc, s8, v128
	s_mov_b32 s8, 0xbc000
	s_nop 0
	v_addc_co_u32_e32 v105, vcc, 0, v129, vcc
	v_add_co_u32_e32 v106, vcc, s8, v128
	s_mov_b32 s8, 0xc0000
	s_nop 0
	v_addc_co_u32_e32 v107, vcc, 0, v129, vcc
	global_load_dwordx2 v[102:103], v[96:97], off nt
	global_load_dwordx2 v[100:101], v[98:99], off nt
	s_nop 0
	global_load_dwordx2 v[96:97], v[104:105], off nt
	global_load_dwordx2 v[98:99], v[106:107], off nt
	v_add_co_u32_e32 v104, vcc, s8, v128
	s_mov_b32 s8, 0xc4000
	s_nop 0
	v_addc_co_u32_e32 v105, vcc, 0, v129, vcc
	v_add_co_u32_e32 v106, vcc, s8, v128
	s_mov_b32 s8, 0xc8000
	s_nop 0
	v_addc_co_u32_e32 v107, vcc, 0, v129, vcc
	v_add_co_u32_e32 v112, vcc, s8, v128
	s_mov_b32 s8, 0xcc000
	s_nop 0
	v_addc_co_u32_e32 v113, vcc, 0, v129, vcc
	v_add_co_u32_e32 v114, vcc, s8, v128
	s_mov_b32 s8, 0xd0000
	s_nop 0
	v_addc_co_u32_e32 v115, vcc, 0, v129, vcc
	global_load_dwordx2 v[110:111], v[104:105], off nt
	global_load_dwordx2 v[108:109], v[106:107], off nt
	s_nop 0
	global_load_dwordx2 v[104:105], v[112:113], off nt
	global_load_dwordx2 v[106:107], v[114:115], off nt
	v_add_co_u32_e32 v112, vcc, s8, v128
	s_mov_b32 s8, 0xd4000
	s_nop 0
	v_addc_co_u32_e32 v113, vcc, 0, v129, vcc
	v_add_co_u32_e32 v114, vcc, s8, v128
	s_mov_b32 s8, 0xd8000
	s_nop 0
	v_addc_co_u32_e32 v115, vcc, 0, v129, vcc
	v_add_co_u32_e32 v120, vcc, s8, v128
	s_mov_b32 s8, 0xdc000
	s_nop 0
	v_addc_co_u32_e32 v121, vcc, 0, v129, vcc
	v_add_co_u32_e32 v122, vcc, s8, v128
	s_mov_b32 s8, 0xe0000
	s_nop 0
	v_addc_co_u32_e32 v123, vcc, 0, v129, vcc
	global_load_dwordx2 v[118:119], v[112:113], off nt
	global_load_dwordx2 v[116:117], v[114:115], off nt
	s_nop 0
	global_load_dwordx2 v[112:113], v[120:121], off nt
	global_load_dwordx2 v[114:115], v[122:123], off nt
	v_add_co_u32_e32 v120, vcc, s8, v128
	s_mov_b32 s8, 0xe4000
	s_nop 0
	v_addc_co_u32_e32 v121, vcc, 0, v129, vcc
	v_add_co_u32_e32 v122, vcc, s8, v128
	s_mov_b32 s8, 0xe8000
	s_nop 0
	v_addc_co_u32_e32 v123, vcc, 0, v129, vcc
	v_add_co_u32_e32 v130, vcc, s8, v128
	s_mov_b32 s8, 0xec000
	s_nop 0
	v_addc_co_u32_e32 v131, vcc, 0, v129, vcc
	v_add_co_u32_e32 v132, vcc, s8, v128
	s_mov_b32 s8, 0xf0000
	s_nop 0
	v_addc_co_u32_e32 v133, vcc, 0, v129, vcc
	global_load_dwordx2 v[126:127], v[120:121], off nt
	global_load_dwordx2 v[124:125], v[122:123], off nt
	s_nop 0
	global_load_dwordx2 v[120:121], v[130:131], off nt
	global_load_dwordx2 v[122:123], v[132:133], off nt
	v_add_co_u32_e32 v130, vcc, s8, v128
	s_mov_b32 s8, 0xf4000
	s_nop 0
	v_addc_co_u32_e32 v131, vcc, 0, v129, vcc
	v_add_co_u32_e32 v132, vcc, s8, v128
	s_mov_b32 s8, 0xf8000
	s_nop 0
	v_addc_co_u32_e32 v133, vcc, 0, v129, vcc
	v_add_co_u32_e32 v142, vcc, s8, v128
	s_mov_b32 s8, 0xfc000
	s_nop 0
	v_addc_co_u32_e32 v143, vcc, 0, v129, vcc
	v_add_co_u32_e32 v144, vcc, s8, v128
	s_nop 1
	v_addc_co_u32_e32 v145, vcc, 0, v129, vcc
	global_load_dwordx2 v[134:135], v[130:131], off nt
	s_nop 0
	global_load_dwordx2 v[132:133], v[132:133], off nt
	s_nop 0
	global_load_dwordx2 v[128:129], v[142:143], off nt
	global_load_dwordx2 v[130:131], v[144:145], off nt
	v_cmp_gt_i32_e32 vcc, 0, v140
	s_and_saveexec_b64 s[8:9], vcc
	s_cbranch_execz .LBB0_325
	s_waitcnt vmcnt(0)
	v_mov_b32_e32 v130, 0
	v_mov_b32_e32 v131, v130
	v_mov_b32_e32 v128, v130
	v_mov_b32_e32 v129, v130
	v_mov_b32_e32 v132, v130
	v_mov_b32_e32 v133, v130
	v_mov_b32_e32 v134, v130
	v_mov_b32_e32 v135, v130
	v_mov_b32_e32 v122, v130
	v_mov_b32_e32 v123, v130
	v_mov_b32_e32 v120, v130
	v_mov_b32_e32 v121, v130
	v_mov_b32_e32 v124, v130
	v_mov_b32_e32 v125, v130
	v_mov_b32_e32 v126, v130
	v_mov_b32_e32 v127, v130
	v_mov_b32_e32 v114, v130
	v_mov_b32_e32 v115, v130
	v_mov_b32_e32 v112, v130
	v_mov_b32_e32 v113, v130
	v_mov_b32_e32 v116, v130
	v_mov_b32_e32 v117, v130
	v_mov_b32_e32 v118, v130
	v_mov_b32_e32 v119, v130
	v_mov_b32_e32 v106, v130
	v_mov_b32_e32 v107, v130
	v_mov_b32_e32 v104, v130
	v_mov_b32_e32 v105, v130
	v_mov_b32_e32 v108, v130
	v_mov_b32_e32 v109, v130
	v_mov_b32_e32 v110, v130
	v_mov_b32_e32 v111, v130
	v_mov_b32_e32 v98, v130
	v_mov_b32_e32 v99, v130
	v_mov_b32_e32 v96, v130
	v_mov_b32_e32 v97, v130
	v_mov_b32_e32 v100, v130
	v_mov_b32_e32 v101, v130
	v_mov_b32_e32 v102, v130
	v_mov_b32_e32 v103, v130
	v_mov_b32_e32 v90, v130
	v_mov_b32_e32 v91, v130
	v_mov_b32_e32 v88, v130
	v_mov_b32_e32 v89, v130
	v_mov_b32_e32 v92, v130
	v_mov_b32_e32 v93, v130
	v_mov_b32_e32 v94, v130
	v_mov_b32_e32 v95, v130
	v_mov_b32_e32 v82, v130
	v_mov_b32_e32 v83, v130
	v_mov_b32_e32 v80, v130
	v_mov_b32_e32 v81, v130
	v_mov_b32_e32 v84, v130
	v_mov_b32_e32 v85, v130
	v_mov_b32_e32 v86, v130
	v_mov_b32_e32 v87, v130
	v_mov_b32_e32 v74, v130
	v_mov_b32_e32 v75, v130
	v_mov_b32_e32 v72, v130
	v_mov_b32_e32 v73, v130
	v_mov_b32_e32 v76, v130
	v_mov_b32_e32 v77, v130
	v_mov_b32_e32 v78, v130
	v_mov_b32_e32 v79, v130
	v_mov_b32_e32 v66, v130
	v_mov_b32_e32 v67, v130
	v_mov_b32_e32 v64, v130
	v_mov_b32_e32 v65, v130
	v_mov_b32_e32 v68, v130
	v_mov_b32_e32 v69, v130
	v_mov_b32_e32 v70, v130
	v_mov_b32_e32 v71, v130
	v_mov_b32_e32 v58, v130
	v_mov_b32_e32 v59, v130
	v_mov_b32_e32 v56, v130
	v_mov_b32_e32 v57, v130
	v_mov_b32_e32 v60, v130
	v_mov_b32_e32 v61, v130
	v_mov_b32_e32 v62, v130
	v_mov_b32_e32 v63, v130
	v_mov_b32_e32 v50, v130
	v_mov_b32_e32 v51, v130
	v_mov_b32_e32 v48, v130
	v_mov_b32_e32 v49, v130
	v_mov_b32_e32 v52, v130
	v_mov_b32_e32 v53, v130
	v_mov_b32_e32 v54, v130
	v_mov_b32_e32 v55, v130
	v_mov_b32_e32 v42, v130
	v_mov_b32_e32 v43, v130
	v_mov_b32_e32 v40, v130
	v_mov_b32_e32 v41, v130
	v_mov_b32_e32 v44, v130
	v_mov_b32_e32 v45, v130
	v_mov_b32_e32 v46, v130
	v_mov_b32_e32 v47, v130
	v_mov_b32_e32 v32, v130
	v_mov_b32_e32 v33, v130
	v_mov_b32_e32 v30, v130
	v_mov_b32_e32 v31, v130
	v_mov_b32_e32 v36, v130
	v_mov_b32_e32 v37, v130
	v_mov_b32_e32 v38, v130
	v_mov_b32_e32 v39, v130
	v_mov_b32_e32 v24, v130
	v_mov_b32_e32 v25, v130
	v_mov_b32_e32 v22, v130
	v_mov_b32_e32 v23, v130
	v_mov_b32_e32 v26, v130
	v_mov_b32_e32 v27, v130
	v_mov_b32_e32 v28, v130
	v_mov_b32_e32 v29, v130
	v_mov_b32_e32 v16, v130
	v_mov_b32_e32 v17, v130
	v_mov_b32_e32 v14, v130
	v_mov_b32_e32 v15, v130
	v_mov_b32_e32 v18, v130
	v_mov_b32_e32 v19, v130
	v_mov_b32_e32 v20, v130
	v_mov_b32_e32 v21, v130
	v_mov_b32_e32 v4, v130
	v_mov_b32_e32 v5, v130
	v_mov_b32_e32 v2, v130
	v_mov_b32_e32 v3, v130
	v_mov_b32_e32 v10, v130
	v_mov_b32_e32 v11, v130
	v_mov_b32_e32 v12, v130
	v_mov_b32_e32 v13, v130

.LBB0_326:
	s_and_b64 vcc, exec, s[6:7]
	s_cbranch_vccz .LBB0_342
	s_add_i32 s6, s13, 0xffffc380
	s_lshr_b32 s8, s6, 10
	s_add_u32 s6, s10, s8
	s_addc_u32 s7, 0, 0
	v_readlane_b32 s40, v248, 52
	s_lshl_b64 s[6:7], s[6:7], 25
	v_readlane_b32 s50, v248, 62
	v_readlane_b32 s51, v248, 63
	s_add_u32 s6, s50, s6
	s_addc_u32 s7, s51, s7
	s_and_b32 s14, s11, 0xf80
	v_add_u32_e32 v140, s14, v7
	s_add_i32 s9, s12, 0xffff8700
	v_max_i32_e32 v2, 0, v140
	v_mov_b32_e32 v3, v34
	s_and_b32 s9, s9, 0x7c0
	v_lshl_add_u64 v[2:3], v[2:3], 2, s[6:7]
	v_readlane_b32 s6, v252, 15
	v_readlane_b32 s7, v252, 16
	s_lshl_b32 s6, s9, 14
	s_mov_b32 s19, s7
	v_lshl_add_u64 v[128:129], v[2:3], 0, s[6:7]
	s_movk_i32 s6, 0x4000
	v_add_co_u32_e32 v2, vcc, s6, v128
	s_mov_b32 s6, 0x8000
	s_nop 0
	v_addc_co_u32_e32 v3, vcc, 0, v129, vcc
	v_add_co_u32_e32 v4, vcc, s6, v128
	s_mov_b32 s6, 0xc000
	s_nop 0
	v_addc_co_u32_e32 v5, vcc, 0, v129, vcc
	v_add_co_u32_e32 v14, vcc, s6, v128
	s_mov_b32 s6, 0x10000
	s_nop 0
	v_addc_co_u32_e32 v15, vcc, 0, v129, vcc
	global_load_dwordx2 v[12:13], v[128:129], off nt
	global_load_dwordx2 v[10:11], v[2:3], off nt
	s_nop 0
	global_load_dwordx2 v[4:5], v[4:5], off nt
	s_nop 0
	global_load_dwordx2 v[2:3], v[14:15], off nt
	v_add_co_u32_e32 v14, vcc, s6, v128
	s_mov_b32 s6, 0x14000
	s_nop 0
	v_addc_co_u32_e32 v15, vcc, 0, v129, vcc
	v_add_co_u32_e32 v16, vcc, s6, v128
	s_mov_b32 s6, 0x18000
	s_nop 0
	v_addc_co_u32_e32 v17, vcc, 0, v129, vcc
	v_add_co_u32_e32 v22, vcc, s6, v128
	s_mov_b32 s6, 0x1c000
	s_nop 0
	v_addc_co_u32_e32 v23, vcc, 0, v129, vcc
	v_add_co_u32_e32 v24, vcc, s6, v128
	s_mov_b32 s6, 0x20000
	s_nop 0
	v_addc_co_u32_e32 v25, vcc, 0, v129, vcc
	global_load_dwordx2 v[20:21], v[14:15], off nt
	global_load_dwordx2 v[18:19], v[16:17], off nt
	s_nop 0
	global_load_dwordx2 v[16:17], v[22:23], off nt
	global_load_dwordx2 v[14:15], v[24:25], off nt
	v_add_co_u32_e32 v22, vcc, s6, v128
	s_mov_b32 s6, 0x24000
	s_nop 0
	v_addc_co_u32_e32 v23, vcc, 0, v129, vcc
	v_add_co_u32_e32 v24, vcc, s6, v128
	s_mov_b32 s6, 0x28000
	s_nop 0
	v_addc_co_u32_e32 v25, vcc, 0, v129, vcc
	v_add_co_u32_e32 v30, vcc, s6, v128
	s_mov_b32 s6, 0x2c000
	s_nop 0
	v_addc_co_u32_e32 v31, vcc, 0, v129, vcc
	v_add_co_u32_e32 v32, vcc, s6, v128
	s_mov_b32 s6, 0x30000
	s_nop 0
	v_addc_co_u32_e32 v33, vcc, 0, v129, vcc
	global_load_dwordx2 v[28:29], v[22:23], off nt
	global_load_dwordx2 v[26:27], v[24:25], off nt
	s_nop 0
	global_load_dwordx2 v[24:25], v[30:31], off nt
	global_load_dwordx2 v[22:23], v[32:33], off nt
	v_add_co_u32_e32 v30, vcc, s6, v128
	s_mov_b32 s6, 0x34000
	s_nop 0
	v_addc_co_u32_e32 v31, vcc, 0, v129, vcc
	v_add_co_u32_e32 v32, vcc, s6, v128
	s_mov_b32 s6, 0x38000
	s_nop 0
	v_addc_co_u32_e32 v33, vcc, 0, v129, vcc
	v_add_co_u32_e32 v40, vcc, s6, v128
	s_mov_b32 s6, 0x3c000
	s_nop 0
	v_addc_co_u32_e32 v41, vcc, 0, v129, vcc
	v_add_co_u32_e32 v42, vcc, s6, v128
	s_mov_b32 s6, 0x40000
	s_nop 0
	v_addc_co_u32_e32 v43, vcc, 0, v129, vcc
	global_load_dwordx2 v[38:39], v[30:31], off nt
	global_load_dwordx2 v[36:37], v[32:33], off nt
	s_nop 0
	global_load_dwordx2 v[32:33], v[40:41], off nt
	global_load_dwordx2 v[30:31], v[42:43], off nt
	v_add_co_u32_e32 v40, vcc, s6, v128
	s_mov_b32 s6, 0x44000
	s_nop 0
	v_addc_co_u32_e32 v41, vcc, 0, v129, vcc
	v_add_co_u32_e32 v42, vcc, s6, v128
	s_mov_b32 s6, 0x48000
	s_nop 0
	v_addc_co_u32_e32 v43, vcc, 0, v129, vcc
	v_add_co_u32_e32 v48, vcc, s6, v128
	s_mov_b32 s6, 0x4c000
	s_nop 0
	v_addc_co_u32_e32 v49, vcc, 0, v129, vcc
	v_add_co_u32_e32 v50, vcc, s6, v128
	s_mov_b32 s6, 0x50000
	s_nop 0
	v_addc_co_u32_e32 v51, vcc, 0, v129, vcc
	global_load_dwordx2 v[46:47], v[40:41], off nt
	global_load_dwordx2 v[44:45], v[42:43], off nt
	s_nop 0
	global_load_dwordx2 v[42:43], v[48:49], off nt
	global_load_dwordx2 v[40:41], v[50:51], off nt
	v_add_co_u32_e32 v48, vcc, s6, v128
	s_mov_b32 s6, 0x54000
	s_nop 0
	v_addc_co_u32_e32 v49, vcc, 0, v129, vcc
	v_add_co_u32_e32 v50, vcc, s6, v128
	s_mov_b32 s6, 0x58000
	s_nop 0
	v_addc_co_u32_e32 v51, vcc, 0, v129, vcc
	v_add_co_u32_e32 v56, vcc, s6, v128
	s_mov_b32 s6, 0x5c000
	s_nop 0
	v_addc_co_u32_e32 v57, vcc, 0, v129, vcc
	v_add_co_u32_e32 v58, vcc, s6, v128
	s_mov_b32 s6, 0x60000
	s_nop 0
	v_addc_co_u32_e32 v59, vcc, 0, v129, vcc
	global_load_dwordx2 v[54:55], v[48:49], off nt
	global_load_dwordx2 v[52:53], v[50:51], off nt
	s_nop 0
	global_load_dwordx2 v[50:51], v[56:57], off nt
	global_load_dwordx2 v[48:49], v[58:59], off nt
	v_add_co_u32_e32 v56, vcc, s6, v128
	s_mov_b32 s6, 0x64000
	s_nop 0
	v_addc_co_u32_e32 v57, vcc, 0, v129, vcc
	v_add_co_u32_e32 v58, vcc, s6, v128
	s_mov_b32 s6, 0x68000
	s_nop 0
	v_addc_co_u32_e32 v59, vcc, 0, v129, vcc
	v_add_co_u32_e32 v64, vcc, s6, v128
	s_mov_b32 s6, 0x6c000
	s_nop 0
	v_addc_co_u32_e32 v65, vcc, 0, v129, vcc
	v_add_co_u32_e32 v66, vcc, s6, v128
	s_mov_b32 s6, 0x70000
	s_nop 0
	v_addc_co_u32_e32 v67, vcc, 0, v129, vcc
	global_load_dwordx2 v[62:63], v[56:57], off nt
	global_load_dwordx2 v[60:61], v[58:59], off nt
	s_nop 0
	global_load_dwordx2 v[58:59], v[64:65], off nt
	global_load_dwordx2 v[56:57], v[66:67], off nt
	v_add_co_u32_e32 v64, vcc, s6, v128
	s_mov_b32 s6, 0x74000
	s_nop 0
	v_addc_co_u32_e32 v65, vcc, 0, v129, vcc
	v_add_co_u32_e32 v66, vcc, s6, v128
	s_mov_b32 s6, 0x78000
	s_nop 0
	v_addc_co_u32_e32 v67, vcc, 0, v129, vcc
	v_add_co_u32_e32 v72, vcc, s6, v128
	s_mov_b32 s6, 0x7c000
	s_nop 0
	v_addc_co_u32_e32 v73, vcc, 0, v129, vcc
	v_add_co_u32_e32 v74, vcc, s6, v128
	s_mov_b32 s6, 0x80000
	s_nop 0
	v_addc_co_u32_e32 v75, vcc, 0, v129, vcc
	global_load_dwordx2 v[70:71], v[64:65], off nt
	global_load_dwordx2 v[68:69], v[66:67], off nt
	s_nop 0
	global_load_dwordx2 v[66:67], v[72:73], off nt
	global_load_dwordx2 v[64:65], v[74:75], off nt
	v_add_co_u32_e32 v72, vcc, s6, v128
	s_mov_b32 s6, 0x84000
	s_nop 0
	v_addc_co_u32_e32 v73, vcc, 0, v129, vcc
	v_add_co_u32_e32 v74, vcc, s6, v128
	s_mov_b32 s6, 0x88000
	s_nop 0
	v_addc_co_u32_e32 v75, vcc, 0, v129, vcc
	v_add_co_u32_e32 v80, vcc, s6, v128
	s_mov_b32 s6, 0x8c000
	s_nop 0
	v_addc_co_u32_e32 v81, vcc, 0, v129, vcc
	v_add_co_u32_e32 v82, vcc, s6, v128
	s_mov_b32 s6, 0x90000
	s_nop 0
	v_addc_co_u32_e32 v83, vcc, 0, v129, vcc
	global_load_dwordx2 v[78:79], v[72:73], off nt
	global_load_dwordx2 v[76:77], v[74:75], off nt
	s_nop 0
	global_load_dwordx2 v[74:75], v[80:81], off nt
	global_load_dwordx2 v[72:73], v[82:83], off nt
	v_add_co_u32_e32 v80, vcc, s6, v128
	s_mov_b32 s6, 0x94000
	s_nop 0
	v_addc_co_u32_e32 v81, vcc, 0, v129, vcc
	v_add_co_u32_e32 v82, vcc, s6, v128
	s_mov_b32 s6, 0x98000
	s_nop 0
	v_addc_co_u32_e32 v83, vcc, 0, v129, vcc
	v_add_co_u32_e32 v88, vcc, s6, v128
	s_mov_b32 s6, 0x9c000
	s_nop 0
	v_addc_co_u32_e32 v89, vcc, 0, v129, vcc
	v_add_co_u32_e32 v90, vcc, s6, v128
	s_mov_b32 s6, 0xa0000
	s_nop 0
	v_addc_co_u32_e32 v91, vcc, 0, v129, vcc
	global_load_dwordx2 v[86:87], v[80:81], off nt
	global_load_dwordx2 v[84:85], v[82:83], off nt
	s_nop 0
	global_load_dwordx2 v[82:83], v[88:89], off nt
	global_load_dwordx2 v[80:81], v[90:91], off nt
	v_add_co_u32_e32 v88, vcc, s6, v128
	s_mov_b32 s6, 0xa4000
	s_nop 0
	v_addc_co_u32_e32 v89, vcc, 0, v129, vcc
	v_add_co_u32_e32 v90, vcc, s6, v128
	s_mov_b32 s6, 0xa8000
	s_nop 0
	v_addc_co_u32_e32 v91, vcc, 0, v129, vcc
	v_add_co_u32_e32 v96, vcc, s6, v128
	s_mov_b32 s6, 0xac000
	s_nop 0
	v_addc_co_u32_e32 v97, vcc, 0, v129, vcc
	v_add_co_u32_e32 v98, vcc, s6, v128
	s_mov_b32 s6, 0xb0000
	s_nop 0
	v_addc_co_u32_e32 v99, vcc, 0, v129, vcc
	global_load_dwordx2 v[94:95], v[88:89], off nt
	global_load_dwordx2 v[92:93], v[90:91], off nt
	s_nop 0
	global_load_dwordx2 v[90:91], v[96:97], off nt
	global_load_dwordx2 v[88:89], v[98:99], off nt
	v_add_co_u32_e32 v96, vcc, s6, v128
	s_mov_b32 s6, 0xb4000
	s_nop 0
	v_addc_co_u32_e32 v97, vcc, 0, v129, vcc
	v_add_co_u32_e32 v98, vcc, s6, v128
	s_mov_b32 s6, 0xb8000
	s_nop 0
	v_addc_co_u32_e32 v99, vcc, 0, v129, vcc
	v_add_co_u32_e32 v104, vcc, s6, v128
	s_mov_b32 s6, 0xbc000
	s_nop 0
	v_addc_co_u32_e32 v105, vcc, 0, v129, vcc
	v_add_co_u32_e32 v106, vcc, s6, v128
	s_mov_b32 s6, 0xc0000
	s_nop 0
	v_addc_co_u32_e32 v107, vcc, 0, v129, vcc
	global_load_dwordx2 v[102:103], v[96:97], off nt
	global_load_dwordx2 v[100:101], v[98:99], off nt
	s_nop 0
	global_load_dwordx2 v[98:99], v[104:105], off nt
	global_load_dwordx2 v[96:97], v[106:107], off nt
	v_add_co_u32_e32 v104, vcc, s6, v128
	s_mov_b32 s6, 0xc4000
	s_nop 0
	v_addc_co_u32_e32 v105, vcc, 0, v129, vcc
	v_add_co_u32_e32 v106, vcc, s6, v128
	s_mov_b32 s6, 0xc8000
	s_nop 0
	v_addc_co_u32_e32 v107, vcc, 0, v129, vcc
	v_add_co_u32_e32 v112, vcc, s6, v128
	s_mov_b32 s6, 0xcc000
	s_nop 0
	v_addc_co_u32_e32 v113, vcc, 0, v129, vcc
	v_add_co_u32_e32 v114, vcc, s6, v128
	s_mov_b32 s6, 0xd0000
	s_nop 0
	v_addc_co_u32_e32 v115, vcc, 0, v129, vcc
	global_load_dwordx2 v[110:111], v[104:105], off nt
	global_load_dwordx2 v[108:109], v[106:107], off nt
	s_nop 0
	global_load_dwordx2 v[106:107], v[112:113], off nt
	global_load_dwordx2 v[104:105], v[114:115], off nt
	v_add_co_u32_e32 v112, vcc, s6, v128
	s_mov_b32 s6, 0xd4000
	s_nop 0
	v_addc_co_u32_e32 v113, vcc, 0, v129, vcc
	v_add_co_u32_e32 v114, vcc, s6, v128
	s_mov_b32 s6, 0xd8000
	s_nop 0
	v_addc_co_u32_e32 v115, vcc, 0, v129, vcc
	v_add_co_u32_e32 v120, vcc, s6, v128
	s_mov_b32 s6, 0xdc000
	s_nop 0
	v_addc_co_u32_e32 v121, vcc, 0, v129, vcc
	v_add_co_u32_e32 v122, vcc, s6, v128
	s_mov_b32 s6, 0xe0000
	s_nop 0
	v_addc_co_u32_e32 v123, vcc, 0, v129, vcc
	global_load_dwordx2 v[118:119], v[112:113], off nt
	global_load_dwordx2 v[116:117], v[114:115], off nt
	s_nop 0
	global_load_dwordx2 v[114:115], v[120:121], off nt
	global_load_dwordx2 v[112:113], v[122:123], off nt
	v_add_co_u32_e32 v120, vcc, s6, v128
	s_mov_b32 s6, 0xe4000
	s_nop 0
	v_addc_co_u32_e32 v121, vcc, 0, v129, vcc
	v_add_co_u32_e32 v122, vcc, s6, v128
	s_mov_b32 s6, 0xe8000
	s_nop 0
	v_addc_co_u32_e32 v123, vcc, 0, v129, vcc
	v_add_co_u32_e32 v130, vcc, s6, v128
	s_mov_b32 s6, 0xec000
	s_nop 0
	v_addc_co_u32_e32 v131, vcc, 0, v129, vcc
	v_add_co_u32_e32 v132, vcc, s6, v128
	s_mov_b32 s6, 0xf0000
	s_nop 0
	v_addc_co_u32_e32 v133, vcc, 0, v129, vcc
	global_load_dwordx2 v[126:127], v[120:121], off nt
	global_load_dwordx2 v[124:125], v[122:123], off nt
	s_nop 0
	global_load_dwordx2 v[122:123], v[130:131], off nt
	global_load_dwordx2 v[120:121], v[132:133], off nt
	v_add_co_u32_e32 v130, vcc, s6, v128
	s_mov_b32 s6, 0xf4000
	s_nop 0
	v_addc_co_u32_e32 v131, vcc, 0, v129, vcc
	v_add_co_u32_e32 v132, vcc, s6, v128
	s_mov_b32 s6, 0xf8000
	s_nop 0
	v_addc_co_u32_e32 v133, vcc, 0, v129, vcc
	v_add_co_u32_e32 v142, vcc, s6, v128
	s_mov_b32 s6, 0xfc000
	s_nop 0
	v_addc_co_u32_e32 v143, vcc, 0, v129, vcc
	v_add_co_u32_e32 v144, vcc, s6, v128
	v_readlane_b32 s41, v248, 53
	s_nop 0
	v_addc_co_u32_e32 v145, vcc, 0, v129, vcc
	global_load_dwordx2 v[134:135], v[130:131], off nt
	s_nop 0
	global_load_dwordx2 v[132:133], v[132:133], off nt
	s_nop 0
	global_load_dwordx2 v[128:129], v[142:143], off nt
	global_load_dwordx2 v[130:131], v[144:145], off nt
	v_cmp_gt_i32_e32 vcc, 0, v140
	v_readlane_b32 s42, v248, 54
	v_readlane_b32 s43, v248, 55
	v_readlane_b32 s44, v248, 56
	v_readlane_b32 s45, v248, 57
	v_readlane_b32 s46, v248, 58
	v_readlane_b32 s47, v248, 59
	v_readlane_b32 s48, v248, 60
	v_readlane_b32 s49, v248, 61
	v_readlane_b32 s52, v249, 0
	v_readlane_b32 s53, v249, 1
	v_readlane_b32 s54, v249, 2
	v_readlane_b32 s55, v249, 3
	s_and_saveexec_b64 s[6:7], vcc
	s_cbranch_execz .LBB0_329
	s_waitcnt vmcnt(0)
	v_mov_b32_e32 v130, 0
	v_mov_b32_e32 v131, v130
	v_mov_b32_e32 v128, v130
	v_mov_b32_e32 v129, v130
	v_mov_b32_e32 v132, v130
	v_mov_b32_e32 v133, v130
	v_mov_b32_e32 v134, v130
	v_mov_b32_e32 v135, v130
	v_mov_b32_e32 v120, v130
	v_mov_b32_e32 v121, v130
	v_mov_b32_e32 v122, v130
	v_mov_b32_e32 v123, v130
	v_mov_b32_e32 v124, v130
	v_mov_b32_e32 v125, v130
	v_mov_b32_e32 v126, v130
	v_mov_b32_e32 v127, v130
	v_mov_b32_e32 v112, v130
	v_mov_b32_e32 v113, v130
	v_mov_b32_e32 v114, v130
	v_mov_b32_e32 v115, v130
	v_mov_b32_e32 v116, v130
	v_mov_b32_e32 v117, v130
	v_mov_b32_e32 v118, v130
	v_mov_b32_e32 v119, v130
	v_mov_b32_e32 v104, v130
	v_mov_b32_e32 v105, v130
	v_mov_b32_e32 v106, v130
	v_mov_b32_e32 v107, v130
	v_mov_b32_e32 v108, v130
	v_mov_b32_e32 v109, v130
	v_mov_b32_e32 v110, v130
	v_mov_b32_e32 v111, v130
	v_mov_b32_e32 v96, v130
	v_mov_b32_e32 v97, v130
	v_mov_b32_e32 v98, v130
	v_mov_b32_e32 v99, v130
	v_mov_b32_e32 v100, v130
	v_mov_b32_e32 v101, v130
	v_mov_b32_e32 v102, v130
	v_mov_b32_e32 v103, v130
	v_mov_b32_e32 v88, v130
	v_mov_b32_e32 v89, v130
	v_mov_b32_e32 v90, v130
	v_mov_b32_e32 v91, v130
	v_mov_b32_e32 v92, v130
	v_mov_b32_e32 v93, v130
	v_mov_b32_e32 v94, v130
	v_mov_b32_e32 v95, v130
	v_mov_b32_e32 v80, v130
	v_mov_b32_e32 v81, v130
	v_mov_b32_e32 v82, v130
	v_mov_b32_e32 v83, v130
	v_mov_b32_e32 v84, v130
	v_mov_b32_e32 v85, v130
	v_mov_b32_e32 v86, v130
	v_mov_b32_e32 v87, v130
	v_mov_b32_e32 v72, v130
	v_mov_b32_e32 v73, v130
	v_mov_b32_e32 v74, v130
	v_mov_b32_e32 v75, v130
	v_mov_b32_e32 v76, v130
	v_mov_b32_e32 v77, v130
	v_mov_b32_e32 v78, v130
	v_mov_b32_e32 v79, v130
	v_mov_b32_e32 v64, v130
	v_mov_b32_e32 v65, v130
	v_mov_b32_e32 v66, v130
	v_mov_b32_e32 v67, v130
	v_mov_b32_e32 v68, v130
	v_mov_b32_e32 v69, v130
	v_mov_b32_e32 v70, v130
	v_mov_b32_e32 v71, v130
	v_mov_b32_e32 v56, v130
	v_mov_b32_e32 v57, v130
	v_mov_b32_e32 v58, v130
	v_mov_b32_e32 v59, v130
	v_mov_b32_e32 v60, v130
	v_mov_b32_e32 v61, v130
	v_mov_b32_e32 v62, v130
	v_mov_b32_e32 v63, v130
	v_mov_b32_e32 v48, v130
	v_mov_b32_e32 v49, v130
	v_mov_b32_e32 v50, v130
	v_mov_b32_e32 v51, v130
	v_mov_b32_e32 v52, v130
	v_mov_b32_e32 v53, v130
	v_mov_b32_e32 v54, v130
	v_mov_b32_e32 v55, v130
	v_mov_b32_e32 v40, v130
	v_mov_b32_e32 v41, v130
	v_mov_b32_e32 v42, v130
	v_mov_b32_e32 v43, v130
	v_mov_b32_e32 v44, v130
	v_mov_b32_e32 v45, v130
	v_mov_b32_e32 v46, v130
	v_mov_b32_e32 v47, v130
	v_mov_b32_e32 v30, v130
	v_mov_b32_e32 v31, v130
	v_mov_b32_e32 v32, v130
	v_mov_b32_e32 v33, v130
	v_mov_b32_e32 v36, v130
	v_mov_b32_e32 v37, v130
	v_mov_b32_e32 v38, v130
	v_mov_b32_e32 v39, v130
	v_mov_b32_e32 v22, v130
	v_mov_b32_e32 v23, v130
	v_mov_b32_e32 v24, v130
	v_mov_b32_e32 v25, v130
	v_mov_b32_e32 v26, v130
	v_mov_b32_e32 v27, v130
	v_mov_b32_e32 v28, v130
	v_mov_b32_e32 v29, v130
	v_mov_b32_e32 v14, v130
	v_mov_b32_e32 v15, v130
	v_mov_b32_e32 v16, v130
	v_mov_b32_e32 v17, v130
	v_mov_b32_e32 v18, v130
	v_mov_b32_e32 v19, v130
	v_mov_b32_e32 v20, v130
	v_mov_b32_e32 v21, v130
	v_mov_b32_e32 v2, v130
	v_mov_b32_e32 v3, v130
	v_mov_b32_e32 v4, v130
	v_mov_b32_e32 v5, v130
	v_mov_b32_e32 v10, v130
	v_mov_b32_e32 v11, v130
	v_mov_b32_e32 v12, v130
	v_mov_b32_e32 v13, v130

.LBB0_331:
	s_add_i32 s6, s13, 0xdb80
	s_and_b32 s7, s6, 0xffff
	s_mul_i32 s7, s7, 0xaaab
	s_lshr_b32 s8, s7, 16
	s_lshr_b32 s7, s7, 23
	s_mulk_i32 s7, 0xc0
	s_sub_i32 s6, s6, s7
	s_lshl_b32 s6, s6, 6
	v_readlane_b32 s14, v252, 15
	s_and_b32 s6, s6, 0xffc0
	v_readlane_b32 s15, v252, 16
	s_and_b32 s14, s8, 0xff80
	v_add_u32_e32 v2, s6, v138
	v_mov_b32_e32 v3, v34
	v_lshl_add_u64 v[2:3], v[2:3], 2, s[36:37]
	s_mul_i32 s8, s14, 0x1e040
	s_mov_b32 s9, s15
	v_lshl_add_u64 v[2:3], v[2:3], 0, s[8:9]
	s_mov_b32 s7, 0x1e000
	v_add_co_u32_e32 v10, vcc, s7, v2
	s_mov_b32 s7, 0x3c000
	s_nop 0
	v_addc_co_u32_e32 v11, vcc, 0, v3, vcc
	global_load_dword v4, v[2:3], off nt
	global_load_dword v5, v[10:11], off offset:64
	v_add_co_u32_e32 v10, vcc, s7, v2
	s_mov_b32 s7, 0x5a000
	s_nop 0
	v_addc_co_u32_e32 v11, vcc, 0, v3, vcc
	v_add_co_u32_e32 v12, vcc, s7, v2
	s_mov_b32 s7, 0x78000
	s_nop 0
	v_addc_co_u32_e32 v13, vcc, 0, v3, vcc
	global_load_dword v10, v[10:11], off offset:128
	v_writelane_b32 v252, s8, 15
	global_load_dword v11, v[12:13], off offset:192
	v_add_co_u32_e32 v12, vcc, s7, v2
	s_mov_b32 s7, 0x96000
	s_nop 0
	v_addc_co_u32_e32 v13, vcc, 0, v3, vcc
	v_add_co_u32_e32 v14, vcc, s7, v2
	s_mov_b32 s7, 0xb4000
	s_nop 0
	v_addc_co_u32_e32 v15, vcc, 0, v3, vcc
	global_load_dword v12, v[12:13], off offset:256
	v_writelane_b32 v252, s9, 16
	global_load_dword v13, v[14:15], off offset:320
	v_add_co_u32_e32 v14, vcc, s7, v2
	s_mov_b32 s7, 0xd2000
	s_nop 0
	v_addc_co_u32_e32 v15, vcc, 0, v3, vcc
	v_add_co_u32_e32 v16, vcc, s7, v2
	s_mov_b32 s7, 0xf0000
	s_nop 0
	v_addc_co_u32_e32 v17, vcc, 0, v3, vcc
	global_load_dword v14, v[14:15], off offset:384
	s_nop 0
	global_load_dword v15, v[16:17], off offset:448
	v_add_co_u32_e32 v16, vcc, s7, v2
	s_mov_b32 s7, 0x10e000
	s_nop 0
	v_addc_co_u32_e32 v17, vcc, 0, v3, vcc
	v_add_co_u32_e32 v18, vcc, s7, v2
	s_mov_b32 s7, 0x12c000
	s_nop 0
	v_addc_co_u32_e32 v19, vcc, 0, v3, vcc
	global_load_dword v16, v[16:17], off offset:512
	s_nop 0
	global_load_dword v17, v[18:19], off offset:576
	v_add_co_u32_e32 v18, vcc, s7, v2
	s_mov_b32 s7, 0x14a000
	s_nop 0
	v_addc_co_u32_e32 v19, vcc, 0, v3, vcc
	v_add_co_u32_e32 v20, vcc, s7, v2
	s_mov_b32 s7, 0x168000
	s_nop 0
	v_addc_co_u32_e32 v21, vcc, 0, v3, vcc
	global_load_dword v18, v[18:19], off offset:640
	s_nop 0
	global_load_dword v19, v[20:21], off offset:704
	v_add_co_u32_e32 v20, vcc, s7, v2
	s_mov_b32 s7, 0x186000
	s_nop 0
	v_addc_co_u32_e32 v21, vcc, 0, v3, vcc
	v_add_co_u32_e32 v22, vcc, s7, v2
	s_mov_b32 s7, 0x1a4000
	s_nop 0
	v_addc_co_u32_e32 v23, vcc, 0, v3, vcc
	global_load_dword v20, v[20:21], off offset:768
	s_nop 0
	global_load_dword v21, v[22:23], off offset:832
	v_add_co_u32_e32 v22, vcc, s7, v2
	s_mov_b32 s7, 0x1c2000
	s_nop 0
	v_addc_co_u32_e32 v23, vcc, 0, v3, vcc
	v_add_co_u32_e32 v24, vcc, s7, v2
	s_mov_b32 s7, 0x1e0000
	s_nop 0
	v_addc_co_u32_e32 v25, vcc, 0, v3, vcc
	global_load_dword v22, v[22:23], off offset:896
	s_nop 0
	global_load_dword v23, v[24:25], off offset:960
	v_add_co_u32_e32 v24, vcc, s7, v2
	s_mov_b32 s7, 0x1fe000
	s_nop 0
	v_addc_co_u32_e32 v25, vcc, 0, v3, vcc
	v_add_co_u32_e32 v26, vcc, s7, v2
	s_mov_b32 s7, 0x21c000
	s_nop 0
	v_addc_co_u32_e32 v27, vcc, 0, v3, vcc
	global_load_dword v24, v[24:25], off offset:1024
	s_nop 0
	global_load_dword v25, v[26:27], off offset:1088
	v_add_co_u32_e32 v26, vcc, s7, v2
	s_mov_b32 s7, 0x23a000
	s_nop 0
	v_addc_co_u32_e32 v27, vcc, 0, v3, vcc
	v_add_co_u32_e32 v28, vcc, s7, v2
	s_mov_b32 s7, 0x258000
	s_nop 0
	v_addc_co_u32_e32 v29, vcc, 0, v3, vcc
	global_load_dword v26, v[26:27], off offset:1152
	s_nop 0
	global_load_dword v27, v[28:29], off offset:1216
	v_add_co_u32_e32 v28, vcc, s7, v2
	s_mov_b32 s7, 0x276000
	s_nop 0
	v_addc_co_u32_e32 v29, vcc, 0, v3, vcc
	v_add_co_u32_e32 v30, vcc, s7, v2
	s_mov_b32 s7, 0x294000
	s_nop 0
	v_addc_co_u32_e32 v31, vcc, 0, v3, vcc
	global_load_dword v28, v[28:29], off offset:1280
	s_nop 0
	global_load_dword v29, v[30:31], off offset:1344
	v_add_co_u32_e32 v30, vcc, s7, v2
	s_mov_b32 s7, 0x2b2000
	s_nop 0
	v_addc_co_u32_e32 v31, vcc, 0, v3, vcc
	v_add_co_u32_e32 v32, vcc, s7, v2
	s_mov_b32 s7, 0x2d0000
	s_nop 0
	v_addc_co_u32_e32 v33, vcc, 0, v3, vcc
	global_load_dword v30, v[30:31], off offset:1408
	s_nop 0
	global_load_dword v31, v[32:33], off offset:1472
	v_add_co_u32_e32 v32, vcc, s7, v2
	s_mov_b32 s7, 0x2ee000
	s_nop 0
	v_addc_co_u32_e32 v33, vcc, 0, v3, vcc
	v_add_co_u32_e32 v36, vcc, s7, v2
	s_mov_b32 s7, 0x30c000
	s_nop 0
	v_addc_co_u32_e32 v37, vcc, 0, v3, vcc
	global_load_dword v32, v[32:33], off offset:1536
	s_nop 0
	global_load_dword v33, v[36:37], off offset:1600
	v_add_co_u32_e32 v36, vcc, s7, v2
	s_mov_b32 s7, 0x32a000
	s_nop 0
	v_addc_co_u32_e32 v37, vcc, 0, v3, vcc
	v_add_co_u32_e32 v38, vcc, s7, v2
	s_mov_b32 s7, 0x348000
	s_nop 0
	v_addc_co_u32_e32 v39, vcc, 0, v3, vcc
	global_load_dword v36, v[36:37], off offset:1664
	s_nop 0
	global_load_dword v37, v[38:39], off offset:1728
	v_add_co_u32_e32 v38, vcc, s7, v2
	s_mov_b32 s7, 0x366000
	s_nop 0
	v_addc_co_u32_e32 v39, vcc, 0, v3, vcc
	v_add_co_u32_e32 v40, vcc, s7, v2
	s_mov_b32 s7, 0x384000
	s_nop 0
	v_addc_co_u32_e32 v41, vcc, 0, v3, vcc
	global_load_dword v38, v[38:39], off offset:1792
	s_nop 0
	global_load_dword v39, v[40:41], off offset:1856
	v_add_co_u32_e32 v40, vcc, s7, v2
	s_mov_b32 s7, 0x3a2000
	s_nop 0
	v_addc_co_u32_e32 v41, vcc, 0, v3, vcc
	v_add_co_u32_e32 v42, vcc, s7, v2
	s_mov_b32 s7, 0x3c0000
	s_nop 0
	v_addc_co_u32_e32 v43, vcc, 0, v3, vcc
	global_load_dword v40, v[40:41], off offset:1920
	s_nop 0
	global_load_dword v41, v[42:43], off offset:1984
	v_add_co_u32_e32 v42, vcc, s7, v2
	s_mov_b32 s7, 0x3de000
	s_nop 0
	v_addc_co_u32_e32 v43, vcc, 0, v3, vcc
	v_add_co_u32_e32 v44, vcc, s7, v2
	s_mov_b32 s7, 0x3fc000
	s_nop 0
	v_addc_co_u32_e32 v45, vcc, 0, v3, vcc
	global_load_dword v42, v[42:43], off offset:2048
	s_nop 0
	global_load_dword v43, v[44:45], off offset:2112
	v_add_co_u32_e32 v44, vcc, s7, v2
	s_mov_b32 s7, 0x41a000
	s_nop 0
	v_addc_co_u32_e32 v45, vcc, 0, v3, vcc
	v_add_co_u32_e32 v46, vcc, s7, v2
	s_mov_b32 s7, 0x438000
	s_nop 0
	v_addc_co_u32_e32 v47, vcc, 0, v3, vcc
	global_load_dword v44, v[44:45], off offset:2176
	s_nop 0
	global_load_dword v45, v[46:47], off offset:2240
	v_add_co_u32_e32 v46, vcc, s7, v2
	s_mov_b32 s7, 0x456000
	s_nop 0
	v_addc_co_u32_e32 v47, vcc, 0, v3, vcc
	v_add_co_u32_e32 v48, vcc, s7, v2
	s_mov_b32 s7, 0x474000
	s_nop 0
	v_addc_co_u32_e32 v49, vcc, 0, v3, vcc
	global_load_dword v46, v[46:47], off offset:2304
	s_nop 0
	global_load_dword v47, v[48:49], off offset:2368
	v_add_co_u32_e32 v48, vcc, s7, v2
	s_mov_b32 s7, 0x492000
	s_nop 0
	v_addc_co_u32_e32 v49, vcc, 0, v3, vcc
	v_add_co_u32_e32 v50, vcc, s7, v2
	s_mov_b32 s7, 0x4b0000
	s_nop 0
	v_addc_co_u32_e32 v51, vcc, 0, v3, vcc
	global_load_dword v48, v[48:49], off offset:2432
	s_nop 0
	global_load_dword v49, v[50:51], off offset:2496
	v_add_co_u32_e32 v50, vcc, s7, v2
	s_mov_b32 s7, 0x4ce000
	s_nop 0
	v_addc_co_u32_e32 v51, vcc, 0, v3, vcc
	v_add_co_u32_e32 v52, vcc, s7, v2
	s_mov_b32 s7, 0x4ec000
	s_nop 0
	v_addc_co_u32_e32 v53, vcc, 0, v3, vcc
	global_load_dword v50, v[50:51], off offset:2560
	s_nop 0
	global_load_dword v51, v[52:53], off offset:2624
	v_add_co_u32_e32 v52, vcc, s7, v2
	s_mov_b32 s7, 0x50a000
	s_nop 0
	v_addc_co_u32_e32 v53, vcc, 0, v3, vcc
	v_add_co_u32_e32 v54, vcc, s7, v2
	s_mov_b32 s7, 0x528000
	s_nop 0
	v_addc_co_u32_e32 v55, vcc, 0, v3, vcc
	global_load_dword v52, v[52:53], off offset:2688
	s_nop 0
	global_load_dword v53, v[54:55], off offset:2752
	v_add_co_u32_e32 v54, vcc, s7, v2
	s_mov_b32 s7, 0x546000
	s_nop 0
	v_addc_co_u32_e32 v55, vcc, 0, v3, vcc
	v_add_co_u32_e32 v56, vcc, s7, v2
	s_mov_b32 s7, 0x564000
	s_nop 0
	v_addc_co_u32_e32 v57, vcc, 0, v3, vcc
	global_load_dword v54, v[54:55], off offset:2816
	s_nop 0
	global_load_dword v55, v[56:57], off offset:2880
	v_add_co_u32_e32 v56, vcc, s7, v2
	s_mov_b32 s7, 0x582000
	s_nop 0
	v_addc_co_u32_e32 v57, vcc, 0, v3, vcc
	v_add_co_u32_e32 v58, vcc, s7, v2
	s_mov_b32 s7, 0x5a0000
	s_nop 0
	v_addc_co_u32_e32 v59, vcc, 0, v3, vcc
	global_load_dword v56, v[56:57], off offset:2944
	s_nop 0
	global_load_dword v57, v[58:59], off offset:3008
	v_add_co_u32_e32 v58, vcc, s7, v2
	s_mov_b32 s7, 0x5be000
	s_nop 0
	v_addc_co_u32_e32 v59, vcc, 0, v3, vcc
	v_add_co_u32_e32 v60, vcc, s7, v2
	s_mov_b32 s7, 0x5dc000
	s_nop 0
	v_addc_co_u32_e32 v61, vcc, 0, v3, vcc
	global_load_dword v58, v[58:59], off offset:3072
	s_nop 0
	global_load_dword v59, v[60:61], off offset:3136
	v_add_co_u32_e32 v60, vcc, s7, v2
	s_mov_b32 s7, 0x5fa000
	s_nop 0
	v_addc_co_u32_e32 v61, vcc, 0, v3, vcc
	v_add_co_u32_e32 v62, vcc, s7, v2
	s_mov_b32 s7, 0x618000
	s_nop 0
	v_addc_co_u32_e32 v63, vcc, 0, v3, vcc
	global_load_dword v60, v[60:61], off offset:3200
	s_nop 0
	global_load_dword v61, v[62:63], off offset:3264
	v_add_co_u32_e32 v62, vcc, s7, v2
	s_mov_b32 s7, 0x636000
	s_nop 0
	v_addc_co_u32_e32 v63, vcc, 0, v3, vcc
	v_add_co_u32_e32 v64, vcc, s7, v2
	s_mov_b32 s7, 0x654000
	s_nop 0
	v_addc_co_u32_e32 v65, vcc, 0, v3, vcc
	global_load_dword v62, v[62:63], off offset:3328
	s_nop 0
	global_load_dword v63, v[64:65], off offset:3392
	v_add_co_u32_e32 v64, vcc, s7, v2
	s_mov_b32 s7, 0x672000
	s_nop 0
	v_addc_co_u32_e32 v65, vcc, 0, v3, vcc
	v_add_co_u32_e32 v66, vcc, s7, v2
	s_mov_b32 s7, 0x690000
	s_nop 0
	v_addc_co_u32_e32 v67, vcc, 0, v3, vcc
	global_load_dword v64, v[64:65], off offset:3456
	s_nop 0
	global_load_dword v65, v[66:67], off offset:3520
	v_add_co_u32_e32 v66, vcc, s7, v2
	s_mov_b32 s7, 0x6ae000
	s_nop 0
	v_addc_co_u32_e32 v67, vcc, 0, v3, vcc
	v_add_co_u32_e32 v68, vcc, s7, v2
	s_mov_b32 s7, 0x6cc000
	s_nop 0
	v_addc_co_u32_e32 v69, vcc, 0, v3, vcc
	global_load_dword v66, v[66:67], off offset:3584
	s_nop 0
	global_load_dword v67, v[68:69], off offset:3648
	v_add_co_u32_e32 v68, vcc, s7, v2
	s_mov_b32 s7, 0x6ea000
	s_nop 0
	v_addc_co_u32_e32 v69, vcc, 0, v3, vcc
	v_add_co_u32_e32 v70, vcc, s7, v2
	s_mov_b32 s7, 0x708000
	s_nop 0
	v_addc_co_u32_e32 v71, vcc, 0, v3, vcc
	global_load_dword v68, v[68:69], off offset:3712
	s_nop 0
	global_load_dword v69, v[70:71], off offset:3776
	v_add_co_u32_e32 v70, vcc, s7, v2
	s_mov_b32 s7, 0x726000
	s_nop 0
	v_addc_co_u32_e32 v71, vcc, 0, v3, vcc
	v_add_co_u32_e32 v72, vcc, s7, v2
	s_mov_b32 s7, 0x744000
	s_nop 0
	v_addc_co_u32_e32 v73, vcc, 0, v3, vcc
	global_load_dword v70, v[70:71], off offset:3840
	s_nop 0
	global_load_dword v71, v[72:73], off offset:3904
	v_add_co_u32_e32 v72, vcc, s7, v2
	s_mov_b32 s7, 0x762000
	s_nop 0
	v_addc_co_u32_e32 v73, vcc, 0, v3, vcc
	v_add_co_u32_e32 v74, vcc, s7, v2
	s_mov_b32 s7, 0x781000
	s_nop 0
	v_addc_co_u32_e32 v75, vcc, 0, v3, vcc
	global_load_dword v72, v[72:73], off offset:3968
	s_nop 0
	global_load_dword v73, v[74:75], off offset:4032
	v_add_co_u32_e32 v74, vcc, s7, v2
	s_mov_b32 s7, 0x79f000
	s_nop 0
	v_addc_co_u32_e32 v75, vcc, 0, v3, vcc
	v_add_co_u32_e32 v76, vcc, s7, v2
	s_mov_b32 s7, 0x7bd000
	s_nop 0
	v_addc_co_u32_e32 v77, vcc, 0, v3, vcc
	global_load_dword v74, v[74:75], off nt
	s_nop 0
	global_load_dword v75, v[76:77], off offset:64
	v_add_co_u32_e32 v76, vcc, s7, v2
	s_mov_b32 s7, 0x7db000
	s_nop 0
	v_addc_co_u32_e32 v77, vcc, 0, v3, vcc
	v_add_co_u32_e32 v78, vcc, s7, v2
	s_mov_b32 s7, 0x7f9000
	s_nop 0
	v_addc_co_u32_e32 v79, vcc, 0, v3, vcc
	global_load_dword v76, v[76:77], off offset:128
	s_nop 0
	global_load_dword v77, v[78:79], off offset:192
	v_add_co_u32_e32 v78, vcc, s7, v2
	s_mov_b32 s7, 0x817000
	s_nop 0
	v_addc_co_u32_e32 v79, vcc, 0, v3, vcc
	v_add_co_u32_e32 v80, vcc, s7, v2
	s_mov_b32 s7, 0x835000
	s_nop 0
	v_addc_co_u32_e32 v81, vcc, 0, v3, vcc
	global_load_dword v78, v[78:79], off offset:256
	s_nop 0
	global_load_dword v79, v[80:81], off offset:320
	v_add_co_u32_e32 v80, vcc, s7, v2
	s_mov_b32 s7, 0x853000
	s_nop 0
	v_addc_co_u32_e32 v81, vcc, 0, v3, vcc
	v_add_co_u32_e32 v82, vcc, s7, v2
	s_mov_b32 s7, 0x871000
	s_nop 0
	v_addc_co_u32_e32 v83, vcc, 0, v3, vcc
	global_load_dword v80, v[80:81], off offset:384
	s_nop 0
	global_load_dword v81, v[82:83], off offset:448
	v_add_co_u32_e32 v82, vcc, s7, v2
	s_mov_b32 s7, 0x88f000
	s_nop 0
	v_addc_co_u32_e32 v83, vcc, 0, v3, vcc
	v_add_co_u32_e32 v84, vcc, s7, v2
	s_mov_b32 s7, 0x8ad000
	s_nop 0
	v_addc_co_u32_e32 v85, vcc, 0, v3, vcc
	global_load_dword v82, v[82:83], off offset:512
	s_nop 0
	global_load_dword v83, v[84:85], off offset:576
	v_add_co_u32_e32 v84, vcc, s7, v2
	s_mov_b32 s7, 0x8cb000
	s_nop 0
	v_addc_co_u32_e32 v85, vcc, 0, v3, vcc
	v_add_co_u32_e32 v86, vcc, s7, v2
	s_mov_b32 s7, 0x8e9000
	s_nop 0
	v_addc_co_u32_e32 v87, vcc, 0, v3, vcc
	global_load_dword v84, v[84:85], off offset:640
	s_nop 0
	global_load_dword v85, v[86:87], off offset:704
	v_add_co_u32_e32 v86, vcc, s7, v2
	s_mov_b32 s7, 0x907000
	s_nop 0
	v_addc_co_u32_e32 v87, vcc, 0, v3, vcc
	v_add_co_u32_e32 v88, vcc, s7, v2
	s_mov_b32 s7, 0x925000
	s_nop 0
	v_addc_co_u32_e32 v89, vcc, 0, v3, vcc
	global_load_dword v86, v[86:87], off offset:768
	s_nop 0
	global_load_dword v87, v[88:89], off offset:832
	v_add_co_u32_e32 v88, vcc, s7, v2
	s_mov_b32 s7, 0x943000
	s_nop 0
	v_addc_co_u32_e32 v89, vcc, 0, v3, vcc
	v_add_co_u32_e32 v90, vcc, s7, v2
	s_mov_b32 s7, 0x961000
	s_nop 0
	v_addc_co_u32_e32 v91, vcc, 0, v3, vcc
	global_load_dword v88, v[88:89], off offset:896
	s_nop 0
	global_load_dword v89, v[90:91], off offset:960
	v_add_co_u32_e32 v90, vcc, s7, v2
	s_mov_b32 s7, 0x97f000
	s_nop 0
	v_addc_co_u32_e32 v91, vcc, 0, v3, vcc
	v_add_co_u32_e32 v92, vcc, s7, v2
	s_mov_b32 s7, 0x99d000
	s_nop 0
	v_addc_co_u32_e32 v93, vcc, 0, v3, vcc
	global_load_dword v90, v[90:91], off offset:1024
	s_nop 0
	global_load_dword v91, v[92:93], off offset:1088
	v_add_co_u32_e32 v92, vcc, s7, v2
	s_mov_b32 s7, 0x9bb000
	s_nop 0
	v_addc_co_u32_e32 v93, vcc, 0, v3, vcc
	v_add_co_u32_e32 v94, vcc, s7, v2
	s_mov_b32 s7, 0x9d9000
	s_nop 0
	v_addc_co_u32_e32 v95, vcc, 0, v3, vcc
	global_load_dword v92, v[92:93], off offset:1152
	s_nop 0
	global_load_dword v93, v[94:95], off offset:1216
	v_add_co_u32_e32 v94, vcc, s7, v2
	s_mov_b32 s7, 0x9f7000
	s_nop 0
	v_addc_co_u32_e32 v95, vcc, 0, v3, vcc
	v_add_co_u32_e32 v96, vcc, s7, v2
	s_mov_b32 s7, 0xa15000
	s_nop 0
	v_addc_co_u32_e32 v97, vcc, 0, v3, vcc
	global_load_dword v94, v[94:95], off offset:1280
	s_nop 0
	global_load_dword v95, v[96:97], off offset:1344
	v_add_co_u32_e32 v96, vcc, s7, v2
	s_mov_b32 s7, 0xa33000
	s_nop 0
	v_addc_co_u32_e32 v97, vcc, 0, v3, vcc
	v_add_co_u32_e32 v98, vcc, s7, v2
	s_mov_b32 s7, 0xa51000
	s_nop 0
	v_addc_co_u32_e32 v99, vcc, 0, v3, vcc
	global_load_dword v96, v[96:97], off offset:1408
	s_nop 0
	global_load_dword v97, v[98:99], off offset:1472
	v_add_co_u32_e32 v98, vcc, s7, v2
	s_mov_b32 s7, 0xa6f000
	s_nop 0
	v_addc_co_u32_e32 v99, vcc, 0, v3, vcc
	v_add_co_u32_e32 v100, vcc, s7, v2
	s_mov_b32 s7, 0xa8d000
	s_nop 0
	v_addc_co_u32_e32 v101, vcc, 0, v3, vcc
	global_load_dword v98, v[98:99], off offset:1536
	s_nop 0
	global_load_dword v99, v[100:101], off offset:1600
	v_add_co_u32_e32 v100, vcc, s7, v2
	s_mov_b32 s7, 0xaab000
	s_nop 0
	v_addc_co_u32_e32 v101, vcc, 0, v3, vcc
	v_add_co_u32_e32 v102, vcc, s7, v2
	s_mov_b32 s7, 0xac9000
	s_nop 0
	v_addc_co_u32_e32 v103, vcc, 0, v3, vcc
	global_load_dword v100, v[100:101], off offset:1664
	s_nop 0
	global_load_dword v101, v[102:103], off offset:1728
	v_add_co_u32_e32 v102, vcc, s7, v2
	s_mov_b32 s7, 0xae7000
	s_nop 0
	v_addc_co_u32_e32 v103, vcc, 0, v3, vcc
	v_add_co_u32_e32 v104, vcc, s7, v2
	s_mov_b32 s7, 0xb05000
	s_nop 0
	v_addc_co_u32_e32 v105, vcc, 0, v3, vcc
	global_load_dword v102, v[102:103], off offset:1792
	s_nop 0
	global_load_dword v103, v[104:105], off offset:1856
	v_add_co_u32_e32 v104, vcc, s7, v2
	s_mov_b32 s7, 0xb23000
	s_nop 0
	v_addc_co_u32_e32 v105, vcc, 0, v3, vcc
	v_add_co_u32_e32 v106, vcc, s7, v2
	s_mov_b32 s7, 0xb41000
	s_nop 0
	v_addc_co_u32_e32 v107, vcc, 0, v3, vcc
	global_load_dword v104, v[104:105], off offset:1920
	s_nop 0
	global_load_dword v1, v[106:107], off offset:1984
	v_add_co_u32_e32 v106, vcc, s7, v2
	s_mov_b32 s7, 0xb5f000
	s_nop 0
	v_addc_co_u32_e32 v107, vcc, 0, v3, vcc
	global_load_dword v105, v[106:107], off offset:2048
	v_add_co_u32_e32 v106, vcc, s7, v2
	s_mov_b32 s7, 0xb7d000
	s_nop 0
	v_addc_co_u32_e32 v107, vcc, 0, v3, vcc
	global_load_dword v108, v[106:107], off offset:2112
	v_add_co_u32_e32 v106, vcc, s7, v2
	s_mov_b32 s7, 0xb9b000
	s_nop 0
	v_addc_co_u32_e32 v107, vcc, 0, v3, vcc
	global_load_dword v109, v[106:107], off offset:2176
	v_add_co_u32_e32 v106, vcc, s7, v2
	s_mov_b32 s7, 0xbb9000
	s_nop 0
	v_addc_co_u32_e32 v107, vcc, 0, v3, vcc
	global_load_dword v110, v[106:107], off offset:2240
	v_add_co_u32_e32 v106, vcc, s7, v2
	s_mov_b32 s7, 0xbd7000
	s_nop 0
	v_addc_co_u32_e32 v107, vcc, 0, v3, vcc
	global_load_dword v111, v[106:107], off offset:2304
	v_add_co_u32_e32 v106, vcc, s7, v2
	s_mov_b32 s7, 0xbf5000
	s_nop 0
	v_addc_co_u32_e32 v107, vcc, 0, v3, vcc
	global_load_dword v112, v[106:107], off offset:2368
	v_add_co_u32_e32 v106, vcc, s7, v2
	s_mov_b32 s7, 0xc13000
	s_nop 0
	v_addc_co_u32_e32 v107, vcc, 0, v3, vcc
	global_load_dword v113, v[106:107], off offset:2432
	v_add_co_u32_e32 v106, vcc, s7, v2
	s_mov_b32 s7, 0xc31000
	s_nop 0
	v_addc_co_u32_e32 v107, vcc, 0, v3, vcc
	global_load_dword v114, v[106:107], off offset:2496
	v_add_co_u32_e32 v106, vcc, s7, v2
	s_mov_b32 s7, 0xc4f000
	s_nop 0
	v_addc_co_u32_e32 v107, vcc, 0, v3, vcc
	global_load_dword v115, v[106:107], off offset:2560
	v_add_co_u32_e32 v106, vcc, s7, v2
	s_mov_b32 s7, 0xc6d000
	s_nop 0
	v_addc_co_u32_e32 v107, vcc, 0, v3, vcc
	global_load_dword v116, v[106:107], off offset:2624
	v_add_co_u32_e32 v106, vcc, s7, v2
	s_mov_b32 s7, 0xc8b000
	s_nop 0
	v_addc_co_u32_e32 v107, vcc, 0, v3, vcc
	global_load_dword v117, v[106:107], off offset:2688
	v_add_co_u32_e32 v106, vcc, s7, v2
	s_mov_b32 s7, 0xca9000
	s_nop 0
	v_addc_co_u32_e32 v107, vcc, 0, v3, vcc
	global_load_dword v118, v[106:107], off offset:2752
	v_add_co_u32_e32 v106, vcc, s7, v2
	s_mov_b32 s7, 0xcc7000
	s_nop 0
	v_addc_co_u32_e32 v107, vcc, 0, v3, vcc
	global_load_dword v119, v[106:107], off offset:2816
	v_add_co_u32_e32 v106, vcc, s7, v2
	s_mov_b32 s7, 0xce5000
	s_nop 0
	v_addc_co_u32_e32 v107, vcc, 0, v3, vcc
	global_load_dword v120, v[106:107], off offset:2880
	v_add_co_u32_e32 v106, vcc, s7, v2
	s_mov_b32 s7, 0xd03000
	s_nop 0
	v_addc_co_u32_e32 v107, vcc, 0, v3, vcc
	global_load_dword v121, v[106:107], off offset:2944
	v_add_co_u32_e32 v106, vcc, s7, v2
	s_mov_b32 s7, 0xd21000
	s_nop 0
	v_addc_co_u32_e32 v107, vcc, 0, v3, vcc
	global_load_dword v122, v[106:107], off offset:3008
	v_add_co_u32_e32 v106, vcc, s7, v2
	s_mov_b32 s7, 0xd3f000
	s_nop 0
	v_addc_co_u32_e32 v107, vcc, 0, v3, vcc
	global_load_dword v123, v[106:107], off offset:3072
	v_add_co_u32_e32 v106, vcc, s7, v2
	s_mov_b32 s7, 0xd5d000
	s_nop 0
	v_addc_co_u32_e32 v107, vcc, 0, v3, vcc
	global_load_dword v124, v[106:107], off offset:3136
	v_add_co_u32_e32 v106, vcc, s7, v2
	s_mov_b32 s7, 0xd7b000
	s_nop 0
	v_addc_co_u32_e32 v107, vcc, 0, v3, vcc
	global_load_dword v125, v[106:107], off offset:3200
	v_add_co_u32_e32 v106, vcc, s7, v2
	s_mov_b32 s7, 0xd99000
	s_nop 0
	v_addc_co_u32_e32 v107, vcc, 0, v3, vcc
	global_load_dword v126, v[106:107], off offset:3264
	v_add_co_u32_e32 v106, vcc, s7, v2
	s_mov_b32 s7, 0xdb7000
	s_nop 0
	v_addc_co_u32_e32 v107, vcc, 0, v3, vcc
	global_load_dword v127, v[106:107], off offset:3328
	v_add_co_u32_e32 v106, vcc, s7, v2
	s_mov_b32 s7, 0xdd5000
	s_nop 0
	v_addc_co_u32_e32 v107, vcc, 0, v3, vcc
	global_load_dword v128, v[106:107], off offset:3392
	v_add_co_u32_e32 v106, vcc, s7, v2
	s_mov_b32 s7, 0xdf3000
	s_nop 0
	v_addc_co_u32_e32 v107, vcc, 0, v3, vcc
	global_load_dword v129, v[106:107], off offset:3456
	v_add_co_u32_e32 v106, vcc, s7, v2
	s_mov_b32 s7, 0xe11000
	s_nop 0
	v_addc_co_u32_e32 v107, vcc, 0, v3, vcc
	global_load_dword v130, v[106:107], off offset:3520
	v_add_co_u32_e32 v106, vcc, s7, v2
	s_mov_b32 s7, 0xe2f000
	s_nop 0
	v_addc_co_u32_e32 v107, vcc, 0, v3, vcc
	global_load_dword v131, v[106:107], off offset:3584
	v_add_co_u32_e32 v106, vcc, s7, v2
	s_mov_b32 s7, 0xe4d000
	s_nop 0
	v_addc_co_u32_e32 v107, vcc, 0, v3, vcc
	global_load_dword v132, v[106:107], off offset:3648
	v_add_co_u32_e32 v106, vcc, s7, v2
	s_mov_b32 s7, 0xe6b000
	s_nop 0
	v_addc_co_u32_e32 v107, vcc, 0, v3, vcc
	global_load_dword v133, v[106:107], off offset:3712
	v_add_co_u32_e32 v106, vcc, s7, v2
	s_mov_b32 s7, 0xe89000
	s_nop 0
	v_addc_co_u32_e32 v107, vcc, 0, v3, vcc
	global_load_dword v134, v[106:107], off offset:3776
	v_add_co_u32_e32 v106, vcc, s7, v2
	s_mov_b32 s7, 0xea7000
	s_nop 0
	v_addc_co_u32_e32 v107, vcc, 0, v3, vcc
	global_load_dword v135, v[106:107], off offset:3840
	v_add_co_u32_e32 v106, vcc, s7, v2
	s_mov_b32 s7, 0xec5000
	s_nop 0
	v_addc_co_u32_e32 v107, vcc, 0, v3, vcc
	global_load_dword v140, v[106:107], off offset:3904
	v_add_co_u32_e32 v106, vcc, s7, v2
	s_mov_b32 s7, 0xee3000
	s_nop 0
	v_addc_co_u32_e32 v107, vcc, 0, v3, vcc
	v_add_co_u32_e32 v2, vcc, s7, v2
	global_load_dword v106, v[106:107], off offset:3968
	s_nop 0
	v_addc_co_u32_e32 v3, vcc, 0, v3, vcc
	global_load_dword v107, v[2:3], off offset:4032
	s_waitcnt vmcnt(0)
	v_mul_f32_e32 v3, 0x42800000, v4
	v_mul_f32_e32 v4, 0x42800000, v5
	v_mov_b32_e32 v2, v34
	v_cvt_pk_fp8_f32 v2, v3, v4
	v_mul_f32_e32 v5, 0x42800000, v10
	v_mul_f32_e32 v10, 0x42800000, v11
	v_mul_f32_e32 v4, 0x42800000, v12
	v_cvt_pk_fp8_f32 v2, v5, v10 op_sel:[0,0,1]
	v_mul_f32_e32 v5, 0x42800000, v13
	v_mov_b32_e32 v3, v34
	v_cvt_pk_fp8_f32 v3, v4, v5
	v_mul_f32_e32 v10, 0x42800000, v14
	v_mul_f32_e32 v11, 0x42800000, v15
	v_mul_f32_e32 v5, 0x42800000, v16
	v_cvt_pk_fp8_f32 v3, v10, v11 op_sel:[0,0,1]
	v_mul_f32_e32 v10, 0x42800000, v17
	v_mov_b32_e32 v4, v34
	v_cvt_pk_fp8_f32 v4, v5, v10
	v_mul_f32_e32 v11, 0x42800000, v18
	v_mul_f32_e32 v12, 0x42800000, v19
	v_mul_f32_e32 v10, 0x42800000, v20
	v_cvt_pk_fp8_f32 v4, v11, v12 op_sel:[0,0,1]
	v_mul_f32_e32 v11, 0x42800000, v21
	v_mov_b32_e32 v5, v34
	v_cvt_pk_fp8_f32 v5, v10, v11
	v_readfirstlane_b32 s7, v0
	v_mul_f32_e32 v12, 0x42800000, v22
	v_mul_f32_e32 v13, 0x42800000, v23
	s_lshl_b32 s7, s7, 8
	v_cvt_pk_fp8_f32 v5, v12, v13 op_sel:[0,0,1]
	s_and_b32 s7, s7, 0x7fffc000
	s_add_i32 s7, s7, 0
	v_add_u32_e32 v141, s7, v139
	ds_write_b128 v141, v[2:5]
	v_mul_f32_e32 v3, 0x42800000, v24
	v_mul_f32_e32 v4, 0x42800000, v25
	v_mov_b32_e32 v2, v34
	v_cvt_pk_fp8_f32 v2, v3, v4
	v_mul_f32_e32 v5, 0x42800000, v26
	v_mul_f32_e32 v10, 0x42800000, v27
	v_mul_f32_e32 v4, 0x42800000, v28
	v_cvt_pk_fp8_f32 v2, v5, v10 op_sel:[0,0,1]
	v_mul_f32_e32 v5, 0x42800000, v29
	v_mov_b32_e32 v3, v34
	v_cvt_pk_fp8_f32 v3, v4, v5
	v_mul_f32_e32 v10, 0x42800000, v30
	v_mul_f32_e32 v11, 0x42800000, v31
	v_mul_f32_e32 v5, 0x42800000, v32
	v_cvt_pk_fp8_f32 v3, v10, v11 op_sel:[0,0,1]
	v_mul_f32_e32 v10, 0x42800000, v33
	v_mov_b32_e32 v4, v34
	v_cvt_pk_fp8_f32 v4, v5, v10
	v_mul_f32_e32 v11, 0x42800000, v36
	v_mul_f32_e32 v12, 0x42800000, v37
	v_mul_f32_e32 v10, 0x42800000, v38
	v_cvt_pk_fp8_f32 v4, v11, v12 op_sel:[0,0,1]
	v_mul_f32_e32 v11, 0x42800000, v39
	v_mov_b32_e32 v5, v34
	v_cvt_pk_fp8_f32 v5, v10, v11
	v_mul_f32_e32 v12, 0x42800000, v40
	v_mul_f32_e32 v13, 0x42800000, v41
	v_mul_f32_e32 v10, 0x42800000, v45
	v_cvt_pk_fp8_f32 v5, v12, v13 op_sel:[0,0,1]
	v_mul_f32_e32 v11, 0x42800000, v49
	v_mul_f32_e32 v12, 0x42800000, v53
	v_mul_f32_e32 v13, 0x42800000, v57
	ds_write_b128 v141, v[2:5] offset:16
	v_mul_f32_e32 v3, 0x42800000, v42
	v_mul_f32_e32 v4, 0x42800000, v43
	v_mov_b32_e32 v2, v34
	v_cvt_pk_fp8_f32 v2, v3, v4
	v_mul_f32_e32 v5, 0x42800000, v44
	v_mul_f32_e32 v4, 0x42800000, v46
	v_mov_b32_e32 v3, v34
	v_cvt_pk_fp8_f32 v2, v5, v10 op_sel:[0,0,1]
	v_mul_f32_e32 v5, 0x42800000, v47
	v_cvt_pk_fp8_f32 v3, v4, v5
	v_mul_f32_e32 v10, 0x42800000, v48
	v_mul_f32_e32 v5, 0x42800000, v50
	v_mov_b32_e32 v4, v34
	v_cvt_pk_fp8_f32 v3, v10, v11 op_sel:[0,0,1]
	v_mul_f32_e32 v10, 0x42800000, v51
	v_cvt_pk_fp8_f32 v4, v5, v10
	v_mul_f32_e32 v11, 0x42800000, v52
	v_mul_f32_e32 v10, 0x42800000, v54
	v_mov_b32_e32 v5, v34
	v_cvt_pk_fp8_f32 v4, v11, v12 op_sel:[0,0,1]
	v_mul_f32_e32 v11, 0x42800000, v55
	v_cvt_pk_fp8_f32 v5, v10, v11
	v_mul_f32_e32 v12, 0x42800000, v56
	v_mul_f32_e32 v10, 0x42800000, v61
	v_mul_f32_e32 v11, 0x42800000, v65
	v_cvt_pk_fp8_f32 v5, v12, v13 op_sel:[0,0,1]
	v_mul_f32_e32 v12, 0x42800000, v69
	v_mul_f32_e32 v13, 0x42800000, v73
	v_mul_f32_e32 v1, 0x42800000, v1
	ds_write_b128 v141, v[2:5] offset:32
	v_mul_f32_e32 v3, 0x42800000, v58
	v_mul_f32_e32 v4, 0x42800000, v59
	v_mov_b32_e32 v2, v34
	v_cvt_pk_fp8_f32 v2, v3, v4
	v_mul_f32_e32 v5, 0x42800000, v60
	v_mul_f32_e32 v4, 0x42800000, v62
	v_mov_b32_e32 v3, v34
	v_cvt_pk_fp8_f32 v2, v5, v10 op_sel:[0,0,1]
	v_mul_f32_e32 v5, 0x42800000, v63
	v_cvt_pk_fp8_f32 v3, v4, v5
	v_mul_f32_e32 v10, 0x42800000, v64
	v_mul_f32_e32 v5, 0x42800000, v66
	v_mov_b32_e32 v4, v34
	v_cvt_pk_fp8_f32 v3, v10, v11 op_sel:[0,0,1]
	v_mul_f32_e32 v10, 0x42800000, v67
	v_cvt_pk_fp8_f32 v4, v5, v10
	v_mul_f32_e32 v11, 0x42800000, v68
	v_mul_f32_e32 v10, 0x42800000, v70
	v_mov_b32_e32 v5, v34
	v_cvt_pk_fp8_f32 v4, v11, v12 op_sel:[0,0,1]
	v_mul_f32_e32 v11, 0x42800000, v71
	v_cvt_pk_fp8_f32 v5, v10, v11
	v_mul_f32_e32 v12, 0x42800000, v72
	v_mul_f32_e32 v10, 0x42800000, v77
	v_mul_f32_e32 v11, 0x42800000, v81
	v_cvt_pk_fp8_f32 v5, v12, v13 op_sel:[0,0,1]
	v_mul_f32_e32 v12, 0x42800000, v85
	v_mul_f32_e32 v13, 0x42800000, v89
	ds_write_b128 v141, v[2:5] offset:48
	v_mul_f32_e32 v3, 0x42800000, v74
	v_mul_f32_e32 v4, 0x42800000, v75
	v_mov_b32_e32 v2, v34
	v_cvt_pk_fp8_f32 v2, v3, v4
	v_mul_f32_e32 v5, 0x42800000, v76
	v_mul_f32_e32 v4, 0x42800000, v78
	v_mov_b32_e32 v3, v34
	v_cvt_pk_fp8_f32 v2, v5, v10 op_sel:[0,0,1]
	v_mul_f32_e32 v5, 0x42800000, v79
	v_cvt_pk_fp8_f32 v3, v4, v5
	v_mul_f32_e32 v10, 0x42800000, v80
	v_mul_f32_e32 v5, 0x42800000, v82
	v_mov_b32_e32 v4, v34
	v_cvt_pk_fp8_f32 v3, v10, v11 op_sel:[0,0,1]
	v_mul_f32_e32 v10, 0x42800000, v83
	v_cvt_pk_fp8_f32 v4, v5, v10
	v_mul_f32_e32 v11, 0x42800000, v84
	v_mul_f32_e32 v10, 0x42800000, v86
	v_mov_b32_e32 v5, v34
	v_cvt_pk_fp8_f32 v4, v11, v12 op_sel:[0,0,1]
	v_mul_f32_e32 v11, 0x42800000, v87
	v_cvt_pk_fp8_f32 v5, v10, v11
	v_mul_f32_e32 v12, 0x42800000, v88
	v_mul_f32_e32 v10, 0x42800000, v93
	v_mul_f32_e32 v11, 0x42800000, v97
	v_cvt_pk_fp8_f32 v5, v12, v13 op_sel:[0,0,1]
	v_mul_f32_e32 v12, 0x42800000, v101
	ds_write_b128 v141, v[2:5] offset:64
	v_mul_f32_e32 v3, 0x42800000, v90
	v_mul_f32_e32 v4, 0x42800000, v91
	v_mov_b32_e32 v2, v34
	v_cvt_pk_fp8_f32 v2, v3, v4
	v_mul_f32_e32 v5, 0x42800000, v92
	v_mul_f32_e32 v4, 0x42800000, v94
	v_mov_b32_e32 v3, v34
	v_cvt_pk_fp8_f32 v2, v5, v10 op_sel:[0,0,1]
	v_mul_f32_e32 v5, 0x42800000, v95
	v_cvt_pk_fp8_f32 v3, v4, v5
	v_mul_f32_e32 v10, 0x42800000, v96
	v_mul_f32_e32 v5, 0x42800000, v98
	v_mov_b32_e32 v4, v34
	v_cvt_pk_fp8_f32 v3, v10, v11 op_sel:[0,0,1]
	v_mul_f32_e32 v10, 0x42800000, v99
	v_cvt_pk_fp8_f32 v4, v5, v10
	v_mul_f32_e32 v11, 0x42800000, v100
	v_mul_f32_e32 v10, 0x42800000, v102
	v_mov_b32_e32 v5, v34
	v_cvt_pk_fp8_f32 v4, v11, v12 op_sel:[0,0,1]
	v_mul_f32_e32 v11, 0x42800000, v103
	v_cvt_pk_fp8_f32 v5, v10, v11
	v_mul_f32_e32 v12, 0x42800000, v104
	v_mul_f32_e32 v10, 0x42800000, v114
	v_mul_f32_e32 v11, 0x42800000, v118
	v_cvt_pk_fp8_f32 v5, v12, v1 op_sel:[0,0,1]
	v_mul_f32_e32 v1, 0x42800000, v105
	v_mul_f32_e32 v12, 0x42800000, v122
	ds_write_b128 v141, v[2:5] offset:80
	v_mul_f32_e32 v3, 0x42800000, v108
	v_mov_b32_e32 v2, v34
	v_cvt_pk_fp8_f32 v2, v1, v3
	v_mul_f32_e32 v4, 0x42800000, v109
	v_mul_f32_e32 v5, 0x42800000, v110
	v_mul_f32_e32 v1, 0x42800000, v111
	v_cvt_pk_fp8_f32 v2, v4, v5 op_sel:[0,0,1]
	v_mul_f32_e32 v4, 0x42800000, v112
	v_mov_b32_e32 v3, v34
	v_cvt_pk_fp8_f32 v3, v1, v4
	v_mul_f32_e32 v5, 0x42800000, v113
	v_mul_f32_e32 v1, 0x42800000, v115
	v_mov_b32_e32 v4, v34
	v_cvt_pk_fp8_f32 v3, v5, v10 op_sel:[0,0,1]
	v_mul_f32_e32 v5, 0x42800000, v116
	v_cvt_pk_fp8_f32 v4, v1, v5
	v_mul_f32_e32 v10, 0x42800000, v117
	v_mul_f32_e32 v1, 0x42800000, v119
	v_mov_b32_e32 v5, v34
	v_cvt_pk_fp8_f32 v4, v10, v11 op_sel:[0,0,1]
	v_mul_f32_e32 v10, 0x42800000, v120
	v_cvt_pk_fp8_f32 v5, v1, v10
	v_mul_f32_e32 v11, 0x42800000, v121
	v_mul_f32_e32 v1, 0x42800000, v123
	v_mul_f32_e32 v10, 0x42800000, v130
	v_cvt_pk_fp8_f32 v5, v11, v12 op_sel:[0,0,1]
	v_mul_f32_e32 v11, 0x42800000, v134
	v_mul_f32_e32 v12, 0x42800000, v107
	ds_write_b128 v141, v[2:5] offset:96
	v_mul_f32_e32 v3, 0x42800000, v124
	v_mov_b32_e32 v2, v34
	v_cvt_pk_fp8_f32 v2, v1, v3
	v_mul_f32_e32 v4, 0x42800000, v125
	v_mul_f32_e32 v5, 0x42800000, v126
	v_mul_f32_e32 v1, 0x42800000, v127
	v_cvt_pk_fp8_f32 v2, v4, v5 op_sel:[0,0,1]
	v_mul_f32_e32 v4, 0x42800000, v128
	v_mov_b32_e32 v3, v34
	v_cvt_pk_fp8_f32 v3, v1, v4
	v_mul_f32_e32 v5, 0x42800000, v129
	v_mul_f32_e32 v1, 0x42800000, v131
	v_mov_b32_e32 v4, v34
	v_cvt_pk_fp8_f32 v3, v5, v10 op_sel:[0,0,1]
	v_mul_f32_e32 v5, 0x42800000, v132
	v_cvt_pk_fp8_f32 v4, v1, v5
	v_mul_f32_e32 v10, 0x42800000, v133
	v_mul_f32_e32 v1, 0x42800000, v135
	v_mov_b32_e32 v5, v34
	v_cvt_pk_fp8_f32 v4, v10, v11 op_sel:[0,0,1]
	v_mul_f32_e32 v10, 0x42800000, v140
	v_cvt_pk_fp8_f32 v5, v1, v10
	v_mul_f32_e32 v11, 0x42800000, v106
	v_add_u32_e32 v1, s7, v137
	v_cvt_pk_fp8_f32 v5, v11, v12 op_sel:[0,0,1]
	ds_write_b128 v141, v[2:5] offset:112
	v_add_u32_e32 v2, s6, v136
	v_ashrrev_i32_e32 v3, 31, v2
	v_lshlrev_b64 v[2:3], 12, v[2:3]
	v_lshl_add_u64 v[2:3], s[38:39], 0, v[2:3]
	v_lshl_add_u64 v[2:3], v[2:3], 0, s[14:15]
	v_lshl_add_u64 v[10:11], v[2:3], 0, v[8:9]
	ds_read_b128 v[2:5], v1
	s_mov_b32 s6, 0x8000
	v_add_co_u32_e32 v12, vcc, s6, v10
	s_mov_b32 s6, 0x10000
	s_waitcnt lgkmcnt(0)
	global_store_dwordx4 v[10:11], v[2:5], off
	ds_read_b128 v[2:5], v1 offset:1024
	v_addc_co_u32_e32 v13, vcc, 0, v11, vcc
	s_waitcnt lgkmcnt(0)
	global_store_dwordx4 v[12:13], v[2:5], off
	ds_read_b128 v[2:5], v1 offset:2048
	v_add_co_u32_e32 v12, vcc, s6, v10
	s_mov_b32 s6, 0x18000
	s_nop 0
	v_addc_co_u32_e32 v13, vcc, 0, v11, vcc
	s_waitcnt lgkmcnt(0)
	global_store_dwordx4 v[12:13], v[2:5], off
	ds_read_b128 v[2:5], v1 offset:3072
	v_add_co_u32_e32 v12, vcc, s6, v10
	s_mov_b32 s6, 0x20000
	s_nop 0
	v_addc_co_u32_e32 v13, vcc, 0, v11, vcc
	s_waitcnt lgkmcnt(0)
	global_store_dwordx4 v[12:13], v[2:5], off
	ds_read_b128 v[2:5], v1 offset:4096
	v_add_co_u32_e32 v12, vcc, s6, v10
	s_nop 1
	v_addc_co_u32_e32 v13, vcc, 0, v11, vcc
	s_waitcnt lgkmcnt(0)
	global_store_dwordx4 v[12:13], v[2:5], off
	ds_read_b128 v[2:5], v1 offset:5120
	v_add_co_u32_e32 v12, vcc, 0x28000, v10
	s_nop 1
	v_addc_co_u32_e32 v13, vcc, 0, v11, vcc
	s_waitcnt lgkmcnt(0)
	global_store_dwordx4 v[12:13], v[2:5], off
	ds_read_b128 v[2:5], v1 offset:6144
	v_add_co_u32_e32 v12, vcc, 0x30000, v10
	s_nop 1
	v_addc_co_u32_e32 v13, vcc, 0, v11, vcc
	s_waitcnt lgkmcnt(0)
	global_store_dwordx4 v[12:13], v[2:5], off
	ds_read_b128 v[2:5], v1 offset:7168
	v_add_co_u32_e32 v10, vcc, 0x38000, v10
	s_nop 1
	v_addc_co_u32_e32 v11, vcc, 0, v11, vcc
	s_waitcnt lgkmcnt(0)
	global_store_dwordx4 v[10:11], v[2:5], off

.LBB0_340:
	s_or_b64 exec, exec, s[6:7]
	v_max_i32_e32 v2, 0, v140
	v_mov_b32_e32 v3, v34
	s_lshl_b32 s8, s15, 6
	v_lshl_add_u64 v[128:129], v[2:3], 2, s[36:37]
	v_mad_u64_u32 v[2:3], s[6:7], s8, v227, v[128:129]
	s_or_b32 s6, s8, 1
	s_nop 0
	v_mad_u64_u32 v[4:5], s[6:7], s6, v227, v[128:129]
	s_or_b32 s6, s8, 2
	s_nop 0
	v_mad_u64_u32 v[14:15], s[6:7], s6, v227, v[128:129]
	s_or_b32 s6, s8, 3
	s_nop 0
	v_mad_u64_u32 v[16:17], s[6:7], s6, v227, v[128:129]
	s_or_b32 s6, s8, 4
	global_load_dwordx2 v[12:13], v[2:3], off nt
	global_load_dwordx2 v[10:11], v[4:5], off nt
	s_nop 0
	global_load_dwordx2 v[4:5], v[14:15], off nt
	global_load_dwordx2 v[2:3], v[16:17], off nt
	v_mad_u64_u32 v[14:15], s[6:7], s6, v227, v[128:129]
	s_or_b32 s6, s8, 5
	s_nop 0
	v_mad_u64_u32 v[16:17], s[6:7], s6, v227, v[128:129]
	s_or_b32 s6, s8, 6
	s_nop 0
	v_mad_u64_u32 v[18:19], s[6:7], s6, v227, v[128:129]
	s_or_b32 s6, s8, 7
	s_nop 0
	v_mad_u64_u32 v[20:21], s[6:7], s6, v227, v[128:129]
	s_or_b32 s6, s8, 8
	global_load_dwordx2 v[26:27], v[14:15], off nt
	global_load_dwordx2 v[22:23], v[16:17], off nt
	s_nop 0
	global_load_dwordx2 v[18:19], v[18:19], off nt
	s_nop 0
	global_load_dwordx2 v[14:15], v[20:21], off nt
	v_mad_u64_u32 v[16:17], s[6:7], s6, v227, v[128:129]
	s_or_b32 s6, s8, 9
	s_nop 0
	v_mad_u64_u32 v[20:21], s[6:7], s6, v227, v[128:129]
	s_or_b32 s6, s8, 10
	s_nop 0
	v_mad_u64_u32 v[30:31], s[6:7], s6, v227, v[128:129]
	s_or_b32 s6, s8, 11
	s_nop 0
	v_mad_u64_u32 v[32:33], s[6:7], s6, v227, v[128:129]
	s_or_b32 s6, s8, 12
	global_load_dwordx2 v[28:29], v[16:17], off nt
	global_load_dwordx2 v[24:25], v[20:21], off nt
	s_nop 0
	global_load_dwordx2 v[20:21], v[30:31], off nt
	global_load_dwordx2 v[16:17], v[32:33], off nt
	v_mad_u64_u32 v[30:31], s[6:7], s6, v227, v[128:129]
	s_or_b32 s6, s8, 13
	s_nop 0
	v_mad_u64_u32 v[32:33], s[6:7], s6, v227, v[128:129]
	s_or_b32 s6, s8, 14
	s_nop 0
	v_mad_u64_u32 v[36:37], s[6:7], s6, v227, v[128:129]
	s_or_b32 s6, s8, 15
	s_nop 0
	v_mad_u64_u32 v[38:39], s[6:7], s6, v227, v[128:129]
	s_or_b32 s6, s8, 16
	global_load_dwordx2 v[44:45], v[30:31], off nt
	global_load_dwordx2 v[40:41], v[32:33], off nt
	s_nop 0
	global_load_dwordx2 v[36:37], v[36:37], off nt
	s_nop 0
	global_load_dwordx2 v[30:31], v[38:39], off nt
	v_mad_u64_u32 v[32:33], s[6:7], s6, v227, v[128:129]
	s_or_b32 s6, s8, 17
	s_nop 0
	v_mad_u64_u32 v[38:39], s[6:7], s6, v227, v[128:129]
	s_or_b32 s6, s8, 18
	s_nop 0
	v_mad_u64_u32 v[48:49], s[6:7], s6, v227, v[128:129]
	s_or_b32 s6, s8, 19
	s_nop 0
	v_mad_u64_u32 v[50:51], s[6:7], s6, v227, v[128:129]
	s_or_b32 s6, s8, 20
	global_load_dwordx2 v[46:47], v[32:33], off nt
	global_load_dwordx2 v[42:43], v[38:39], off nt
	s_nop 0
	global_load_dwordx2 v[38:39], v[48:49], off nt
	global_load_dwordx2 v[32:33], v[50:51], off nt
	v_mad_u64_u32 v[48:49], s[6:7], s6, v227, v[128:129]
	s_or_b32 s6, s8, 21
	s_nop 0
	v_mad_u64_u32 v[50:51], s[6:7], s6, v227, v[128:129]
	s_or_b32 s6, s8, 22
	s_nop 0
	v_mad_u64_u32 v[52:53], s[6:7], s6, v227, v[128:129]
	s_or_b32 s6, s8, 23
	s_nop 0
	v_mad_u64_u32 v[54:55], s[6:7], s6, v227, v[128:129]
	s_or_b32 s6, s8, 24
	global_load_dwordx2 v[60:61], v[48:49], off nt
	global_load_dwordx2 v[56:57], v[50:51], off nt
	s_nop 0
	global_load_dwordx2 v[52:53], v[52:53], off nt
	s_nop 0
	global_load_dwordx2 v[48:49], v[54:55], off nt
	v_mad_u64_u32 v[50:51], s[6:7], s6, v227, v[128:129]
	s_or_b32 s6, s8, 25
	s_nop 0
	v_mad_u64_u32 v[54:55], s[6:7], s6, v227, v[128:129]
	s_or_b32 s6, s8, 26
	s_nop 0
	v_mad_u64_u32 v[64:65], s[6:7], s6, v227, v[128:129]
	s_or_b32 s6, s8, 27
	s_nop 0
	v_mad_u64_u32 v[66:67], s[6:7], s6, v227, v[128:129]
	s_or_b32 s6, s8, 28
	global_load_dwordx2 v[62:63], v[50:51], off nt
	global_load_dwordx2 v[58:59], v[54:55], off nt
	s_nop 0
	global_load_dwordx2 v[54:55], v[64:65], off nt
	global_load_dwordx2 v[50:51], v[66:67], off nt
	v_mad_u64_u32 v[64:65], s[6:7], s6, v227, v[128:129]
	s_or_b32 s6, s8, 29
	s_nop 0
	v_mad_u64_u32 v[66:67], s[6:7], s6, v227, v[128:129]
	s_or_b32 s6, s8, 30
	s_nop 0
	v_mad_u64_u32 v[68:69], s[6:7], s6, v227, v[128:129]
	s_or_b32 s6, s8, 31
	s_nop 0
	v_mad_u64_u32 v[70:71], s[6:7], s6, v227, v[128:129]
	s_or_b32 s6, s8, 32
	global_load_dwordx2 v[76:77], v[64:65], off nt
	global_load_dwordx2 v[72:73], v[66:67], off nt
	s_nop 0
	global_load_dwordx2 v[68:69], v[68:69], off nt
	s_nop 0
	global_load_dwordx2 v[64:65], v[70:71], off nt
	v_mad_u64_u32 v[66:67], s[6:7], s6, v227, v[128:129]
	s_or_b32 s6, s8, 33
	s_nop 0
	v_mad_u64_u32 v[70:71], s[6:7], s6, v227, v[128:129]
	s_or_b32 s6, s8, 34
	s_nop 0
	v_mad_u64_u32 v[80:81], s[6:7], s6, v227, v[128:129]
	s_or_b32 s6, s8, 35
	s_nop 0
	v_mad_u64_u32 v[82:83], s[6:7], s6, v227, v[128:129]
	s_or_b32 s6, s8, 36
	global_load_dwordx2 v[78:79], v[66:67], off nt
	global_load_dwordx2 v[74:75], v[70:71], off nt
	s_nop 0
	global_load_dwordx2 v[70:71], v[80:81], off nt
	global_load_dwordx2 v[66:67], v[82:83], off nt
	v_mad_u64_u32 v[80:81], s[6:7], s6, v227, v[128:129]
	s_or_b32 s6, s8, 37
	s_nop 0
	v_mad_u64_u32 v[82:83], s[6:7], s6, v227, v[128:129]
	s_or_b32 s6, s8, 38
	s_nop 0
	v_mad_u64_u32 v[84:85], s[6:7], s6, v227, v[128:129]
	s_or_b32 s6, s8, 39
	s_nop 0
	v_mad_u64_u32 v[86:87], s[6:7], s6, v227, v[128:129]
	s_or_b32 s6, s8, 40
	global_load_dwordx2 v[92:93], v[80:81], off nt
	global_load_dwordx2 v[88:89], v[82:83], off nt
	s_nop 0
	global_load_dwordx2 v[84:85], v[84:85], off nt
	s_nop 0
	global_load_dwordx2 v[80:81], v[86:87], off nt
	v_mad_u64_u32 v[82:83], s[6:7], s6, v227, v[128:129]
	s_or_b32 s6, s8, 41
	s_nop 0
	v_mad_u64_u32 v[86:87], s[6:7], s6, v227, v[128:129]
	s_or_b32 s6, s8, 42
	s_nop 0
	v_mad_u64_u32 v[96:97], s[6:7], s6, v227, v[128:129]
	s_or_b32 s6, s8, 43
	s_nop 0
	v_mad_u64_u32 v[98:99], s[6:7], s6, v227, v[128:129]
	s_or_b32 s6, s8, 44
	global_load_dwordx2 v[94:95], v[82:83], off nt
	global_load_dwordx2 v[90:91], v[86:87], off nt
	s_nop 0
	global_load_dwordx2 v[86:87], v[96:97], off nt
	global_load_dwordx2 v[82:83], v[98:99], off nt
	v_mad_u64_u32 v[96:97], s[6:7], s6, v227, v[128:129]
	s_or_b32 s6, s8, 45
	s_nop 0
	v_mad_u64_u32 v[98:99], s[6:7], s6, v227, v[128:129]
	s_or_b32 s6, s8, 46
	s_nop 0
	v_mad_u64_u32 v[100:101], s[6:7], s6, v227, v[128:129]
	s_or_b32 s6, s8, 47
	s_nop 0
	v_mad_u64_u32 v[102:103], s[6:7], s6, v227, v[128:129]
	s_or_b32 s6, s8, 48
	global_load_dwordx2 v[108:109], v[96:97], off nt
	global_load_dwordx2 v[104:105], v[98:99], off nt
	s_nop 0
	global_load_dwordx2 v[100:101], v[100:101], off nt
	s_nop 0
	global_load_dwordx2 v[96:97], v[102:103], off nt
	v_mad_u64_u32 v[98:99], s[6:7], s6, v227, v[128:129]
	s_or_b32 s6, s8, 49
	s_nop 0
	v_mad_u64_u32 v[102:103], s[6:7], s6, v227, v[128:129]
	s_or_b32 s6, s8, 50
	s_nop 0
	v_mad_u64_u32 v[112:113], s[6:7], s6, v227, v[128:129]
	s_or_b32 s6, s8, 51
	s_nop 0
	v_mad_u64_u32 v[114:115], s[6:7], s6, v227, v[128:129]
	s_or_b32 s6, s8, 52
	global_load_dwordx2 v[110:111], v[98:99], off nt
	global_load_dwordx2 v[106:107], v[102:103], off nt
	s_nop 0
	global_load_dwordx2 v[102:103], v[112:113], off nt
	global_load_dwordx2 v[98:99], v[114:115], off nt
	v_mad_u64_u32 v[112:113], s[6:7], s6, v227, v[128:129]
	s_or_b32 s6, s8, 53
	s_nop 0
	v_mad_u64_u32 v[114:115], s[6:7], s6, v227, v[128:129]
	s_or_b32 s6, s8, 54
	s_nop 0
	v_mad_u64_u32 v[116:117], s[6:7], s6, v227, v[128:129]
	s_or_b32 s6, s8, 55
	s_nop 0
	v_mad_u64_u32 v[118:119], s[6:7], s6, v227, v[128:129]
	s_or_b32 s6, s8, 56
	global_load_dwordx2 v[124:125], v[112:113], off nt
	global_load_dwordx2 v[120:121], v[114:115], off nt
	s_nop 0
	global_load_dwordx2 v[116:117], v[116:117], off nt
	s_nop 0
	global_load_dwordx2 v[112:113], v[118:119], off nt
	v_mad_u64_u32 v[114:115], s[6:7], s6, v227, v[128:129]
	s_or_b32 s6, s8, 57
	s_nop 0
	v_mad_u64_u32 v[118:119], s[6:7], s6, v227, v[128:129]
	s_or_b32 s6, s8, 58
	s_nop 0
	v_mad_u64_u32 v[130:131], s[6:7], s6, v227, v[128:129]
	s_or_b32 s6, s8, 59
	s_nop 0
	v_mad_u64_u32 v[132:133], s[6:7], s6, v227, v[128:129]
	s_or_b32 s6, s8, 60
	global_load_dwordx2 v[126:127], v[114:115], off nt
	global_load_dwordx2 v[122:123], v[118:119], off nt
	s_nop 0
	global_load_dwordx2 v[118:119], v[130:131], off nt
	global_load_dwordx2 v[114:115], v[132:133], off nt
	v_mad_u64_u32 v[130:131], s[6:7], s6, v227, v[128:129]
	s_or_b32 s6, s8, 61
	s_nop 0
	v_mad_u64_u32 v[132:133], s[6:7], s6, v227, v[128:129]
	s_or_b32 s6, s8, 62
	s_nop 0
	v_mad_u64_u32 v[142:143], s[6:7], s6, v227, v[128:129]
	s_or_b32 s6, s8, 63
	s_nop 0
	v_mad_u64_u32 v[128:129], s[6:7], s6, v227, v[128:129]
	global_load_dwordx2 v[134:135], v[130:131], off nt
	s_nop 0
	global_load_dwordx2 v[132:133], v[132:133], off nt
	s_nop 0
	global_load_dwordx2 v[130:131], v[142:143], off nt
	s_nop 0
	global_load_dwordx2 v[128:129], v[128:129], off nt
	v_cmp_gt_i32_e32 vcc, 0, v140
	s_and_saveexec_b64 s[6:7], vcc
	s_cbranch_execz .LBB0_318
	s_waitcnt vmcnt(0)
	v_mov_b32_e32 v128, 0
	v_mov_b32_e32 v129, v128
	v_mov_b32_e32 v130, v128
	v_mov_b32_e32 v131, v128
	v_mov_b32_e32 v132, v128
	v_mov_b32_e32 v133, v128
	v_mov_b32_e32 v134, v128
	v_mov_b32_e32 v135, v128
	v_mov_b32_e32 v114, v128
	v_mov_b32_e32 v115, v128
	v_mov_b32_e32 v118, v128
	v_mov_b32_e32 v119, v128
	v_mov_b32_e32 v122, v128
	v_mov_b32_e32 v123, v128
	v_mov_b32_e32 v126, v128
	v_mov_b32_e32 v127, v128
	v_mov_b32_e32 v112, v128
	v_mov_b32_e32 v113, v128
	v_mov_b32_e32 v116, v128
	v_mov_b32_e32 v117, v128
	v_mov_b32_e32 v120, v128
	v_mov_b32_e32 v121, v128
	v_mov_b32_e32 v124, v128
	v_mov_b32_e32 v125, v128
	v_mov_b32_e32 v98, v128
	v_mov_b32_e32 v99, v128
	v_mov_b32_e32 v102, v128
	v_mov_b32_e32 v103, v128
	v_mov_b32_e32 v106, v128
	v_mov_b32_e32 v107, v128
	v_mov_b32_e32 v110, v128
	v_mov_b32_e32 v111, v128
	v_mov_b32_e32 v96, v128
	v_mov_b32_e32 v97, v128
	v_mov_b32_e32 v100, v128
	v_mov_b32_e32 v101, v128
	v_mov_b32_e32 v104, v128
	v_mov_b32_e32 v105, v128
	v_mov_b32_e32 v108, v128
	v_mov_b32_e32 v109, v128
	v_mov_b32_e32 v82, v128
	v_mov_b32_e32 v83, v128
	v_mov_b32_e32 v86, v128
	v_mov_b32_e32 v87, v128
	v_mov_b32_e32 v90, v128
	v_mov_b32_e32 v91, v128
	v_mov_b32_e32 v94, v128
	v_mov_b32_e32 v95, v128
	v_mov_b32_e32 v80, v128
	v_mov_b32_e32 v81, v128
	v_mov_b32_e32 v84, v128
	v_mov_b32_e32 v85, v128
	v_mov_b32_e32 v88, v128
	v_mov_b32_e32 v89, v128
	v_mov_b32_e32 v92, v128
	v_mov_b32_e32 v93, v128
	v_mov_b32_e32 v66, v128
	v_mov_b32_e32 v67, v128
	v_mov_b32_e32 v70, v128
	v_mov_b32_e32 v71, v128
	v_mov_b32_e32 v74, v128
	v_mov_b32_e32 v75, v128
	v_mov_b32_e32 v78, v128
	v_mov_b32_e32 v79, v128
	v_mov_b32_e32 v64, v128
	v_mov_b32_e32 v65, v128
	v_mov_b32_e32 v68, v128
	v_mov_b32_e32 v69, v128
	v_mov_b32_e32 v72, v128
	v_mov_b32_e32 v73, v128
	v_mov_b32_e32 v76, v128
	v_mov_b32_e32 v77, v128
	v_mov_b32_e32 v50, v128
	v_mov_b32_e32 v51, v128
	v_mov_b32_e32 v54, v128
	v_mov_b32_e32 v55, v128
	v_mov_b32_e32 v58, v128
	v_mov_b32_e32 v59, v128
	v_mov_b32_e32 v62, v128
	v_mov_b32_e32 v63, v128
	v_mov_b32_e32 v48, v128
	v_mov_b32_e32 v49, v128
	v_mov_b32_e32 v52, v128
	v_mov_b32_e32 v53, v128
	v_mov_b32_e32 v56, v128
	v_mov_b32_e32 v57, v128
	v_mov_b32_e32 v60, v128
	v_mov_b32_e32 v61, v128
	v_mov_b32_e32 v32, v128
	v_mov_b32_e32 v33, v128
	v_mov_b32_e32 v38, v128
	v_mov_b32_e32 v39, v128
	v_mov_b32_e32 v42, v128
	v_mov_b32_e32 v43, v128
	v_mov_b32_e32 v46, v128
	v_mov_b32_e32 v47, v128
	v_mov_b32_e32 v30, v128
	v_mov_b32_e32 v31, v128
	v_mov_b32_e32 v36, v128
	v_mov_b32_e32 v37, v128
	v_mov_b32_e32 v40, v128
	v_mov_b32_e32 v41, v128
	v_mov_b32_e32 v44, v128
	v_mov_b32_e32 v45, v128
	v_mov_b32_e32 v16, v128
	v_mov_b32_e32 v17, v128
	v_mov_b32_e32 v20, v128
	v_mov_b32_e32 v21, v128
	v_mov_b32_e32 v24, v128
	v_mov_b32_e32 v25, v128
	v_mov_b32_e32 v28, v128
	v_mov_b32_e32 v29, v128
	v_mov_b32_e32 v14, v128
	v_mov_b32_e32 v15, v128
	v_mov_b32_e32 v18, v128
	v_mov_b32_e32 v19, v128
	v_mov_b32_e32 v22, v128
	v_mov_b32_e32 v23, v128
	v_mov_b32_e32 v26, v128
	v_mov_b32_e32 v27, v128
	v_mov_b32_e32 v2, v128
	v_mov_b32_e32 v3, v128
	v_mov_b32_e32 v4, v128
	v_mov_b32_e32 v5, v128
	v_mov_b32_e32 v10, v128
	v_mov_b32_e32 v11, v128
	v_mov_b32_e32 v12, v128
	v_mov_b32_e32 v13, v128
	s_branch .LBB0_318

.LBB0_1504:
	s_or_b64 exec, exec, s[0:1]
	v_readlane_b32 s4, v251, 1
	s_lshl_b32 s0, s9, 6
	v_max_i32_e32 v4, 0, v3
	v_mov_b32_e32 v5, v34
	v_readlane_b32 s5, v251, 2
	s_or_b32 s1, s0, 1
	v_cmp_gt_i32_e32 vcc, 0, v3
	v_lshl_add_u64 v[126:127], v[4:5], 2, s[4:5]
	v_mad_i64_i32 v[6:7], s[4:5], s1, v227, v[126:127]
	s_or_b32 s1, s0, 2
	v_mad_i64_i32 v[12:13], s[4:5], s1, v227, v[126:127]
	s_or_b32 s1, s0, 3
	v_mad_i64_i32 v[4:5], s[4:5], s0, v227, v[126:127]
	v_mad_i64_i32 v[14:15], s[4:5], s1, v227, v[126:127]
	s_or_b32 s1, s0, 4
	global_load_dwordx2 v[10:11], v[4:5], off nt
	global_load_dwordx2 v[8:9], v[6:7], off nt
	s_nop 0
	global_load_dwordx2 v[6:7], v[12:13], off nt
	global_load_dwordx2 v[4:5], v[14:15], off nt
	v_mad_i64_i32 v[12:13], s[4:5], s1, v227, v[126:127]
	s_or_b32 s1, s0, 5
	v_mad_i64_i32 v[14:15], s[4:5], s1, v227, v[126:127]
	s_or_b32 s1, s0, 6
	v_mad_i64_i32 v[16:17], s[4:5], s1, v227, v[126:127]
	s_or_b32 s1, s0, 7
	v_mad_i64_i32 v[18:19], s[4:5], s1, v227, v[126:127]
	s_or_b32 s1, s0, 8
	global_load_dwordx2 v[24:25], v[12:13], off nt
	global_load_dwordx2 v[20:21], v[14:15], off nt
	s_nop 0
	global_load_dwordx2 v[16:17], v[16:17], off nt
	s_nop 0
	global_load_dwordx2 v[12:13], v[18:19], off nt
	v_mad_i64_i32 v[14:15], s[4:5], s1, v227, v[126:127]
	s_or_b32 s1, s0, 9
	v_mad_i64_i32 v[18:19], s[4:5], s1, v227, v[126:127]
	s_or_b32 s1, s0, 10
	v_mad_i64_i32 v[28:29], s[4:5], s1, v227, v[126:127]
	s_or_b32 s1, s0, 11
	v_mad_i64_i32 v[30:31], s[4:5], s1, v227, v[126:127]
	s_or_b32 s1, s0, 12
	global_load_dwordx2 v[26:27], v[14:15], off nt
	global_load_dwordx2 v[22:23], v[18:19], off nt
	s_nop 0
	global_load_dwordx2 v[18:19], v[28:29], off nt
	global_load_dwordx2 v[14:15], v[30:31], off nt
	v_mad_i64_i32 v[28:29], s[4:5], s1, v227, v[126:127]
	s_or_b32 s1, s0, 13
	v_mad_i64_i32 v[30:31], s[4:5], s1, v227, v[126:127]
	s_or_b32 s1, s0, 14
	v_mad_i64_i32 v[32:33], s[4:5], s1, v227, v[126:127]
	s_or_b32 s1, s0, 15
	v_mad_i64_i32 v[36:37], s[4:5], s1, v227, v[126:127]
	s_or_b32 s1, s0, 16
	global_load_dwordx2 v[42:43], v[28:29], off nt
	global_load_dwordx2 v[38:39], v[30:31], off nt
	s_nop 0
	global_load_dwordx2 v[32:33], v[32:33], off nt
	s_nop 0
	global_load_dwordx2 v[28:29], v[36:37], off nt
	v_mad_i64_i32 v[30:31], s[4:5], s1, v227, v[126:127]
	s_or_b32 s1, s0, 17
	v_mad_i64_i32 v[36:37], s[4:5], s1, v227, v[126:127]
	s_or_b32 s1, s0, 18
	v_mad_i64_i32 v[46:47], s[4:5], s1, v227, v[126:127]
	s_or_b32 s1, s0, 19
	v_mad_i64_i32 v[48:49], s[4:5], s1, v227, v[126:127]
	s_or_b32 s1, s0, 20
	global_load_dwordx2 v[44:45], v[30:31], off nt
	global_load_dwordx2 v[40:41], v[36:37], off nt
	s_nop 0
	global_load_dwordx2 v[36:37], v[46:47], off nt
	global_load_dwordx2 v[30:31], v[48:49], off nt
	v_mad_i64_i32 v[46:47], s[4:5], s1, v227, v[126:127]
	s_or_b32 s1, s0, 21
	v_mad_i64_i32 v[48:49], s[4:5], s1, v227, v[126:127]
	s_or_b32 s1, s0, 22
	v_mad_i64_i32 v[50:51], s[4:5], s1, v227, v[126:127]
	s_or_b32 s1, s0, 23
	v_mad_i64_i32 v[52:53], s[4:5], s1, v227, v[126:127]
	s_or_b32 s1, s0, 24
	global_load_dwordx2 v[58:59], v[46:47], off nt
	global_load_dwordx2 v[54:55], v[48:49], off nt
	s_nop 0
	global_load_dwordx2 v[50:51], v[50:51], off nt
	s_nop 0
	global_load_dwordx2 v[46:47], v[52:53], off nt
	v_mad_i64_i32 v[48:49], s[4:5], s1, v227, v[126:127]
	s_or_b32 s1, s0, 25
	v_mad_i64_i32 v[52:53], s[4:5], s1, v227, v[126:127]
	s_or_b32 s1, s0, 26
	v_mad_i64_i32 v[62:63], s[4:5], s1, v227, v[126:127]
	s_or_b32 s1, s0, 27
	v_mad_i64_i32 v[64:65], s[4:5], s1, v227, v[126:127]
	s_or_b32 s1, s0, 28
	global_load_dwordx2 v[60:61], v[48:49], off nt
	global_load_dwordx2 v[56:57], v[52:53], off nt
	s_nop 0
	global_load_dwordx2 v[52:53], v[62:63], off nt
	global_load_dwordx2 v[48:49], v[64:65], off nt
	v_mad_i64_i32 v[62:63], s[4:5], s1, v227, v[126:127]
	s_or_b32 s1, s0, 29
	v_mad_i64_i32 v[64:65], s[4:5], s1, v227, v[126:127]
	s_or_b32 s1, s0, 30
	v_mad_i64_i32 v[66:67], s[4:5], s1, v227, v[126:127]
	s_or_b32 s1, s0, 31
	v_mad_i64_i32 v[68:69], s[4:5], s1, v227, v[126:127]
	s_or_b32 s1, s0, 32
	global_load_dwordx2 v[74:75], v[62:63], off nt
	global_load_dwordx2 v[70:71], v[64:65], off nt
	s_nop 0
	global_load_dwordx2 v[66:67], v[66:67], off nt
	s_nop 0
	global_load_dwordx2 v[62:63], v[68:69], off nt
	v_mad_i64_i32 v[64:65], s[4:5], s1, v227, v[126:127]
	s_or_b32 s1, s0, 33
	v_mad_i64_i32 v[68:69], s[4:5], s1, v227, v[126:127]
	s_or_b32 s1, s0, 34
	v_mad_i64_i32 v[78:79], s[4:5], s1, v227, v[126:127]
	s_or_b32 s1, s0, 35
	v_mad_i64_i32 v[80:81], s[4:5], s1, v227, v[126:127]
	s_or_b32 s1, s0, 36
	global_load_dwordx2 v[76:77], v[64:65], off nt
	global_load_dwordx2 v[72:73], v[68:69], off nt
	s_nop 0
	global_load_dwordx2 v[68:69], v[78:79], off nt
	global_load_dwordx2 v[64:65], v[80:81], off nt
	v_mad_i64_i32 v[78:79], s[4:5], s1, v227, v[126:127]
	s_or_b32 s1, s0, 37
	v_mad_i64_i32 v[80:81], s[4:5], s1, v227, v[126:127]
	s_or_b32 s1, s0, 38
	v_mad_i64_i32 v[82:83], s[4:5], s1, v227, v[126:127]
	s_or_b32 s1, s0, 39
	v_mad_i64_i32 v[84:85], s[4:5], s1, v227, v[126:127]
	s_or_b32 s1, s0, 40
	global_load_dwordx2 v[90:91], v[78:79], off nt
	global_load_dwordx2 v[86:87], v[80:81], off nt
	s_nop 0
	global_load_dwordx2 v[82:83], v[82:83], off nt
	s_nop 0
	global_load_dwordx2 v[78:79], v[84:85], off nt
	v_mad_i64_i32 v[80:81], s[4:5], s1, v227, v[126:127]
	s_or_b32 s1, s0, 41
	v_mad_i64_i32 v[84:85], s[4:5], s1, v227, v[126:127]
	s_or_b32 s1, s0, 42
	v_mad_i64_i32 v[94:95], s[4:5], s1, v227, v[126:127]
	s_or_b32 s1, s0, 43
	v_mad_i64_i32 v[96:97], s[4:5], s1, v227, v[126:127]
	s_or_b32 s1, s0, 44
	global_load_dwordx2 v[92:93], v[80:81], off nt
	global_load_dwordx2 v[88:89], v[84:85], off nt
	s_nop 0
	global_load_dwordx2 v[84:85], v[94:95], off nt
	global_load_dwordx2 v[80:81], v[96:97], off nt
	v_mad_i64_i32 v[94:95], s[4:5], s1, v227, v[126:127]
	s_or_b32 s1, s0, 45
	v_mad_i64_i32 v[96:97], s[4:5], s1, v227, v[126:127]
	s_or_b32 s1, s0, 46
	v_mad_i64_i32 v[98:99], s[4:5], s1, v227, v[126:127]
	s_or_b32 s1, s0, 47
	v_mad_i64_i32 v[100:101], s[4:5], s1, v227, v[126:127]
	s_or_b32 s1, s0, 48
	global_load_dwordx2 v[106:107], v[94:95], off nt
	global_load_dwordx2 v[102:103], v[96:97], off nt
	s_nop 0
	global_load_dwordx2 v[98:99], v[98:99], off nt
	s_nop 0
	global_load_dwordx2 v[94:95], v[100:101], off nt
	v_mad_i64_i32 v[96:97], s[4:5], s1, v227, v[126:127]
	s_or_b32 s1, s0, 49
	v_mad_i64_i32 v[100:101], s[4:5], s1, v227, v[126:127]
	s_or_b32 s1, s0, 50
	v_mad_i64_i32 v[110:111], s[4:5], s1, v227, v[126:127]
	s_or_b32 s1, s0, 51
	v_mad_i64_i32 v[112:113], s[4:5], s1, v227, v[126:127]
	s_or_b32 s1, s0, 52
	global_load_dwordx2 v[108:109], v[96:97], off nt
	global_load_dwordx2 v[104:105], v[100:101], off nt
	s_nop 0
	global_load_dwordx2 v[100:101], v[110:111], off nt
	global_load_dwordx2 v[96:97], v[112:113], off nt
	v_mad_i64_i32 v[110:111], s[4:5], s1, v227, v[126:127]
	s_or_b32 s1, s0, 53
	v_mad_i64_i32 v[112:113], s[4:5], s1, v227, v[126:127]
	s_or_b32 s1, s0, 54
	v_mad_i64_i32 v[114:115], s[4:5], s1, v227, v[126:127]
	s_or_b32 s1, s0, 55
	v_mad_i64_i32 v[116:117], s[4:5], s1, v227, v[126:127]
	s_or_b32 s1, s0, 56
	global_load_dwordx2 v[122:123], v[110:111], off nt
	global_load_dwordx2 v[118:119], v[112:113], off nt
	s_nop 0
	global_load_dwordx2 v[114:115], v[114:115], off nt
	s_nop 0
	global_load_dwordx2 v[110:111], v[116:117], off nt
	v_mad_i64_i32 v[112:113], s[4:5], s1, v227, v[126:127]
	s_or_b32 s1, s0, 57
	v_mad_i64_i32 v[116:117], s[4:5], s1, v227, v[126:127]
	s_or_b32 s1, s0, 58
	v_mad_i64_i32 v[128:129], s[4:5], s1, v227, v[126:127]
	s_or_b32 s1, s0, 59
	v_mad_i64_i32 v[130:131], s[4:5], s1, v227, v[126:127]
	s_or_b32 s1, s0, 60
	global_load_dwordx2 v[124:125], v[112:113], off nt
	global_load_dwordx2 v[120:121], v[116:117], off nt
	s_nop 0
	global_load_dwordx2 v[116:117], v[128:129], off nt
	global_load_dwordx2 v[112:113], v[130:131], off nt
	v_mad_i64_i32 v[128:129], s[4:5], s1, v227, v[126:127]
	s_or_b32 s1, s0, 61
	v_mad_i64_i32 v[130:131], s[4:5], s1, v227, v[126:127]
	s_or_b32 s1, s0, 62
	v_mad_i64_i32 v[138:139], s[4:5], s1, v227, v[126:127]
	s_or_b32 s1, s0, 63
	v_mad_i64_i32 v[126:127], s[4:5], s1, v227, v[126:127]
	global_load_dwordx2 v[132:133], v[128:129], off nt
	s_nop 0
	global_load_dwordx2 v[130:131], v[130:131], off nt
	s_nop 0
	global_load_dwordx2 v[128:129], v[138:139], off nt
	s_nop 0
	global_load_dwordx2 v[126:127], v[126:127], off nt
	s_ashr_i32 s1, s0, 31
	s_and_saveexec_b64 s[4:5], vcc
	s_cbranch_execz .LBB0_1497
	s_waitcnt vmcnt(0)
	v_mov_b32_e32 v126, 0
	v_mov_b32_e32 v127, v126
	v_mov_b32_e32 v128, v126
	v_mov_b32_e32 v129, v126
	v_mov_b32_e32 v130, v126
	v_mov_b32_e32 v131, v126
	v_mov_b32_e32 v132, v126
	v_mov_b32_e32 v133, v126
	v_mov_b32_e32 v112, v126
	v_mov_b32_e32 v113, v126
	v_mov_b32_e32 v116, v126
	v_mov_b32_e32 v117, v126
	v_mov_b32_e32 v120, v126
	v_mov_b32_e32 v121, v126
	v_mov_b32_e32 v124, v126
	v_mov_b32_e32 v125, v126
	v_mov_b32_e32 v110, v126
	v_mov_b32_e32 v111, v126
	v_mov_b32_e32 v114, v126
	v_mov_b32_e32 v115, v126
	v_mov_b32_e32 v118, v126
	v_mov_b32_e32 v119, v126
	v_mov_b32_e32 v122, v126
	v_mov_b32_e32 v123, v126
	v_mov_b32_e32 v96, v126
	v_mov_b32_e32 v97, v126
	v_mov_b32_e32 v100, v126
	v_mov_b32_e32 v101, v126
	v_mov_b32_e32 v104, v126
	v_mov_b32_e32 v105, v126
	v_mov_b32_e32 v108, v126
	v_mov_b32_e32 v109, v126
	v_mov_b32_e32 v94, v126
	v_mov_b32_e32 v95, v126
	v_mov_b32_e32 v98, v126
	v_mov_b32_e32 v99, v126
	v_mov_b32_e32 v102, v126
	v_mov_b32_e32 v103, v126
	v_mov_b32_e32 v106, v126
	v_mov_b32_e32 v107, v126
	v_mov_b32_e32 v80, v126
	v_mov_b32_e32 v81, v126
	v_mov_b32_e32 v84, v126
	v_mov_b32_e32 v85, v126
	v_mov_b32_e32 v88, v126
	v_mov_b32_e32 v89, v126
	v_mov_b32_e32 v92, v126
	v_mov_b32_e32 v93, v126
	v_mov_b32_e32 v78, v126
	v_mov_b32_e32 v79, v126
	v_mov_b32_e32 v82, v126
	v_mov_b32_e32 v83, v126
	v_mov_b32_e32 v86, v126
	v_mov_b32_e32 v87, v126
	v_mov_b32_e32 v90, v126
	v_mov_b32_e32 v91, v126
	v_mov_b32_e32 v64, v126
	v_mov_b32_e32 v65, v126
	v_mov_b32_e32 v68, v126
	v_mov_b32_e32 v69, v126
	v_mov_b32_e32 v72, v126
	v_mov_b32_e32 v73, v126
	v_mov_b32_e32 v76, v126
	v_mov_b32_e32 v77, v126
	v_mov_b32_e32 v62, v126
	v_mov_b32_e32 v63, v126
	v_mov_b32_e32 v66, v126
	v_mov_b32_e32 v67, v126
	v_mov_b32_e32 v70, v126
	v_mov_b32_e32 v71, v126
	v_mov_b32_e32 v74, v126
	v_mov_b32_e32 v75, v126
	v_mov_b32_e32 v48, v126
	v_mov_b32_e32 v49, v126
	v_mov_b32_e32 v52, v126
	v_mov_b32_e32 v53, v126
	v_mov_b32_e32 v56, v126
	v_mov_b32_e32 v57, v126
	v_mov_b32_e32 v60, v126
	v_mov_b32_e32 v61, v126
	v_mov_b32_e32 v46, v126
	v_mov_b32_e32 v47, v126
	v_mov_b32_e32 v50, v126
	v_mov_b32_e32 v51, v126
	v_mov_b32_e32 v54, v126
	v_mov_b32_e32 v55, v126
	v_mov_b32_e32 v58, v126
	v_mov_b32_e32 v59, v126
	v_mov_b32_e32 v30, v126
	v_mov_b32_e32 v31, v126
	v_mov_b32_e32 v36, v126
	v_mov_b32_e32 v37, v126
	v_mov_b32_e32 v40, v126
	v_mov_b32_e32 v41, v126
	v_mov_b32_e32 v44, v126
	v_mov_b32_e32 v45, v126
	v_mov_b32_e32 v28, v126
	v_mov_b32_e32 v29, v126
	v_mov_b32_e32 v32, v126
	v_mov_b32_e32 v33, v126
	v_mov_b32_e32 v38, v126
	v_mov_b32_e32 v39, v126
	v_mov_b32_e32 v42, v126
	v_mov_b32_e32 v43, v126
	v_mov_b32_e32 v14, v126
	v_mov_b32_e32 v15, v126
	v_mov_b32_e32 v18, v126
	v_mov_b32_e32 v19, v126
	v_mov_b32_e32 v22, v126
	v_mov_b32_e32 v23, v126
	v_mov_b32_e32 v26, v126
	v_mov_b32_e32 v27, v126
	v_mov_b32_e32 v12, v126
	v_mov_b32_e32 v13, v126
	v_mov_b32_e32 v16, v126
	v_mov_b32_e32 v17, v126
	v_mov_b32_e32 v20, v126
	v_mov_b32_e32 v21, v126
	v_mov_b32_e32 v24, v126
	v_mov_b32_e32 v25, v126
	v_mov_b32_e32 v4, v126
	v_mov_b32_e32 v5, v126
	v_mov_b32_e32 v6, v126
	v_mov_b32_e32 v7, v126
	v_mov_b32_e32 v8, v126
	v_mov_b32_e32 v9, v126
	v_mov_b32_e32 v10, v126
	v_mov_b32_e32 v11, v126
	s_branch .LBB0_1497

.LBB0_1645:
	s_add_i32 s4, s10, 0xdb80
	s_and_b32 s5, s4, 0xffff
	s_mul_i32 s5, s5, 0xaaab
	s_lshr_b32 s6, s5, 16
	s_lshr_b32 s5, s5, 23
	s_mulk_i32 s5, 0xc0
	s_sub_i32 s4, s4, s5
	v_readlane_b32 s12, v252, 15
	s_lshl_b32 s4, s4, 6
	s_and_b32 s12, s6, 0xff80
	s_and_b32 s4, s4, 0xffc0
	v_readlane_b32 s6, v251, 1
	v_readlane_b32 s13, v252, 16
	v_add_u32_e32 v2, s4, v140
	v_mov_b32_e32 v3, v34
	v_readlane_b32 s7, v251, 2
	s_mov_b32 s5, 0x1e000
	s_nop 0
	v_lshl_add_u64 v[2:3], v[2:3], 2, s[6:7]
	s_mul_i32 s6, s12, 0x1e040
	s_mov_b32 s7, s13
	v_lshl_add_u64 v[2:3], v[2:3], 0, s[6:7]
	v_add_co_u32_e32 v10, vcc, s5, v2
	s_mov_b32 s5, 0x3c000
	s_nop 0
	v_addc_co_u32_e32 v11, vcc, 0, v3, vcc
	global_load_dword v4, v[2:3], off nt
	global_load_dword v5, v[10:11], off offset:64
	v_add_co_u32_e32 v10, vcc, s5, v2
	s_mov_b32 s5, 0x5a000
	s_nop 0
	v_addc_co_u32_e32 v11, vcc, 0, v3, vcc
	global_load_dword v9, v[10:11], off offset:128
	v_add_co_u32_e32 v10, vcc, s5, v2
	s_mov_b32 s5, 0x78000
	s_nop 0
	v_addc_co_u32_e32 v11, vcc, 0, v3, vcc
	v_add_co_u32_e32 v12, vcc, s5, v2
	s_mov_b32 s5, 0x96000
	s_nop 0
	v_addc_co_u32_e32 v13, vcc, 0, v3, vcc
	global_load_dword v10, v[10:11], off offset:192
	v_readlane_b32 s6, v251, 11
	global_load_dword v11, v[12:13], off offset:256
	v_add_co_u32_e32 v12, vcc, s5, v2
	s_mov_b32 s5, 0xb4000
	s_nop 0
	v_addc_co_u32_e32 v13, vcc, 0, v3, vcc
	v_add_co_u32_e32 v14, vcc, s5, v2
	s_mov_b32 s5, 0xd2000
	s_nop 0
	v_addc_co_u32_e32 v15, vcc, 0, v3, vcc
	global_load_dword v12, v[12:13], off offset:320
	v_readlane_b32 s7, v251, 12
	global_load_dword v13, v[14:15], off offset:384
	v_add_co_u32_e32 v14, vcc, s5, v2
	s_mov_b32 s5, 0xf0000
	s_nop 0
	v_addc_co_u32_e32 v15, vcc, 0, v3, vcc
	v_add_co_u32_e32 v16, vcc, s5, v2
	s_mov_b32 s5, 0x10e000
	s_nop 0
	v_addc_co_u32_e32 v17, vcc, 0, v3, vcc
	global_load_dword v14, v[14:15], off offset:448
	s_nop 0
	global_load_dword v15, v[16:17], off offset:512
	v_add_co_u32_e32 v16, vcc, s5, v2
	s_mov_b32 s5, 0x12c000
	s_nop 0
	v_addc_co_u32_e32 v17, vcc, 0, v3, vcc
	v_add_co_u32_e32 v18, vcc, s5, v2
	s_mov_b32 s5, 0x14a000
	s_nop 0
	v_addc_co_u32_e32 v19, vcc, 0, v3, vcc
	global_load_dword v16, v[16:17], off offset:576
	s_nop 0
	global_load_dword v17, v[18:19], off offset:640
	v_add_co_u32_e32 v18, vcc, s5, v2
	s_mov_b32 s5, 0x168000
	s_nop 0
	v_addc_co_u32_e32 v19, vcc, 0, v3, vcc
	v_add_co_u32_e32 v20, vcc, s5, v2
	s_mov_b32 s5, 0x186000
	s_nop 0
	v_addc_co_u32_e32 v21, vcc, 0, v3, vcc
	global_load_dword v18, v[18:19], off offset:704
	s_nop 0
	global_load_dword v19, v[20:21], off offset:768
	v_add_co_u32_e32 v20, vcc, s5, v2
	s_mov_b32 s5, 0x1a4000
	s_nop 0
	v_addc_co_u32_e32 v21, vcc, 0, v3, vcc
	v_add_co_u32_e32 v22, vcc, s5, v2
	s_mov_b32 s5, 0x1c2000
	s_nop 0
	v_addc_co_u32_e32 v23, vcc, 0, v3, vcc
	global_load_dword v20, v[20:21], off offset:832
	s_nop 0
	global_load_dword v21, v[22:23], off offset:896
	v_add_co_u32_e32 v22, vcc, s5, v2
	s_mov_b32 s5, 0x1e0000
	s_nop 0
	v_addc_co_u32_e32 v23, vcc, 0, v3, vcc
	v_add_co_u32_e32 v24, vcc, s5, v2
	s_mov_b32 s5, 0x1fe000
	s_nop 0
	v_addc_co_u32_e32 v25, vcc, 0, v3, vcc
	global_load_dword v22, v[22:23], off offset:960
	s_nop 0
	global_load_dword v23, v[24:25], off offset:1024
	v_add_co_u32_e32 v24, vcc, s5, v2
	s_mov_b32 s5, 0x21c000
	s_nop 0
	v_addc_co_u32_e32 v25, vcc, 0, v3, vcc
	v_add_co_u32_e32 v26, vcc, s5, v2
	s_mov_b32 s5, 0x23a000
	s_nop 0
	v_addc_co_u32_e32 v27, vcc, 0, v3, vcc
	global_load_dword v24, v[24:25], off offset:1088
	s_nop 0
	global_load_dword v25, v[26:27], off offset:1152
	v_add_co_u32_e32 v26, vcc, s5, v2
	s_mov_b32 s5, 0x258000
	s_nop 0
	v_addc_co_u32_e32 v27, vcc, 0, v3, vcc
	v_add_co_u32_e32 v28, vcc, s5, v2
	s_mov_b32 s5, 0x276000
	s_nop 0
	v_addc_co_u32_e32 v29, vcc, 0, v3, vcc
	global_load_dword v26, v[26:27], off offset:1216
	s_nop 0
	global_load_dword v27, v[28:29], off offset:1280
	v_add_co_u32_e32 v28, vcc, s5, v2
	s_mov_b32 s5, 0x294000
	s_nop 0
	v_addc_co_u32_e32 v29, vcc, 0, v3, vcc
	v_add_co_u32_e32 v30, vcc, s5, v2
	s_mov_b32 s5, 0x2b2000
	s_nop 0
	v_addc_co_u32_e32 v31, vcc, 0, v3, vcc
	global_load_dword v28, v[28:29], off offset:1344
	s_nop 0
	global_load_dword v29, v[30:31], off offset:1408
	v_add_co_u32_e32 v30, vcc, s5, v2
	s_mov_b32 s5, 0x2d0000
	s_nop 0
	v_addc_co_u32_e32 v31, vcc, 0, v3, vcc
	v_add_co_u32_e32 v32, vcc, s5, v2
	s_mov_b32 s5, 0x2ee000
	s_nop 0
	v_addc_co_u32_e32 v33, vcc, 0, v3, vcc
	global_load_dword v30, v[30:31], off offset:1472
	s_nop 0
	global_load_dword v31, v[32:33], off offset:1536
	v_add_co_u32_e32 v32, vcc, s5, v2
	s_mov_b32 s5, 0x30c000
	s_nop 0
	v_addc_co_u32_e32 v33, vcc, 0, v3, vcc
	v_add_co_u32_e32 v36, vcc, s5, v2
	s_mov_b32 s5, 0x32a000
	s_nop 0
	v_addc_co_u32_e32 v37, vcc, 0, v3, vcc
	global_load_dword v32, v[32:33], off offset:1600
	s_nop 0
	global_load_dword v33, v[36:37], off offset:1664
	v_add_co_u32_e32 v36, vcc, s5, v2
	s_mov_b32 s5, 0x348000
	s_nop 0
	v_addc_co_u32_e32 v37, vcc, 0, v3, vcc
	v_add_co_u32_e32 v38, vcc, s5, v2
	s_mov_b32 s5, 0x366000
	s_nop 0
	v_addc_co_u32_e32 v39, vcc, 0, v3, vcc
	global_load_dword v36, v[36:37], off offset:1728
	s_nop 0
	global_load_dword v37, v[38:39], off offset:1792
	v_add_co_u32_e32 v38, vcc, s5, v2
	s_mov_b32 s5, 0x384000
	s_nop 0
	v_addc_co_u32_e32 v39, vcc, 0, v3, vcc
	v_add_co_u32_e32 v40, vcc, s5, v2
	s_mov_b32 s5, 0x3a2000
	s_nop 0
	v_addc_co_u32_e32 v41, vcc, 0, v3, vcc
	global_load_dword v38, v[38:39], off offset:1856
	s_nop 0
	global_load_dword v39, v[40:41], off offset:1920
	v_add_co_u32_e32 v40, vcc, s5, v2
	s_mov_b32 s5, 0x3c0000
	s_nop 0
	v_addc_co_u32_e32 v41, vcc, 0, v3, vcc
	v_add_co_u32_e32 v42, vcc, s5, v2
	s_mov_b32 s5, 0x3de000
	s_nop 0
	v_addc_co_u32_e32 v43, vcc, 0, v3, vcc
	global_load_dword v40, v[40:41], off offset:1984
	s_nop 0
	global_load_dword v41, v[42:43], off offset:2048
	v_add_co_u32_e32 v42, vcc, s5, v2
	s_mov_b32 s5, 0x3fc000
	s_nop 0
	v_addc_co_u32_e32 v43, vcc, 0, v3, vcc
	v_add_co_u32_e32 v44, vcc, s5, v2
	s_mov_b32 s5, 0x41a000
	s_nop 0
	v_addc_co_u32_e32 v45, vcc, 0, v3, vcc
	global_load_dword v42, v[42:43], off offset:2112
	s_nop 0
	global_load_dword v43, v[44:45], off offset:2176
	v_add_co_u32_e32 v44, vcc, s5, v2
	s_mov_b32 s5, 0x438000
	s_nop 0
	v_addc_co_u32_e32 v45, vcc, 0, v3, vcc
	v_add_co_u32_e32 v46, vcc, s5, v2
	s_mov_b32 s5, 0x456000
	s_nop 0
	v_addc_co_u32_e32 v47, vcc, 0, v3, vcc
	global_load_dword v44, v[44:45], off offset:2240
	s_nop 0
	global_load_dword v45, v[46:47], off offset:2304
	v_add_co_u32_e32 v46, vcc, s5, v2
	s_mov_b32 s5, 0x474000
	s_nop 0
	v_addc_co_u32_e32 v47, vcc, 0, v3, vcc
	v_add_co_u32_e32 v48, vcc, s5, v2
	s_mov_b32 s5, 0x492000
	s_nop 0
	v_addc_co_u32_e32 v49, vcc, 0, v3, vcc
	global_load_dword v46, v[46:47], off offset:2368
	s_nop 0
	global_load_dword v47, v[48:49], off offset:2432
	v_add_co_u32_e32 v48, vcc, s5, v2
	s_mov_b32 s5, 0x4b0000
	s_nop 0
	v_addc_co_u32_e32 v49, vcc, 0, v3, vcc
	v_add_co_u32_e32 v50, vcc, s5, v2
	s_mov_b32 s5, 0x4ce000
	s_nop 0
	v_addc_co_u32_e32 v51, vcc, 0, v3, vcc
	global_load_dword v48, v[48:49], off offset:2496
	s_nop 0
	global_load_dword v49, v[50:51], off offset:2560
	v_add_co_u32_e32 v50, vcc, s5, v2
	s_mov_b32 s5, 0x4ec000
	s_nop 0
	v_addc_co_u32_e32 v51, vcc, 0, v3, vcc
	v_add_co_u32_e32 v52, vcc, s5, v2
	s_mov_b32 s5, 0x50a000
	s_nop 0
	v_addc_co_u32_e32 v53, vcc, 0, v3, vcc
	global_load_dword v50, v[50:51], off offset:2624
	s_nop 0
	global_load_dword v51, v[52:53], off offset:2688
	v_add_co_u32_e32 v52, vcc, s5, v2
	s_mov_b32 s5, 0x528000
	s_nop 0
	v_addc_co_u32_e32 v53, vcc, 0, v3, vcc
	v_add_co_u32_e32 v54, vcc, s5, v2
	s_mov_b32 s5, 0x546000
	s_nop 0
	v_addc_co_u32_e32 v55, vcc, 0, v3, vcc
	global_load_dword v52, v[52:53], off offset:2752
	s_nop 0
	global_load_dword v53, v[54:55], off offset:2816
	v_add_co_u32_e32 v54, vcc, s5, v2
	s_mov_b32 s5, 0x564000
	s_nop 0
	v_addc_co_u32_e32 v55, vcc, 0, v3, vcc
	v_add_co_u32_e32 v56, vcc, s5, v2
	s_mov_b32 s5, 0x582000
	s_nop 0
	v_addc_co_u32_e32 v57, vcc, 0, v3, vcc
	global_load_dword v54, v[54:55], off offset:2880
	s_nop 0
	global_load_dword v55, v[56:57], off offset:2944
	v_add_co_u32_e32 v56, vcc, s5, v2
	s_mov_b32 s5, 0x5a0000
	s_nop 0
	v_addc_co_u32_e32 v57, vcc, 0, v3, vcc
	v_add_co_u32_e32 v58, vcc, s5, v2
	s_mov_b32 s5, 0x5be000
	s_nop 0
	v_addc_co_u32_e32 v59, vcc, 0, v3, vcc
	global_load_dword v56, v[56:57], off offset:3008
	s_nop 0
	global_load_dword v57, v[58:59], off offset:3072
	v_add_co_u32_e32 v58, vcc, s5, v2
	s_mov_b32 s5, 0x5dc000
	s_nop 0
	v_addc_co_u32_e32 v59, vcc, 0, v3, vcc
	v_add_co_u32_e32 v60, vcc, s5, v2
	s_mov_b32 s5, 0x5fa000
	s_nop 0
	v_addc_co_u32_e32 v61, vcc, 0, v3, vcc
	global_load_dword v58, v[58:59], off offset:3136
	s_nop 0
	global_load_dword v59, v[60:61], off offset:3200
	v_add_co_u32_e32 v60, vcc, s5, v2
	s_mov_b32 s5, 0x618000
	s_nop 0
	v_addc_co_u32_e32 v61, vcc, 0, v3, vcc
	v_add_co_u32_e32 v62, vcc, s5, v2
	s_mov_b32 s5, 0x636000
	s_nop 0
	v_addc_co_u32_e32 v63, vcc, 0, v3, vcc
	global_load_dword v60, v[60:61], off offset:3264
	s_nop 0
	global_load_dword v61, v[62:63], off offset:3328
	v_add_co_u32_e32 v62, vcc, s5, v2
	s_mov_b32 s5, 0x654000
	s_nop 0
	v_addc_co_u32_e32 v63, vcc, 0, v3, vcc
	v_add_co_u32_e32 v64, vcc, s5, v2
	s_mov_b32 s5, 0x672000
	s_nop 0
	v_addc_co_u32_e32 v65, vcc, 0, v3, vcc
	global_load_dword v62, v[62:63], off offset:3392
	s_nop 0
	global_load_dword v63, v[64:65], off offset:3456
	v_add_co_u32_e32 v64, vcc, s5, v2
	s_mov_b32 s5, 0x690000
	s_nop 0
	v_addc_co_u32_e32 v65, vcc, 0, v3, vcc
	v_add_co_u32_e32 v66, vcc, s5, v2
	s_mov_b32 s5, 0x6ae000
	s_nop 0
	v_addc_co_u32_e32 v67, vcc, 0, v3, vcc
	global_load_dword v64, v[64:65], off offset:3520
	s_nop 0
	global_load_dword v65, v[66:67], off offset:3584
	v_add_co_u32_e32 v66, vcc, s5, v2
	s_mov_b32 s5, 0x6cc000
	s_nop 0
	v_addc_co_u32_e32 v67, vcc, 0, v3, vcc
	v_add_co_u32_e32 v68, vcc, s5, v2
	s_mov_b32 s5, 0x6ea000
	s_nop 0
	v_addc_co_u32_e32 v69, vcc, 0, v3, vcc
	global_load_dword v66, v[66:67], off offset:3648
	s_nop 0
	global_load_dword v67, v[68:69], off offset:3712
	v_add_co_u32_e32 v68, vcc, s5, v2
	s_mov_b32 s5, 0x708000
	s_nop 0
	v_addc_co_u32_e32 v69, vcc, 0, v3, vcc
	v_add_co_u32_e32 v70, vcc, s5, v2
	s_mov_b32 s5, 0x726000
	s_nop 0
	v_addc_co_u32_e32 v71, vcc, 0, v3, vcc
	global_load_dword v68, v[68:69], off offset:3776
	s_nop 0
	global_load_dword v69, v[70:71], off offset:3840
	v_add_co_u32_e32 v70, vcc, s5, v2
	s_mov_b32 s5, 0x744000
	s_nop 0
	v_addc_co_u32_e32 v71, vcc, 0, v3, vcc
	v_add_co_u32_e32 v72, vcc, s5, v2
	s_mov_b32 s5, 0x762000
	s_nop 0
	v_addc_co_u32_e32 v73, vcc, 0, v3, vcc
	global_load_dword v70, v[70:71], off offset:3904
	s_nop 0
	global_load_dword v71, v[72:73], off offset:3968
	v_add_co_u32_e32 v72, vcc, s5, v2
	s_mov_b32 s5, 0x781000
	s_nop 0
	v_addc_co_u32_e32 v73, vcc, 0, v3, vcc
	v_add_co_u32_e32 v74, vcc, s5, v2
	s_mov_b32 s5, 0x79f000
	s_nop 0
	v_addc_co_u32_e32 v75, vcc, 0, v3, vcc
	global_load_dword v72, v[72:73], off offset:4032
	s_nop 0
	global_load_dword v73, v[74:75], off nt
	v_add_co_u32_e32 v74, vcc, s5, v2
	s_mov_b32 s5, 0x7bd000
	s_nop 0
	v_addc_co_u32_e32 v75, vcc, 0, v3, vcc
	v_add_co_u32_e32 v76, vcc, s5, v2
	s_mov_b32 s5, 0x7db000
	s_nop 0
	v_addc_co_u32_e32 v77, vcc, 0, v3, vcc
	global_load_dword v74, v[74:75], off offset:64
	s_nop 0
	global_load_dword v75, v[76:77], off offset:128
	v_add_co_u32_e32 v76, vcc, s5, v2
	s_mov_b32 s5, 0x7f9000
	s_nop 0
	v_addc_co_u32_e32 v77, vcc, 0, v3, vcc
	v_add_co_u32_e32 v78, vcc, s5, v2
	s_mov_b32 s5, 0x817000
	s_nop 0
	v_addc_co_u32_e32 v79, vcc, 0, v3, vcc
	global_load_dword v76, v[76:77], off offset:192
	s_nop 0
	global_load_dword v77, v[78:79], off offset:256
	v_add_co_u32_e32 v78, vcc, s5, v2
	s_mov_b32 s5, 0x835000
	s_nop 0
	v_addc_co_u32_e32 v79, vcc, 0, v3, vcc
	v_add_co_u32_e32 v80, vcc, s5, v2
	s_mov_b32 s5, 0x853000
	s_nop 0
	v_addc_co_u32_e32 v81, vcc, 0, v3, vcc
	global_load_dword v78, v[78:79], off offset:320
	s_nop 0
	global_load_dword v79, v[80:81], off offset:384
	v_add_co_u32_e32 v80, vcc, s5, v2
	s_mov_b32 s5, 0x871000
	s_nop 0
	v_addc_co_u32_e32 v81, vcc, 0, v3, vcc
	v_add_co_u32_e32 v82, vcc, s5, v2
	s_mov_b32 s5, 0x88f000
	s_nop 0
	v_addc_co_u32_e32 v83, vcc, 0, v3, vcc
	global_load_dword v80, v[80:81], off offset:448
	s_nop 0
	global_load_dword v81, v[82:83], off offset:512
	v_add_co_u32_e32 v82, vcc, s5, v2
	s_mov_b32 s5, 0x8ad000
	s_nop 0
	v_addc_co_u32_e32 v83, vcc, 0, v3, vcc
	v_add_co_u32_e32 v84, vcc, s5, v2
	s_mov_b32 s5, 0x8cb000
	s_nop 0
	v_addc_co_u32_e32 v85, vcc, 0, v3, vcc
	global_load_dword v82, v[82:83], off offset:576
	s_nop 0
	global_load_dword v83, v[84:85], off offset:640
	v_add_co_u32_e32 v84, vcc, s5, v2
	s_mov_b32 s5, 0x8e9000
	s_nop 0
	v_addc_co_u32_e32 v85, vcc, 0, v3, vcc
	v_add_co_u32_e32 v86, vcc, s5, v2
	s_mov_b32 s5, 0x907000
	s_nop 0
	v_addc_co_u32_e32 v87, vcc, 0, v3, vcc
	global_load_dword v84, v[84:85], off offset:704
	s_nop 0
	global_load_dword v85, v[86:87], off offset:768
	v_add_co_u32_e32 v86, vcc, s5, v2
	s_mov_b32 s5, 0x925000
	s_nop 0
	v_addc_co_u32_e32 v87, vcc, 0, v3, vcc
	v_add_co_u32_e32 v88, vcc, s5, v2
	s_mov_b32 s5, 0x943000
	s_nop 0
	v_addc_co_u32_e32 v89, vcc, 0, v3, vcc
	global_load_dword v86, v[86:87], off offset:832
	s_nop 0
	global_load_dword v87, v[88:89], off offset:896
	v_add_co_u32_e32 v88, vcc, s5, v2
	s_mov_b32 s5, 0x961000
	s_nop 0
	v_addc_co_u32_e32 v89, vcc, 0, v3, vcc
	v_add_co_u32_e32 v90, vcc, s5, v2
	s_mov_b32 s5, 0x97f000
	s_nop 0
	v_addc_co_u32_e32 v91, vcc, 0, v3, vcc
	global_load_dword v88, v[88:89], off offset:960
	s_nop 0
	global_load_dword v89, v[90:91], off offset:1024
	v_add_co_u32_e32 v90, vcc, s5, v2
	s_mov_b32 s5, 0x99d000
	s_nop 0
	v_addc_co_u32_e32 v91, vcc, 0, v3, vcc
	v_add_co_u32_e32 v92, vcc, s5, v2
	s_mov_b32 s5, 0x9bb000
	s_nop 0
	v_addc_co_u32_e32 v93, vcc, 0, v3, vcc
	global_load_dword v90, v[90:91], off offset:1088
	s_nop 0
	global_load_dword v91, v[92:93], off offset:1152
	v_add_co_u32_e32 v92, vcc, s5, v2
	s_mov_b32 s5, 0x9d9000
	s_nop 0
	v_addc_co_u32_e32 v93, vcc, 0, v3, vcc
	v_add_co_u32_e32 v94, vcc, s5, v2
	s_mov_b32 s5, 0x9f7000
	s_nop 0
	v_addc_co_u32_e32 v95, vcc, 0, v3, vcc
	global_load_dword v92, v[92:93], off offset:1216
	s_nop 0
	global_load_dword v93, v[94:95], off offset:1280
	v_add_co_u32_e32 v94, vcc, s5, v2
	s_mov_b32 s5, 0xa15000
	s_nop 0
	v_addc_co_u32_e32 v95, vcc, 0, v3, vcc
	v_add_co_u32_e32 v96, vcc, s5, v2
	s_mov_b32 s5, 0xa33000
	s_nop 0
	v_addc_co_u32_e32 v97, vcc, 0, v3, vcc
	global_load_dword v94, v[94:95], off offset:1344
	s_nop 0
	global_load_dword v95, v[96:97], off offset:1408
	v_add_co_u32_e32 v96, vcc, s5, v2
	s_mov_b32 s5, 0xa51000
	s_nop 0
	v_addc_co_u32_e32 v97, vcc, 0, v3, vcc
	v_add_co_u32_e32 v98, vcc, s5, v2
	s_mov_b32 s5, 0xa6f000
	s_nop 0
	v_addc_co_u32_e32 v99, vcc, 0, v3, vcc
	global_load_dword v96, v[96:97], off offset:1472
	s_nop 0
	global_load_dword v97, v[98:99], off offset:1536
	v_add_co_u32_e32 v98, vcc, s5, v2
	s_mov_b32 s5, 0xa8d000
	s_nop 0
	v_addc_co_u32_e32 v99, vcc, 0, v3, vcc
	v_add_co_u32_e32 v100, vcc, s5, v2
	s_mov_b32 s5, 0xaab000
	s_nop 0
	v_addc_co_u32_e32 v101, vcc, 0, v3, vcc
	global_load_dword v98, v[98:99], off offset:1600
	s_nop 0
	global_load_dword v99, v[100:101], off offset:1664
	v_add_co_u32_e32 v100, vcc, s5, v2
	s_mov_b32 s5, 0xac9000
	s_nop 0
	v_addc_co_u32_e32 v101, vcc, 0, v3, vcc
	v_add_co_u32_e32 v102, vcc, s5, v2
	s_mov_b32 s5, 0xae7000
	s_nop 0
	v_addc_co_u32_e32 v103, vcc, 0, v3, vcc
	global_load_dword v100, v[100:101], off offset:1728
	s_nop 0
	global_load_dword v101, v[102:103], off offset:1792
	v_add_co_u32_e32 v102, vcc, s5, v2
	s_mov_b32 s5, 0xb05000
	s_nop 0
	v_addc_co_u32_e32 v103, vcc, 0, v3, vcc
	v_add_co_u32_e32 v104, vcc, s5, v2
	s_mov_b32 s5, 0xb23000
	s_nop 0
	v_addc_co_u32_e32 v105, vcc, 0, v3, vcc
	global_load_dword v102, v[102:103], off offset:1856
	s_nop 0
	global_load_dword v103, v[104:105], off offset:1920
	v_add_co_u32_e32 v104, vcc, s5, v2
	s_mov_b32 s5, 0xb41000
	s_nop 0
	v_addc_co_u32_e32 v105, vcc, 0, v3, vcc
	global_load_dword v1, v[104:105], off offset:1984
	v_add_co_u32_e32 v104, vcc, s5, v2
	s_mov_b32 s5, 0xb5f000
	s_nop 0
	v_addc_co_u32_e32 v105, vcc, 0, v3, vcc
	global_load_dword v106, v[104:105], off offset:2048
	v_add_co_u32_e32 v104, vcc, s5, v2
	s_mov_b32 s5, 0xb7d000
	s_nop 0
	v_addc_co_u32_e32 v105, vcc, 0, v3, vcc
	global_load_dword v107, v[104:105], off offset:2112
	v_add_co_u32_e32 v104, vcc, s5, v2
	s_mov_b32 s5, 0xb9b000
	s_nop 0
	v_addc_co_u32_e32 v105, vcc, 0, v3, vcc
	global_load_dword v108, v[104:105], off offset:2176
	v_add_co_u32_e32 v104, vcc, s5, v2
	s_mov_b32 s5, 0xbb9000
	s_nop 0
	v_addc_co_u32_e32 v105, vcc, 0, v3, vcc
	global_load_dword v109, v[104:105], off offset:2240
	v_add_co_u32_e32 v104, vcc, s5, v2
	s_mov_b32 s5, 0xbd7000
	s_nop 0
	v_addc_co_u32_e32 v105, vcc, 0, v3, vcc
	global_load_dword v110, v[104:105], off offset:2304
	v_add_co_u32_e32 v104, vcc, s5, v2
	s_mov_b32 s5, 0xbf5000
	s_nop 0
	v_addc_co_u32_e32 v105, vcc, 0, v3, vcc
	global_load_dword v111, v[104:105], off offset:2368
	v_add_co_u32_e32 v104, vcc, s5, v2
	s_mov_b32 s5, 0xc13000
	s_nop 0
	v_addc_co_u32_e32 v105, vcc, 0, v3, vcc
	global_load_dword v112, v[104:105], off offset:2432
	v_add_co_u32_e32 v104, vcc, s5, v2
	s_mov_b32 s5, 0xc31000
	s_nop 0
	v_addc_co_u32_e32 v105, vcc, 0, v3, vcc
	global_load_dword v113, v[104:105], off offset:2496
	v_add_co_u32_e32 v104, vcc, s5, v2
	s_mov_b32 s5, 0xc4f000
	s_nop 0
	v_addc_co_u32_e32 v105, vcc, 0, v3, vcc
	global_load_dword v114, v[104:105], off offset:2560
	v_add_co_u32_e32 v104, vcc, s5, v2
	s_mov_b32 s5, 0xc6d000
	s_nop 0
	v_addc_co_u32_e32 v105, vcc, 0, v3, vcc
	global_load_dword v115, v[104:105], off offset:2624
	v_add_co_u32_e32 v104, vcc, s5, v2
	s_mov_b32 s5, 0xc8b000
	s_nop 0
	v_addc_co_u32_e32 v105, vcc, 0, v3, vcc
	global_load_dword v116, v[104:105], off offset:2688
	v_add_co_u32_e32 v104, vcc, s5, v2
	s_mov_b32 s5, 0xca9000
	s_nop 0
	v_addc_co_u32_e32 v105, vcc, 0, v3, vcc
	global_load_dword v117, v[104:105], off offset:2752
	v_add_co_u32_e32 v104, vcc, s5, v2
	s_mov_b32 s5, 0xcc7000
	s_nop 0
	v_addc_co_u32_e32 v105, vcc, 0, v3, vcc
	global_load_dword v118, v[104:105], off offset:2816
	v_add_co_u32_e32 v104, vcc, s5, v2
	s_mov_b32 s5, 0xce5000
	s_nop 0
	v_addc_co_u32_e32 v105, vcc, 0, v3, vcc
	global_load_dword v119, v[104:105], off offset:2880
	v_add_co_u32_e32 v104, vcc, s5, v2
	s_mov_b32 s5, 0xd03000
	s_nop 0
	v_addc_co_u32_e32 v105, vcc, 0, v3, vcc
	global_load_dword v120, v[104:105], off offset:2944
	v_add_co_u32_e32 v104, vcc, s5, v2
	s_mov_b32 s5, 0xd21000
	s_nop 0
	v_addc_co_u32_e32 v105, vcc, 0, v3, vcc
	global_load_dword v121, v[104:105], off offset:3008
	v_add_co_u32_e32 v104, vcc, s5, v2
	s_mov_b32 s5, 0xd3f000
	s_nop 0
	v_addc_co_u32_e32 v105, vcc, 0, v3, vcc
	global_load_dword v122, v[104:105], off offset:3072
	v_add_co_u32_e32 v104, vcc, s5, v2
	s_mov_b32 s5, 0xd5d000
	s_nop 0
	v_addc_co_u32_e32 v105, vcc, 0, v3, vcc
	global_load_dword v123, v[104:105], off offset:3136
	v_add_co_u32_e32 v104, vcc, s5, v2
	s_mov_b32 s5, 0xd7b000
	s_nop 0
	v_addc_co_u32_e32 v105, vcc, 0, v3, vcc
	global_load_dword v124, v[104:105], off offset:3200
	v_add_co_u32_e32 v104, vcc, s5, v2
	s_mov_b32 s5, 0xd99000
	s_nop 0
	v_addc_co_u32_e32 v105, vcc, 0, v3, vcc
	global_load_dword v125, v[104:105], off offset:3264
	v_add_co_u32_e32 v104, vcc, s5, v2
	s_mov_b32 s5, 0xdb7000
	s_nop 0
	v_addc_co_u32_e32 v105, vcc, 0, v3, vcc
	global_load_dword v126, v[104:105], off offset:3328
	v_add_co_u32_e32 v104, vcc, s5, v2
	s_mov_b32 s5, 0xdd5000
	s_nop 0
	v_addc_co_u32_e32 v105, vcc, 0, v3, vcc
	global_load_dword v127, v[104:105], off offset:3392
	v_add_co_u32_e32 v104, vcc, s5, v2
	s_mov_b32 s5, 0xdf3000
	s_nop 0
	v_addc_co_u32_e32 v105, vcc, 0, v3, vcc
	global_load_dword v128, v[104:105], off offset:3456
	v_add_co_u32_e32 v104, vcc, s5, v2
	s_mov_b32 s5, 0xe11000
	s_nop 0
	v_addc_co_u32_e32 v105, vcc, 0, v3, vcc
	global_load_dword v129, v[104:105], off offset:3520
	v_add_co_u32_e32 v104, vcc, s5, v2
	s_mov_b32 s5, 0xe2f000
	s_nop 0
	v_addc_co_u32_e32 v105, vcc, 0, v3, vcc
	global_load_dword v130, v[104:105], off offset:3584
	v_add_co_u32_e32 v104, vcc, s5, v2
	s_mov_b32 s5, 0xe4d000
	s_nop 0
	v_addc_co_u32_e32 v105, vcc, 0, v3, vcc
	global_load_dword v131, v[104:105], off offset:3648
	v_add_co_u32_e32 v104, vcc, s5, v2
	s_mov_b32 s5, 0xe6b000
	s_nop 0
	v_addc_co_u32_e32 v105, vcc, 0, v3, vcc
	global_load_dword v132, v[104:105], off offset:3712
	v_add_co_u32_e32 v104, vcc, s5, v2
	s_mov_b32 s5, 0xe89000
	s_nop 0
	v_addc_co_u32_e32 v105, vcc, 0, v3, vcc
	global_load_dword v133, v[104:105], off offset:3776
	v_add_co_u32_e32 v104, vcc, s5, v2
	s_mov_b32 s5, 0xea7000
	s_nop 0
	v_addc_co_u32_e32 v105, vcc, 0, v3, vcc
	global_load_dword v134, v[104:105], off offset:3840
	v_add_co_u32_e32 v104, vcc, s5, v2
	s_mov_b32 s5, 0xec5000
	s_nop 0
	v_addc_co_u32_e32 v105, vcc, 0, v3, vcc
	global_load_dword v135, v[104:105], off offset:3904
	v_add_co_u32_e32 v104, vcc, s5, v2
	s_mov_b32 s5, 0xee3000
	s_nop 0
	v_addc_co_u32_e32 v105, vcc, 0, v3, vcc
	v_add_co_u32_e32 v2, vcc, s5, v2
	global_load_dword v104, v[104:105], off offset:3968
	s_nop 0
	v_addc_co_u32_e32 v3, vcc, 0, v3, vcc
	global_load_dword v105, v[2:3], off offset:4032
	s_waitcnt vmcnt(62)
	v_mul_f32_e32 v3, 0x42800000, v4
	v_mul_f32_e32 v4, 0x42800000, v5
	v_mov_b32_e32 v2, v34
	v_cvt_pk_fp8_f32 v2, v3, v4
	v_mul_f32_e32 v5, 0x42800000, v9
	v_mul_f32_e32 v9, 0x42800000, v10
	v_mul_f32_e32 v4, 0x42800000, v11
	v_cvt_pk_fp8_f32 v2, v5, v9 op_sel:[0,0,1]
	v_mul_f32_e32 v5, 0x42800000, v12
	v_mov_b32_e32 v3, v34
	v_cvt_pk_fp8_f32 v3, v4, v5
	v_mul_f32_e32 v9, 0x42800000, v13
	v_mul_f32_e32 v10, 0x42800000, v14
	v_mul_f32_e32 v5, 0x42800000, v15
	v_cvt_pk_fp8_f32 v3, v9, v10 op_sel:[0,0,1]
	v_mul_f32_e32 v9, 0x42800000, v16
	v_mov_b32_e32 v4, v34
	v_cvt_pk_fp8_f32 v4, v5, v9
	v_mul_f32_e32 v10, 0x42800000, v17
	v_mul_f32_e32 v11, 0x42800000, v18
	v_mul_f32_e32 v9, 0x42800000, v19
	v_cvt_pk_fp8_f32 v4, v10, v11 op_sel:[0,0,1]
	v_mul_f32_e32 v10, 0x42800000, v20
	v_mov_b32_e32 v5, v34
	v_cvt_pk_fp8_f32 v5, v9, v10
	v_readfirstlane_b32 s5, v0
	v_mul_f32_e32 v11, 0x42800000, v21
	v_mul_f32_e32 v12, 0x42800000, v22
	s_lshl_b32 s5, s5, 8
	v_cvt_pk_fp8_f32 v5, v11, v12 op_sel:[0,0,1]
	s_and_b32 s5, s5, 0x7fffc000
	s_add_i32 s5, s5, 0
	v_add_u32_e32 v142, s5, v141
	ds_write_b128 v142, v[2:5]
	v_mul_f32_e32 v3, 0x42800000, v23
	v_mul_f32_e32 v4, 0x42800000, v24
	v_mov_b32_e32 v2, v34
	v_cvt_pk_fp8_f32 v2, v3, v4
	v_mul_f32_e32 v5, 0x42800000, v25
	v_mul_f32_e32 v9, 0x42800000, v26
	v_mul_f32_e32 v4, 0x42800000, v27
	v_cvt_pk_fp8_f32 v2, v5, v9 op_sel:[0,0,1]
	v_mul_f32_e32 v5, 0x42800000, v28
	v_mov_b32_e32 v3, v34
	v_cvt_pk_fp8_f32 v3, v4, v5
	v_mul_f32_e32 v9, 0x42800000, v29
	v_mul_f32_e32 v10, 0x42800000, v30
	v_mul_f32_e32 v5, 0x42800000, v31
	v_cvt_pk_fp8_f32 v3, v9, v10 op_sel:[0,0,1]
	v_mul_f32_e32 v9, 0x42800000, v32
	v_mov_b32_e32 v4, v34
	v_cvt_pk_fp8_f32 v4, v5, v9
	v_mul_f32_e32 v10, 0x42800000, v33
	v_mul_f32_e32 v11, 0x42800000, v36
	v_mul_f32_e32 v9, 0x42800000, v37
	v_cvt_pk_fp8_f32 v4, v10, v11 op_sel:[0,0,1]
	v_mul_f32_e32 v10, 0x42800000, v38
	v_mov_b32_e32 v5, v34
	v_cvt_pk_fp8_f32 v5, v9, v10
	v_mul_f32_e32 v11, 0x42800000, v39
	v_mul_f32_e32 v12, 0x42800000, v40
	v_mul_f32_e32 v9, 0x42800000, v44
	v_cvt_pk_fp8_f32 v5, v11, v12 op_sel:[0,0,1]
	v_mul_f32_e32 v10, 0x42800000, v48
	v_mul_f32_e32 v11, 0x42800000, v52
	v_mul_f32_e32 v12, 0x42800000, v56
	ds_write_b128 v142, v[2:5] offset:16
	v_mul_f32_e32 v3, 0x42800000, v41
	v_mul_f32_e32 v4, 0x42800000, v42
	v_mov_b32_e32 v2, v34
	v_cvt_pk_fp8_f32 v2, v3, v4
	v_mul_f32_e32 v5, 0x42800000, v43
	v_mul_f32_e32 v4, 0x42800000, v45
	v_mov_b32_e32 v3, v34
	v_cvt_pk_fp8_f32 v2, v5, v9 op_sel:[0,0,1]
	v_mul_f32_e32 v5, 0x42800000, v46
	v_cvt_pk_fp8_f32 v3, v4, v5
	v_mul_f32_e32 v9, 0x42800000, v47
	v_mul_f32_e32 v5, 0x42800000, v49
	v_mov_b32_e32 v4, v34
	v_cvt_pk_fp8_f32 v3, v9, v10 op_sel:[0,0,1]
	v_mul_f32_e32 v9, 0x42800000, v50
	v_cvt_pk_fp8_f32 v4, v5, v9
	v_mul_f32_e32 v10, 0x42800000, v51
	v_mul_f32_e32 v9, 0x42800000, v53
	v_mov_b32_e32 v5, v34
	v_cvt_pk_fp8_f32 v4, v10, v11 op_sel:[0,0,1]
	v_mul_f32_e32 v10, 0x42800000, v54
	v_cvt_pk_fp8_f32 v5, v9, v10
	v_mul_f32_e32 v11, 0x42800000, v55
	v_mul_f32_e32 v9, 0x42800000, v60
	v_mul_f32_e32 v10, 0x42800000, v64
	v_cvt_pk_fp8_f32 v5, v11, v12 op_sel:[0,0,1]
	v_mul_f32_e32 v11, 0x42800000, v68
	v_mul_f32_e32 v12, 0x42800000, v72
	s_waitcnt vmcnt(32)
	v_mul_f32_e32 v1, 0x42800000, v1
	ds_write_b128 v142, v[2:5] offset:32
	v_mul_f32_e32 v3, 0x42800000, v57
	v_mul_f32_e32 v4, 0x42800000, v58
	v_mov_b32_e32 v2, v34
	v_cvt_pk_fp8_f32 v2, v3, v4
	v_mul_f32_e32 v5, 0x42800000, v59
	v_mul_f32_e32 v4, 0x42800000, v61
	v_mov_b32_e32 v3, v34
	v_cvt_pk_fp8_f32 v2, v5, v9 op_sel:[0,0,1]
	v_mul_f32_e32 v5, 0x42800000, v62
	v_cvt_pk_fp8_f32 v3, v4, v5
	v_mul_f32_e32 v9, 0x42800000, v63
	v_mul_f32_e32 v5, 0x42800000, v65
	v_mov_b32_e32 v4, v34
	v_cvt_pk_fp8_f32 v3, v9, v10 op_sel:[0,0,1]
	v_mul_f32_e32 v9, 0x42800000, v66
	v_cvt_pk_fp8_f32 v4, v5, v9
	v_mul_f32_e32 v10, 0x42800000, v67
	v_mul_f32_e32 v9, 0x42800000, v69
	v_mov_b32_e32 v5, v34
	v_cvt_pk_fp8_f32 v4, v10, v11 op_sel:[0,0,1]
	v_mul_f32_e32 v10, 0x42800000, v70
	v_cvt_pk_fp8_f32 v5, v9, v10
	v_mul_f32_e32 v11, 0x42800000, v71
	v_mul_f32_e32 v9, 0x42800000, v76
	v_mul_f32_e32 v10, 0x42800000, v80
	v_cvt_pk_fp8_f32 v5, v11, v12 op_sel:[0,0,1]
	v_mul_f32_e32 v11, 0x42800000, v84
	v_mul_f32_e32 v12, 0x42800000, v88
	ds_write_b128 v142, v[2:5] offset:48
	v_mul_f32_e32 v3, 0x42800000, v73
	v_mul_f32_e32 v4, 0x42800000, v74
	v_mov_b32_e32 v2, v34
	v_cvt_pk_fp8_f32 v2, v3, v4
	v_mul_f32_e32 v5, 0x42800000, v75
	v_mul_f32_e32 v4, 0x42800000, v77
	v_mov_b32_e32 v3, v34
	v_cvt_pk_fp8_f32 v2, v5, v9 op_sel:[0,0,1]
	v_mul_f32_e32 v5, 0x42800000, v78
	v_cvt_pk_fp8_f32 v3, v4, v5
	v_mul_f32_e32 v9, 0x42800000, v79
	v_mul_f32_e32 v5, 0x42800000, v81
	v_mov_b32_e32 v4, v34
	v_cvt_pk_fp8_f32 v3, v9, v10 op_sel:[0,0,1]
	v_mul_f32_e32 v9, 0x42800000, v82
	v_cvt_pk_fp8_f32 v4, v5, v9
	v_mul_f32_e32 v10, 0x42800000, v83
	v_mul_f32_e32 v9, 0x42800000, v85
	v_mov_b32_e32 v5, v34
	v_cvt_pk_fp8_f32 v4, v10, v11 op_sel:[0,0,1]
	v_mul_f32_e32 v10, 0x42800000, v86
	v_cvt_pk_fp8_f32 v5, v9, v10
	v_mul_f32_e32 v11, 0x42800000, v87
	v_mul_f32_e32 v9, 0x42800000, v92
	v_mul_f32_e32 v10, 0x42800000, v96
	v_cvt_pk_fp8_f32 v5, v11, v12 op_sel:[0,0,1]
	v_mul_f32_e32 v11, 0x42800000, v100
	ds_write_b128 v142, v[2:5] offset:64
	v_mul_f32_e32 v3, 0x42800000, v89
	v_mul_f32_e32 v4, 0x42800000, v90
	v_mov_b32_e32 v2, v34
	v_cvt_pk_fp8_f32 v2, v3, v4
	v_mul_f32_e32 v5, 0x42800000, v91
	v_mul_f32_e32 v4, 0x42800000, v93
	v_mov_b32_e32 v3, v34
	v_cvt_pk_fp8_f32 v2, v5, v9 op_sel:[0,0,1]
	v_mul_f32_e32 v5, 0x42800000, v94
	v_cvt_pk_fp8_f32 v3, v4, v5
	v_mul_f32_e32 v9, 0x42800000, v95
	v_mul_f32_e32 v5, 0x42800000, v97
	v_mov_b32_e32 v4, v34
	v_cvt_pk_fp8_f32 v3, v9, v10 op_sel:[0,0,1]
	v_mul_f32_e32 v9, 0x42800000, v98
	v_cvt_pk_fp8_f32 v4, v5, v9
	v_mul_f32_e32 v10, 0x42800000, v99
	v_mul_f32_e32 v9, 0x42800000, v101
	v_mov_b32_e32 v5, v34
	v_cvt_pk_fp8_f32 v4, v10, v11 op_sel:[0,0,1]
	v_mul_f32_e32 v10, 0x42800000, v102
	v_cvt_pk_fp8_f32 v5, v9, v10
	v_mul_f32_e32 v11, 0x42800000, v103
	s_waitcnt vmcnt(24)
	v_mul_f32_e32 v9, 0x42800000, v113
	s_waitcnt vmcnt(20)
	v_mul_f32_e32 v10, 0x42800000, v117
	v_cvt_pk_fp8_f32 v5, v11, v1 op_sel:[0,0,1]
	v_mul_f32_e32 v1, 0x42800000, v106
	s_waitcnt vmcnt(16)
	v_mul_f32_e32 v11, 0x42800000, v121
	ds_write_b128 v142, v[2:5] offset:80
	v_mul_f32_e32 v3, 0x42800000, v107
	v_mov_b32_e32 v2, v34
	v_cvt_pk_fp8_f32 v2, v1, v3
	v_mul_f32_e32 v4, 0x42800000, v108
	v_mul_f32_e32 v5, 0x42800000, v109
	v_mul_f32_e32 v1, 0x42800000, v110
	v_cvt_pk_fp8_f32 v2, v4, v5 op_sel:[0,0,1]
	v_mul_f32_e32 v4, 0x42800000, v111
	v_mov_b32_e32 v3, v34
	v_cvt_pk_fp8_f32 v3, v1, v4
	v_mul_f32_e32 v5, 0x42800000, v112
	v_mul_f32_e32 v1, 0x42800000, v114
	v_mov_b32_e32 v4, v34
	v_cvt_pk_fp8_f32 v3, v5, v9 op_sel:[0,0,1]
	v_mul_f32_e32 v5, 0x42800000, v115
	v_cvt_pk_fp8_f32 v4, v1, v5
	v_mul_f32_e32 v9, 0x42800000, v116
	v_mul_f32_e32 v1, 0x42800000, v118
	v_mov_b32_e32 v5, v34
	v_cvt_pk_fp8_f32 v4, v9, v10 op_sel:[0,0,1]
	v_mul_f32_e32 v9, 0x42800000, v119
	v_cvt_pk_fp8_f32 v5, v1, v9
	v_mul_f32_e32 v10, 0x42800000, v120
	s_waitcnt vmcnt(15)
	v_mul_f32_e32 v1, 0x42800000, v122
	s_waitcnt vmcnt(8)
	v_mul_f32_e32 v9, 0x42800000, v129
	v_cvt_pk_fp8_f32 v5, v10, v11 op_sel:[0,0,1]
	s_waitcnt vmcnt(4)
	v_mul_f32_e32 v10, 0x42800000, v133
	s_waitcnt vmcnt(0)
	v_mul_f32_e32 v11, 0x42800000, v105
	ds_write_b128 v142, v[2:5] offset:96
	v_mul_f32_e32 v3, 0x42800000, v123
	v_mov_b32_e32 v2, v34
	v_cvt_pk_fp8_f32 v2, v1, v3
	v_mul_f32_e32 v4, 0x42800000, v124
	v_mul_f32_e32 v5, 0x42800000, v125
	v_mul_f32_e32 v1, 0x42800000, v126
	v_cvt_pk_fp8_f32 v2, v4, v5 op_sel:[0,0,1]
	v_mul_f32_e32 v4, 0x42800000, v127
	v_mov_b32_e32 v3, v34
	v_cvt_pk_fp8_f32 v3, v1, v4
	v_mul_f32_e32 v5, 0x42800000, v128
	v_mul_f32_e32 v1, 0x42800000, v130
	v_mov_b32_e32 v4, v34
	v_cvt_pk_fp8_f32 v3, v5, v9 op_sel:[0,0,1]
	v_mul_f32_e32 v5, 0x42800000, v131
	v_cvt_pk_fp8_f32 v4, v1, v5
	v_mul_f32_e32 v9, 0x42800000, v132
	v_mul_f32_e32 v1, 0x42800000, v134
	v_mov_b32_e32 v5, v34
	v_cvt_pk_fp8_f32 v4, v9, v10 op_sel:[0,0,1]
	v_mul_f32_e32 v9, 0x42800000, v135
	v_cvt_pk_fp8_f32 v5, v1, v9
	v_mul_f32_e32 v10, 0x42800000, v104
	v_add_u32_e32 v1, s5, v139
	v_cvt_pk_fp8_f32 v5, v10, v11 op_sel:[0,0,1]
	ds_write_b128 v142, v[2:5] offset:112
	v_add_u32_e32 v2, s4, v138
	v_ashrrev_i32_e32 v3, 31, v2
	v_lshlrev_b64 v[2:3], 12, v[2:3]
	v_lshl_add_u64 v[2:3], s[6:7], 0, v[2:3]
	v_lshl_add_u64 v[2:3], v[2:3], 0, s[12:13]
	v_lshl_add_u64 v[10:11], v[2:3], 0, v[6:7]
	ds_read_b128 v[2:5], v1
	s_mov_b32 s4, 0x8000
	v_add_co_u32_e32 v12, vcc, s4, v10
	s_mov_b32 s4, 0x10000
	s_waitcnt lgkmcnt(0)
	global_store_dwordx4 v[10:11], v[2:5], off
	ds_read_b128 v[2:5], v1 offset:1024
	v_addc_co_u32_e32 v13, vcc, 0, v11, vcc
	s_mov_b32 s7, s13
	v_writelane_b32 v252, s6, 15
	s_waitcnt lgkmcnt(0)
	global_store_dwordx4 v[12:13], v[2:5], off
	ds_read_b128 v[2:5], v1 offset:2048
	v_add_co_u32_e32 v12, vcc, s4, v10
	s_mov_b32 s4, 0x18000
	s_nop 0
	v_addc_co_u32_e32 v13, vcc, 0, v11, vcc
	s_waitcnt lgkmcnt(0)
	global_store_dwordx4 v[12:13], v[2:5], off
	ds_read_b128 v[2:5], v1 offset:3072
	v_add_co_u32_e32 v12, vcc, s4, v10
	s_mov_b32 s4, 0x20000
	s_nop 0
	v_addc_co_u32_e32 v13, vcc, 0, v11, vcc
	s_waitcnt lgkmcnt(0)
	global_store_dwordx4 v[12:13], v[2:5], off
	ds_read_b128 v[2:5], v1 offset:4096
	v_add_co_u32_e32 v12, vcc, s4, v10
	v_writelane_b32 v252, s7, 16
	s_nop 0
	v_addc_co_u32_e32 v13, vcc, 0, v11, vcc
	s_waitcnt lgkmcnt(0)
	global_store_dwordx4 v[12:13], v[2:5], off
	ds_read_b128 v[2:5], v1 offset:5120
	v_add_co_u32_e32 v12, vcc, 0x28000, v10
	s_nop 1
	v_addc_co_u32_e32 v13, vcc, 0, v11, vcc
	s_waitcnt lgkmcnt(0)
	global_store_dwordx4 v[12:13], v[2:5], off
	ds_read_b128 v[2:5], v1 offset:6144
	v_add_co_u32_e32 v12, vcc, 0x30000, v10
	s_nop 1
	v_addc_co_u32_e32 v13, vcc, 0, v11, vcc
	s_waitcnt lgkmcnt(0)
	global_store_dwordx4 v[12:13], v[2:5], off
	ds_read_b128 v[2:5], v1 offset:7168
	v_add_co_u32_e32 v10, vcc, 0x38000, v10
	s_nop 1
	v_addc_co_u32_e32 v11, vcc, 0, v11, vcc
	s_waitcnt lgkmcnt(0)
	global_store_dwordx4 v[10:11], v[2:5], off
	s_cbranch_execnz .LBB0_1642

.LBB0_1652:
	s_or_b64 exec, exec, s[4:5]
	v_readlane_b32 s6, v251, 1
	s_lshl_b32 s4, s12, 6
	v_max_i32_e32 v2, 0, v9
	v_mov_b32_e32 v3, v34
	v_readlane_b32 s7, v251, 2
	s_or_b32 s5, s4, 1
	v_cmp_gt_i32_e32 vcc, 0, v9
	v_lshl_add_u64 v[128:129], v[2:3], 2, s[6:7]
	v_mad_i64_i32 v[4:5], s[6:7], s5, v227, v[128:129]
	s_or_b32 s5, s4, 2
	v_mad_i64_i32 v[14:15], s[6:7], s5, v227, v[128:129]
	s_or_b32 s5, s4, 3
	v_mad_i64_i32 v[2:3], s[6:7], s4, v227, v[128:129]
	v_mad_i64_i32 v[16:17], s[6:7], s5, v227, v[128:129]
	s_or_b32 s5, s4, 4
	global_load_dwordx2 v[12:13], v[2:3], off nt
	global_load_dwordx2 v[10:11], v[4:5], off nt
	s_nop 0
	global_load_dwordx2 v[4:5], v[14:15], off nt
	global_load_dwordx2 v[2:3], v[16:17], off nt
	v_mad_i64_i32 v[14:15], s[6:7], s5, v227, v[128:129]
	s_or_b32 s5, s4, 5
	v_mad_i64_i32 v[16:17], s[6:7], s5, v227, v[128:129]
	s_or_b32 s5, s4, 6
	v_mad_i64_i32 v[18:19], s[6:7], s5, v227, v[128:129]
	s_or_b32 s5, s4, 7
	v_mad_i64_i32 v[20:21], s[6:7], s5, v227, v[128:129]
	s_or_b32 s5, s4, 8
	global_load_dwordx2 v[26:27], v[14:15], off nt
	global_load_dwordx2 v[22:23], v[16:17], off nt
	s_nop 0
	global_load_dwordx2 v[18:19], v[18:19], off nt
	s_nop 0
	global_load_dwordx2 v[14:15], v[20:21], off nt
	v_mad_i64_i32 v[16:17], s[6:7], s5, v227, v[128:129]
	s_or_b32 s5, s4, 9
	v_mad_i64_i32 v[20:21], s[6:7], s5, v227, v[128:129]
	s_or_b32 s5, s4, 10
	v_mad_i64_i32 v[30:31], s[6:7], s5, v227, v[128:129]
	s_or_b32 s5, s4, 11
	v_mad_i64_i32 v[32:33], s[6:7], s5, v227, v[128:129]
	s_or_b32 s5, s4, 12
	global_load_dwordx2 v[28:29], v[16:17], off nt
	global_load_dwordx2 v[24:25], v[20:21], off nt
	s_nop 0
	global_load_dwordx2 v[20:21], v[30:31], off nt
	global_load_dwordx2 v[16:17], v[32:33], off nt
	v_mad_i64_i32 v[30:31], s[6:7], s5, v227, v[128:129]
	s_or_b32 s5, s4, 13
	v_mad_i64_i32 v[32:33], s[6:7], s5, v227, v[128:129]
	s_or_b32 s5, s4, 14
	v_mad_i64_i32 v[36:37], s[6:7], s5, v227, v[128:129]
	s_or_b32 s5, s4, 15
	v_mad_i64_i32 v[38:39], s[6:7], s5, v227, v[128:129]
	s_or_b32 s5, s4, 16
	global_load_dwordx2 v[44:45], v[30:31], off nt
	global_load_dwordx2 v[40:41], v[32:33], off nt
	s_nop 0
	global_load_dwordx2 v[36:37], v[36:37], off nt
	s_nop 0
	global_load_dwordx2 v[30:31], v[38:39], off nt
	v_mad_i64_i32 v[32:33], s[6:7], s5, v227, v[128:129]
	s_or_b32 s5, s4, 17
	v_mad_i64_i32 v[38:39], s[6:7], s5, v227, v[128:129]
	s_or_b32 s5, s4, 18
	v_mad_i64_i32 v[48:49], s[6:7], s5, v227, v[128:129]
	s_or_b32 s5, s4, 19
	v_mad_i64_i32 v[50:51], s[6:7], s5, v227, v[128:129]
	s_or_b32 s5, s4, 20
	global_load_dwordx2 v[46:47], v[32:33], off nt
	global_load_dwordx2 v[42:43], v[38:39], off nt
	s_nop 0
	global_load_dwordx2 v[38:39], v[48:49], off nt
	global_load_dwordx2 v[32:33], v[50:51], off nt
	v_mad_i64_i32 v[48:49], s[6:7], s5, v227, v[128:129]
	s_or_b32 s5, s4, 21
	v_mad_i64_i32 v[50:51], s[6:7], s5, v227, v[128:129]
	s_or_b32 s5, s4, 22
	v_mad_i64_i32 v[52:53], s[6:7], s5, v227, v[128:129]
	s_or_b32 s5, s4, 23
	v_mad_i64_i32 v[54:55], s[6:7], s5, v227, v[128:129]
	s_or_b32 s5, s4, 24
	global_load_dwordx2 v[60:61], v[48:49], off nt
	global_load_dwordx2 v[56:57], v[50:51], off nt
	s_nop 0
	global_load_dwordx2 v[52:53], v[52:53], off nt
	s_nop 0
	global_load_dwordx2 v[48:49], v[54:55], off nt
	v_mad_i64_i32 v[50:51], s[6:7], s5, v227, v[128:129]
	s_or_b32 s5, s4, 25
	v_mad_i64_i32 v[54:55], s[6:7], s5, v227, v[128:129]
	s_or_b32 s5, s4, 26
	v_mad_i64_i32 v[64:65], s[6:7], s5, v227, v[128:129]
	s_or_b32 s5, s4, 27
	v_mad_i64_i32 v[66:67], s[6:7], s5, v227, v[128:129]
	s_or_b32 s5, s4, 28
	global_load_dwordx2 v[62:63], v[50:51], off nt
	global_load_dwordx2 v[58:59], v[54:55], off nt
	s_nop 0
	global_load_dwordx2 v[54:55], v[64:65], off nt
	global_load_dwordx2 v[50:51], v[66:67], off nt
	v_mad_i64_i32 v[64:65], s[6:7], s5, v227, v[128:129]
	s_or_b32 s5, s4, 29
	v_mad_i64_i32 v[66:67], s[6:7], s5, v227, v[128:129]
	s_or_b32 s5, s4, 30
	v_mad_i64_i32 v[68:69], s[6:7], s5, v227, v[128:129]
	s_or_b32 s5, s4, 31
	v_mad_i64_i32 v[70:71], s[6:7], s5, v227, v[128:129]
	s_or_b32 s5, s4, 32
	global_load_dwordx2 v[76:77], v[64:65], off nt
	global_load_dwordx2 v[72:73], v[66:67], off nt
	s_nop 0
	global_load_dwordx2 v[68:69], v[68:69], off nt
	s_nop 0
	global_load_dwordx2 v[64:65], v[70:71], off nt
	v_mad_i64_i32 v[66:67], s[6:7], s5, v227, v[128:129]
	s_or_b32 s5, s4, 33
	v_mad_i64_i32 v[70:71], s[6:7], s5, v227, v[128:129]
	s_or_b32 s5, s4, 34
	v_mad_i64_i32 v[80:81], s[6:7], s5, v227, v[128:129]
	s_or_b32 s5, s4, 35
	v_mad_i64_i32 v[82:83], s[6:7], s5, v227, v[128:129]
	s_or_b32 s5, s4, 36
	global_load_dwordx2 v[78:79], v[66:67], off nt
	global_load_dwordx2 v[74:75], v[70:71], off nt
	s_nop 0
	global_load_dwordx2 v[70:71], v[80:81], off nt
	global_load_dwordx2 v[66:67], v[82:83], off nt
	v_mad_i64_i32 v[80:81], s[6:7], s5, v227, v[128:129]
	s_or_b32 s5, s4, 37
	v_mad_i64_i32 v[82:83], s[6:7], s5, v227, v[128:129]
	s_or_b32 s5, s4, 38
	v_mad_i64_i32 v[84:85], s[6:7], s5, v227, v[128:129]
	s_or_b32 s5, s4, 39
	v_mad_i64_i32 v[86:87], s[6:7], s5, v227, v[128:129]
	s_or_b32 s5, s4, 40
	global_load_dwordx2 v[92:93], v[80:81], off nt
	global_load_dwordx2 v[88:89], v[82:83], off nt
	s_nop 0
	global_load_dwordx2 v[84:85], v[84:85], off nt
	s_nop 0
	global_load_dwordx2 v[80:81], v[86:87], off nt
	v_mad_i64_i32 v[82:83], s[6:7], s5, v227, v[128:129]
	s_or_b32 s5, s4, 41
	v_mad_i64_i32 v[86:87], s[6:7], s5, v227, v[128:129]
	s_or_b32 s5, s4, 42
	v_mad_i64_i32 v[96:97], s[6:7], s5, v227, v[128:129]
	s_or_b32 s5, s4, 43
	v_mad_i64_i32 v[98:99], s[6:7], s5, v227, v[128:129]
	s_or_b32 s5, s4, 44
	global_load_dwordx2 v[94:95], v[82:83], off nt
	global_load_dwordx2 v[90:91], v[86:87], off nt
	s_nop 0
	global_load_dwordx2 v[86:87], v[96:97], off nt
	global_load_dwordx2 v[82:83], v[98:99], off nt
	v_mad_i64_i32 v[96:97], s[6:7], s5, v227, v[128:129]
	s_or_b32 s5, s4, 45
	v_mad_i64_i32 v[98:99], s[6:7], s5, v227, v[128:129]
	s_or_b32 s5, s4, 46
	v_mad_i64_i32 v[100:101], s[6:7], s5, v227, v[128:129]
	s_or_b32 s5, s4, 47
	v_mad_i64_i32 v[102:103], s[6:7], s5, v227, v[128:129]
	s_or_b32 s5, s4, 48
	global_load_dwordx2 v[108:109], v[96:97], off nt
	global_load_dwordx2 v[104:105], v[98:99], off nt
	s_nop 0
	global_load_dwordx2 v[100:101], v[100:101], off nt
	s_nop 0
	global_load_dwordx2 v[96:97], v[102:103], off nt
	v_mad_i64_i32 v[98:99], s[6:7], s5, v227, v[128:129]
	s_or_b32 s5, s4, 49
	v_mad_i64_i32 v[102:103], s[6:7], s5, v227, v[128:129]
	s_or_b32 s5, s4, 50
	v_mad_i64_i32 v[112:113], s[6:7], s5, v227, v[128:129]
	s_or_b32 s5, s4, 51
	v_mad_i64_i32 v[114:115], s[6:7], s5, v227, v[128:129]
	s_or_b32 s5, s4, 52
	global_load_dwordx2 v[110:111], v[98:99], off nt
	global_load_dwordx2 v[106:107], v[102:103], off nt
	s_nop 0
	global_load_dwordx2 v[102:103], v[112:113], off nt
	global_load_dwordx2 v[98:99], v[114:115], off nt
	v_mad_i64_i32 v[112:113], s[6:7], s5, v227, v[128:129]
	s_or_b32 s5, s4, 53
	v_mad_i64_i32 v[114:115], s[6:7], s5, v227, v[128:129]
	s_or_b32 s5, s4, 54
	v_mad_i64_i32 v[116:117], s[6:7], s5, v227, v[128:129]
	s_or_b32 s5, s4, 55
	v_mad_i64_i32 v[118:119], s[6:7], s5, v227, v[128:129]
	s_or_b32 s5, s4, 56
	global_load_dwordx2 v[124:125], v[112:113], off nt
	global_load_dwordx2 v[120:121], v[114:115], off nt
	s_nop 0
	global_load_dwordx2 v[116:117], v[116:117], off nt
	s_nop 0
	global_load_dwordx2 v[112:113], v[118:119], off nt
	v_mad_i64_i32 v[114:115], s[6:7], s5, v227, v[128:129]
	s_or_b32 s5, s4, 57
	v_mad_i64_i32 v[118:119], s[6:7], s5, v227, v[128:129]
	s_or_b32 s5, s4, 58
	v_mad_i64_i32 v[130:131], s[6:7], s5, v227, v[128:129]
	s_or_b32 s5, s4, 59
	v_mad_i64_i32 v[132:133], s[6:7], s5, v227, v[128:129]
	s_or_b32 s5, s4, 60
	global_load_dwordx2 v[126:127], v[114:115], off nt
	global_load_dwordx2 v[122:123], v[118:119], off nt
	s_nop 0
	global_load_dwordx2 v[118:119], v[130:131], off nt
	global_load_dwordx2 v[114:115], v[132:133], off nt
	v_mad_i64_i32 v[130:131], s[6:7], s5, v227, v[128:129]
	s_or_b32 s5, s4, 61
	v_mad_i64_i32 v[132:133], s[6:7], s5, v227, v[128:129]
	s_or_b32 s5, s4, 62
	v_mad_i64_i32 v[142:143], s[6:7], s5, v227, v[128:129]
	s_or_b32 s5, s4, 63
	v_mad_i64_i32 v[128:129], s[6:7], s5, v227, v[128:129]
	global_load_dwordx2 v[134:135], v[130:131], off nt
	s_nop 0
	global_load_dwordx2 v[132:133], v[132:133], off nt
	s_nop 0
	global_load_dwordx2 v[130:131], v[142:143], off nt
	s_nop 0
	global_load_dwordx2 v[128:129], v[128:129], off nt
	s_ashr_i32 s5, s4, 31
	s_and_saveexec_b64 s[6:7], vcc
	s_cbranch_execz .LBB0_1641
	s_waitcnt vmcnt(0)
	v_mov_b32_e32 v128, 0
	v_mov_b32_e32 v129, v128
	v_mov_b32_e32 v130, v128
	v_mov_b32_e32 v131, v128
	v_mov_b32_e32 v132, v128
	v_mov_b32_e32 v133, v128
	v_mov_b32_e32 v134, v128
	v_mov_b32_e32 v135, v128
	v_mov_b32_e32 v114, v128
	v_mov_b32_e32 v115, v128
	v_mov_b32_e32 v118, v128
	v_mov_b32_e32 v119, v128
	v_mov_b32_e32 v122, v128
	v_mov_b32_e32 v123, v128
	v_mov_b32_e32 v126, v128
	v_mov_b32_e32 v127, v128
	v_mov_b32_e32 v112, v128
	v_mov_b32_e32 v113, v128
	v_mov_b32_e32 v116, v128
	v_mov_b32_e32 v117, v128
	v_mov_b32_e32 v120, v128
	v_mov_b32_e32 v121, v128
	v_mov_b32_e32 v124, v128
	v_mov_b32_e32 v125, v128
	v_mov_b32_e32 v98, v128
	v_mov_b32_e32 v99, v128
	v_mov_b32_e32 v102, v128
	v_mov_b32_e32 v103, v128
	v_mov_b32_e32 v106, v128
	v_mov_b32_e32 v107, v128
	v_mov_b32_e32 v110, v128
	v_mov_b32_e32 v111, v128
	v_mov_b32_e32 v96, v128
	v_mov_b32_e32 v97, v128
	v_mov_b32_e32 v100, v128
	v_mov_b32_e32 v101, v128
	v_mov_b32_e32 v104, v128
	v_mov_b32_e32 v105, v128
	v_mov_b32_e32 v108, v128
	v_mov_b32_e32 v109, v128
	v_mov_b32_e32 v82, v128
	v_mov_b32_e32 v83, v128
	v_mov_b32_e32 v86, v128
	v_mov_b32_e32 v87, v128
	v_mov_b32_e32 v90, v128
	v_mov_b32_e32 v91, v128
	v_mov_b32_e32 v94, v128
	v_mov_b32_e32 v95, v128
	v_mov_b32_e32 v80, v128
	v_mov_b32_e32 v81, v128
	v_mov_b32_e32 v84, v128
	v_mov_b32_e32 v85, v128
	v_mov_b32_e32 v88, v128
	v_mov_b32_e32 v89, v128
	v_mov_b32_e32 v92, v128
	v_mov_b32_e32 v93, v128
	v_mov_b32_e32 v66, v128
	v_mov_b32_e32 v67, v128
	v_mov_b32_e32 v70, v128
	v_mov_b32_e32 v71, v128
	v_mov_b32_e32 v74, v128
	v_mov_b32_e32 v75, v128
	v_mov_b32_e32 v78, v128
	v_mov_b32_e32 v79, v128
	v_mov_b32_e32 v64, v128
	v_mov_b32_e32 v65, v128
	v_mov_b32_e32 v68, v128
	v_mov_b32_e32 v69, v128
	v_mov_b32_e32 v72, v128
	v_mov_b32_e32 v73, v128
	v_mov_b32_e32 v76, v128
	v_mov_b32_e32 v77, v128
	v_mov_b32_e32 v50, v128
	v_mov_b32_e32 v51, v128
	v_mov_b32_e32 v54, v128
	v_mov_b32_e32 v55, v128
	v_mov_b32_e32 v58, v128
	v_mov_b32_e32 v59, v128
	v_mov_b32_e32 v62, v128
	v_mov_b32_e32 v63, v128
	v_mov_b32_e32 v48, v128
	v_mov_b32_e32 v49, v128
	v_mov_b32_e32 v52, v128
	v_mov_b32_e32 v53, v128
	v_mov_b32_e32 v56, v128
	v_mov_b32_e32 v57, v128
	v_mov_b32_e32 v60, v128
	v_mov_b32_e32 v61, v128
	v_mov_b32_e32 v32, v128
	v_mov_b32_e32 v33, v128
	v_mov_b32_e32 v38, v128
	v_mov_b32_e32 v39, v128
	v_mov_b32_e32 v42, v128
	v_mov_b32_e32 v43, v128
	v_mov_b32_e32 v46, v128
	v_mov_b32_e32 v47, v128
	v_mov_b32_e32 v30, v128
	v_mov_b32_e32 v31, v128
	v_mov_b32_e32 v36, v128
	v_mov_b32_e32 v37, v128
	v_mov_b32_e32 v40, v128
	v_mov_b32_e32 v41, v128
	v_mov_b32_e32 v44, v128
	v_mov_b32_e32 v45, v128
	v_mov_b32_e32 v16, v128
	v_mov_b32_e32 v17, v128
	v_mov_b32_e32 v20, v128
	v_mov_b32_e32 v21, v128
	v_mov_b32_e32 v24, v128
	v_mov_b32_e32 v25, v128
	v_mov_b32_e32 v28, v128
	v_mov_b32_e32 v29, v128
	v_mov_b32_e32 v14, v128
	v_mov_b32_e32 v15, v128
	v_mov_b32_e32 v18, v128
	v_mov_b32_e32 v19, v128
	v_mov_b32_e32 v22, v128
	v_mov_b32_e32 v23, v128
	v_mov_b32_e32 v26, v128
	v_mov_b32_e32 v27, v128
	v_mov_b32_e32 v2, v128
	v_mov_b32_e32 v3, v128
	v_mov_b32_e32 v4, v128
	v_mov_b32_e32 v5, v128
	v_mov_b32_e32 v10, v128
	v_mov_b32_e32 v11, v128
	v_mov_b32_e32 v12, v128
	v_mov_b32_e32 v13, v128
	s_branch .LBB0_1641

.LBB0_1661:
	s_cmpk_gt_i32 s10, 0x247f
	s_mov_b64 s[4:5], -1
	s_cbranch_scc0 .LBB0_1663
	s_add_i32 s4, s10, 0xdb80
	s_and_b32 s5, s4, 0xffff
	s_mul_i32 s5, s5, 0xaaab
	s_lshr_b32 s6, s5, 16
	s_lshr_b32 s5, s5, 23
	s_mulk_i32 s5, 0xc0
	s_sub_i32 s4, s4, s5
	v_readlane_b32 s12, v252, 15
	s_lshl_b32 s4, s4, 6
	s_and_b32 s12, s6, 0xff80
	s_and_b32 s4, s4, 0xffc0
	v_readlane_b32 s6, v251, 1
	v_readlane_b32 s13, v252, 16
	v_add_u32_e32 v2, s4, v140
	v_mov_b32_e32 v3, v34
	v_readlane_b32 s7, v251, 2
	s_mov_b32 s5, 0x1e000
	s_nop 0
	v_lshl_add_u64 v[2:3], v[2:3], 2, s[6:7]
	s_mul_i32 s6, s12, 0x1e040
	s_mov_b32 s7, s13
	v_lshl_add_u64 v[2:3], v[2:3], 0, s[6:7]
	v_add_co_u32_e32 v10, vcc, s5, v2
	s_mov_b32 s5, 0x3c000
	s_nop 0
	v_addc_co_u32_e32 v11, vcc, 0, v3, vcc
	global_load_dword v4, v[2:3], off nt
	global_load_dword v5, v[10:11], off offset:64
	v_add_co_u32_e32 v10, vcc, s5, v2
	s_mov_b32 s5, 0x5a000
	s_nop 0
	v_addc_co_u32_e32 v11, vcc, 0, v3, vcc
	global_load_dword v9, v[10:11], off offset:128
	v_add_co_u32_e32 v10, vcc, s5, v2
	s_mov_b32 s5, 0x78000
	s_nop 0
	v_addc_co_u32_e32 v11, vcc, 0, v3, vcc
	v_add_co_u32_e32 v12, vcc, s5, v2
	s_mov_b32 s5, 0x96000
	s_nop 0
	v_addc_co_u32_e32 v13, vcc, 0, v3, vcc
	global_load_dword v10, v[10:11], off offset:192
	v_readlane_b32 s6, v251, 11
	global_load_dword v11, v[12:13], off offset:256
	v_add_co_u32_e32 v12, vcc, s5, v2
	s_mov_b32 s5, 0xb4000
	s_nop 0
	v_addc_co_u32_e32 v13, vcc, 0, v3, vcc
	v_add_co_u32_e32 v14, vcc, s5, v2
	s_mov_b32 s5, 0xd2000
	s_nop 0
	v_addc_co_u32_e32 v15, vcc, 0, v3, vcc
	global_load_dword v12, v[12:13], off offset:320
	v_readlane_b32 s7, v251, 12
	global_load_dword v13, v[14:15], off offset:384
	v_add_co_u32_e32 v14, vcc, s5, v2
	s_mov_b32 s5, 0xf0000
	s_nop 0
	v_addc_co_u32_e32 v15, vcc, 0, v3, vcc
	v_add_co_u32_e32 v16, vcc, s5, v2
	s_mov_b32 s5, 0x10e000
	s_nop 0
	v_addc_co_u32_e32 v17, vcc, 0, v3, vcc
	global_load_dword v14, v[14:15], off offset:448
	s_nop 0
	global_load_dword v15, v[16:17], off offset:512
	v_add_co_u32_e32 v16, vcc, s5, v2
	s_mov_b32 s5, 0x12c000
	s_nop 0
	v_addc_co_u32_e32 v17, vcc, 0, v3, vcc
	v_add_co_u32_e32 v18, vcc, s5, v2
	s_mov_b32 s5, 0x14a000
	s_nop 0
	v_addc_co_u32_e32 v19, vcc, 0, v3, vcc
	global_load_dword v16, v[16:17], off offset:576
	s_nop 0
	global_load_dword v17, v[18:19], off offset:640
	v_add_co_u32_e32 v18, vcc, s5, v2
	s_mov_b32 s5, 0x168000
	s_nop 0
	v_addc_co_u32_e32 v19, vcc, 0, v3, vcc
	v_add_co_u32_e32 v20, vcc, s5, v2
	s_mov_b32 s5, 0x186000
	s_nop 0
	v_addc_co_u32_e32 v21, vcc, 0, v3, vcc
	global_load_dword v18, v[18:19], off offset:704
	s_nop 0
	global_load_dword v19, v[20:21], off offset:768
	v_add_co_u32_e32 v20, vcc, s5, v2
	s_mov_b32 s5, 0x1a4000
	s_nop 0
	v_addc_co_u32_e32 v21, vcc, 0, v3, vcc
	v_add_co_u32_e32 v22, vcc, s5, v2
	s_mov_b32 s5, 0x1c2000
	s_nop 0
	v_addc_co_u32_e32 v23, vcc, 0, v3, vcc
	global_load_dword v20, v[20:21], off offset:832
	s_nop 0
	global_load_dword v21, v[22:23], off offset:896
	v_add_co_u32_e32 v22, vcc, s5, v2
	s_mov_b32 s5, 0x1e0000
	s_nop 0
	v_addc_co_u32_e32 v23, vcc, 0, v3, vcc
	v_add_co_u32_e32 v24, vcc, s5, v2
	s_mov_b32 s5, 0x1fe000
	s_nop 0
	v_addc_co_u32_e32 v25, vcc, 0, v3, vcc
	global_load_dword v22, v[22:23], off offset:960
	s_nop 0
	global_load_dword v23, v[24:25], off offset:1024
	v_add_co_u32_e32 v24, vcc, s5, v2
	s_mov_b32 s5, 0x21c000
	s_nop 0
	v_addc_co_u32_e32 v25, vcc, 0, v3, vcc
	v_add_co_u32_e32 v26, vcc, s5, v2
	s_mov_b32 s5, 0x23a000
	s_nop 0
	v_addc_co_u32_e32 v27, vcc, 0, v3, vcc
	global_load_dword v24, v[24:25], off offset:1088
	s_nop 0
	global_load_dword v25, v[26:27], off offset:1152
	v_add_co_u32_e32 v26, vcc, s5, v2
	s_mov_b32 s5, 0x258000
	s_nop 0
	v_addc_co_u32_e32 v27, vcc, 0, v3, vcc
	v_add_co_u32_e32 v28, vcc, s5, v2
	s_mov_b32 s5, 0x276000
	s_nop 0
	v_addc_co_u32_e32 v29, vcc, 0, v3, vcc
	global_load_dword v26, v[26:27], off offset:1216
	s_nop 0
	global_load_dword v27, v[28:29], off offset:1280
	v_add_co_u32_e32 v28, vcc, s5, v2
	s_mov_b32 s5, 0x294000
	s_nop 0
	v_addc_co_u32_e32 v29, vcc, 0, v3, vcc
	v_add_co_u32_e32 v30, vcc, s5, v2
	s_mov_b32 s5, 0x2b2000
	s_nop 0
	v_addc_co_u32_e32 v31, vcc, 0, v3, vcc
	global_load_dword v28, v[28:29], off offset:1344
	s_nop 0
	global_load_dword v29, v[30:31], off offset:1408
	v_add_co_u32_e32 v30, vcc, s5, v2
	s_mov_b32 s5, 0x2d0000
	s_nop 0
	v_addc_co_u32_e32 v31, vcc, 0, v3, vcc
	v_add_co_u32_e32 v32, vcc, s5, v2
	s_mov_b32 s5, 0x2ee000
	s_nop 0
	v_addc_co_u32_e32 v33, vcc, 0, v3, vcc
	global_load_dword v30, v[30:31], off offset:1472
	s_nop 0
	global_load_dword v31, v[32:33], off offset:1536
	v_add_co_u32_e32 v32, vcc, s5, v2
	s_mov_b32 s5, 0x30c000
	s_nop 0
	v_addc_co_u32_e32 v33, vcc, 0, v3, vcc
	v_add_co_u32_e32 v36, vcc, s5, v2
	s_mov_b32 s5, 0x32a000
	s_nop 0
	v_addc_co_u32_e32 v37, vcc, 0, v3, vcc
	global_load_dword v32, v[32:33], off offset:1600
	s_nop 0
	global_load_dword v33, v[36:37], off offset:1664
	v_add_co_u32_e32 v36, vcc, s5, v2
	s_mov_b32 s5, 0x348000
	s_nop 0
	v_addc_co_u32_e32 v37, vcc, 0, v3, vcc
	v_add_co_u32_e32 v38, vcc, s5, v2
	s_mov_b32 s5, 0x366000
	s_nop 0
	v_addc_co_u32_e32 v39, vcc, 0, v3, vcc
	global_load_dword v36, v[36:37], off offset:1728
	s_nop 0
	global_load_dword v37, v[38:39], off offset:1792
	v_add_co_u32_e32 v38, vcc, s5, v2
	s_mov_b32 s5, 0x384000
	s_nop 0
	v_addc_co_u32_e32 v39, vcc, 0, v3, vcc
	v_add_co_u32_e32 v40, vcc, s5, v2
	s_mov_b32 s5, 0x3a2000
	s_nop 0
	v_addc_co_u32_e32 v41, vcc, 0, v3, vcc
	global_load_dword v38, v[38:39], off offset:1856
	s_nop 0
	global_load_dword v39, v[40:41], off offset:1920
	v_add_co_u32_e32 v40, vcc, s5, v2
	s_mov_b32 s5, 0x3c0000
	s_nop 0
	v_addc_co_u32_e32 v41, vcc, 0, v3, vcc
	v_add_co_u32_e32 v42, vcc, s5, v2
	s_mov_b32 s5, 0x3de000
	s_nop 0
	v_addc_co_u32_e32 v43, vcc, 0, v3, vcc
	global_load_dword v40, v[40:41], off offset:1984
	s_nop 0
	global_load_dword v41, v[42:43], off offset:2048
	v_add_co_u32_e32 v42, vcc, s5, v2
	s_mov_b32 s5, 0x3fc000
	s_nop 0
	v_addc_co_u32_e32 v43, vcc, 0, v3, vcc
	v_add_co_u32_e32 v44, vcc, s5, v2
	s_mov_b32 s5, 0x41a000
	s_nop 0
	v_addc_co_u32_e32 v45, vcc, 0, v3, vcc
	global_load_dword v42, v[42:43], off offset:2112
	s_nop 0
	global_load_dword v43, v[44:45], off offset:2176
	v_add_co_u32_e32 v44, vcc, s5, v2
	s_mov_b32 s5, 0x438000
	s_nop 0
	v_addc_co_u32_e32 v45, vcc, 0, v3, vcc
	v_add_co_u32_e32 v46, vcc, s5, v2
	s_mov_b32 s5, 0x456000
	s_nop 0
	v_addc_co_u32_e32 v47, vcc, 0, v3, vcc
	global_load_dword v44, v[44:45], off offset:2240
	s_nop 0
	global_load_dword v45, v[46:47], off offset:2304
	v_add_co_u32_e32 v46, vcc, s5, v2
	s_mov_b32 s5, 0x474000
	s_nop 0
	v_addc_co_u32_e32 v47, vcc, 0, v3, vcc
	v_add_co_u32_e32 v48, vcc, s5, v2
	s_mov_b32 s5, 0x492000
	s_nop 0
	v_addc_co_u32_e32 v49, vcc, 0, v3, vcc
	global_load_dword v46, v[46:47], off offset:2368
	s_nop 0
	global_load_dword v47, v[48:49], off offset:2432
	v_add_co_u32_e32 v48, vcc, s5, v2
	s_mov_b32 s5, 0x4b0000
	s_nop 0
	v_addc_co_u32_e32 v49, vcc, 0, v3, vcc
	v_add_co_u32_e32 v50, vcc, s5, v2
	s_mov_b32 s5, 0x4ce000
	s_nop 0
	v_addc_co_u32_e32 v51, vcc, 0, v3, vcc
	global_load_dword v48, v[48:49], off offset:2496
	s_nop 0
	global_load_dword v49, v[50:51], off offset:2560
	v_add_co_u32_e32 v50, vcc, s5, v2
	s_mov_b32 s5, 0x4ec000
	s_nop 0
	v_addc_co_u32_e32 v51, vcc, 0, v3, vcc
	v_add_co_u32_e32 v52, vcc, s5, v2
	s_mov_b32 s5, 0x50a000
	s_nop 0
	v_addc_co_u32_e32 v53, vcc, 0, v3, vcc
	global_load_dword v50, v[50:51], off offset:2624
	s_nop 0
	global_load_dword v51, v[52:53], off offset:2688
	v_add_co_u32_e32 v52, vcc, s5, v2
	s_mov_b32 s5, 0x528000
	s_nop 0
	v_addc_co_u32_e32 v53, vcc, 0, v3, vcc
	v_add_co_u32_e32 v54, vcc, s5, v2
	s_mov_b32 s5, 0x546000
	s_nop 0
	v_addc_co_u32_e32 v55, vcc, 0, v3, vcc
	global_load_dword v52, v[52:53], off offset:2752
	s_nop 0
	global_load_dword v53, v[54:55], off offset:2816
	v_add_co_u32_e32 v54, vcc, s5, v2
	s_mov_b32 s5, 0x564000
	s_nop 0
	v_addc_co_u32_e32 v55, vcc, 0, v3, vcc
	v_add_co_u32_e32 v56, vcc, s5, v2
	s_mov_b32 s5, 0x582000
	s_nop 0
	v_addc_co_u32_e32 v57, vcc, 0, v3, vcc
	global_load_dword v54, v[54:55], off offset:2880
	s_nop 0
	global_load_dword v55, v[56:57], off offset:2944
	v_add_co_u32_e32 v56, vcc, s5, v2
	s_mov_b32 s5, 0x5a0000
	s_nop 0
	v_addc_co_u32_e32 v57, vcc, 0, v3, vcc
	v_add_co_u32_e32 v58, vcc, s5, v2
	s_mov_b32 s5, 0x5be000
	s_nop 0
	v_addc_co_u32_e32 v59, vcc, 0, v3, vcc
	global_load_dword v56, v[56:57], off offset:3008
	s_nop 0
	global_load_dword v57, v[58:59], off offset:3072
	v_add_co_u32_e32 v58, vcc, s5, v2
	s_mov_b32 s5, 0x5dc000
	s_nop 0
	v_addc_co_u32_e32 v59, vcc, 0, v3, vcc
	v_add_co_u32_e32 v60, vcc, s5, v2
	s_mov_b32 s5, 0x5fa000
	s_nop 0
	v_addc_co_u32_e32 v61, vcc, 0, v3, vcc
	global_load_dword v58, v[58:59], off offset:3136
	s_nop 0
	global_load_dword v59, v[60:61], off offset:3200
	v_add_co_u32_e32 v60, vcc, s5, v2
	s_mov_b32 s5, 0x618000
	s_nop 0
	v_addc_co_u32_e32 v61, vcc, 0, v3, vcc
	v_add_co_u32_e32 v62, vcc, s5, v2
	s_mov_b32 s5, 0x636000
	s_nop 0
	v_addc_co_u32_e32 v63, vcc, 0, v3, vcc
	global_load_dword v60, v[60:61], off offset:3264
	s_nop 0
	global_load_dword v61, v[62:63], off offset:3328
	v_add_co_u32_e32 v62, vcc, s5, v2
	s_mov_b32 s5, 0x654000
	s_nop 0
	v_addc_co_u32_e32 v63, vcc, 0, v3, vcc
	v_add_co_u32_e32 v64, vcc, s5, v2
	s_mov_b32 s5, 0x672000
	s_nop 0
	v_addc_co_u32_e32 v65, vcc, 0, v3, vcc
	global_load_dword v62, v[62:63], off offset:3392
	s_nop 0
	global_load_dword v63, v[64:65], off offset:3456
	v_add_co_u32_e32 v64, vcc, s5, v2
	s_mov_b32 s5, 0x690000
	s_nop 0
	v_addc_co_u32_e32 v65, vcc, 0, v3, vcc
	v_add_co_u32_e32 v66, vcc, s5, v2
	s_mov_b32 s5, 0x6ae000
	s_nop 0
	v_addc_co_u32_e32 v67, vcc, 0, v3, vcc
	global_load_dword v64, v[64:65], off offset:3520
	s_nop 0
	global_load_dword v65, v[66:67], off offset:3584
	v_add_co_u32_e32 v66, vcc, s5, v2
	s_mov_b32 s5, 0x6cc000
	s_nop 0
	v_addc_co_u32_e32 v67, vcc, 0, v3, vcc
	v_add_co_u32_e32 v68, vcc, s5, v2
	s_mov_b32 s5, 0x6ea000
	s_nop 0
	v_addc_co_u32_e32 v69, vcc, 0, v3, vcc
	global_load_dword v66, v[66:67], off offset:3648
	s_nop 0
	global_load_dword v67, v[68:69], off offset:3712
	v_add_co_u32_e32 v68, vcc, s5, v2
	s_mov_b32 s5, 0x708000
	s_nop 0
	v_addc_co_u32_e32 v69, vcc, 0, v3, vcc
	v_add_co_u32_e32 v70, vcc, s5, v2
	s_mov_b32 s5, 0x726000
	s_nop 0
	v_addc_co_u32_e32 v71, vcc, 0, v3, vcc
	global_load_dword v68, v[68:69], off offset:3776
	s_nop 0
	global_load_dword v69, v[70:71], off offset:3840
	v_add_co_u32_e32 v70, vcc, s5, v2
	s_mov_b32 s5, 0x744000
	s_nop 0
	v_addc_co_u32_e32 v71, vcc, 0, v3, vcc
	v_add_co_u32_e32 v72, vcc, s5, v2
	s_mov_b32 s5, 0x762000
	s_nop 0
	v_addc_co_u32_e32 v73, vcc, 0, v3, vcc
	global_load_dword v70, v[70:71], off offset:3904
	s_nop 0
	global_load_dword v71, v[72:73], off offset:3968
	v_add_co_u32_e32 v72, vcc, s5, v2
	s_mov_b32 s5, 0x781000
	s_nop 0
	v_addc_co_u32_e32 v73, vcc, 0, v3, vcc
	v_add_co_u32_e32 v74, vcc, s5, v2
	s_mov_b32 s5, 0x79f000
	s_nop 0
	v_addc_co_u32_e32 v75, vcc, 0, v3, vcc
	global_load_dword v72, v[72:73], off offset:4032
	s_nop 0
	global_load_dword v73, v[74:75], off nt
	v_add_co_u32_e32 v74, vcc, s5, v2
	s_mov_b32 s5, 0x7bd000
	s_nop 0
	v_addc_co_u32_e32 v75, vcc, 0, v3, vcc
	v_add_co_u32_e32 v76, vcc, s5, v2
	s_mov_b32 s5, 0x7db000
	s_nop 0
	v_addc_co_u32_e32 v77, vcc, 0, v3, vcc
	global_load_dword v74, v[74:75], off offset:64
	s_nop 0
	global_load_dword v75, v[76:77], off offset:128
	v_add_co_u32_e32 v76, vcc, s5, v2
	s_mov_b32 s5, 0x7f9000
	s_nop 0
	v_addc_co_u32_e32 v77, vcc, 0, v3, vcc
	v_add_co_u32_e32 v78, vcc, s5, v2
	s_mov_b32 s5, 0x817000
	s_nop 0
	v_addc_co_u32_e32 v79, vcc, 0, v3, vcc
	global_load_dword v76, v[76:77], off offset:192
	s_nop 0
	global_load_dword v77, v[78:79], off offset:256
	v_add_co_u32_e32 v78, vcc, s5, v2
	s_mov_b32 s5, 0x835000
	s_nop 0
	v_addc_co_u32_e32 v79, vcc, 0, v3, vcc
	v_add_co_u32_e32 v80, vcc, s5, v2
	s_mov_b32 s5, 0x853000
	s_nop 0
	v_addc_co_u32_e32 v81, vcc, 0, v3, vcc
	global_load_dword v78, v[78:79], off offset:320
	s_nop 0
	global_load_dword v79, v[80:81], off offset:384
	v_add_co_u32_e32 v80, vcc, s5, v2
	s_mov_b32 s5, 0x871000
	s_nop 0
	v_addc_co_u32_e32 v81, vcc, 0, v3, vcc
	v_add_co_u32_e32 v82, vcc, s5, v2
	s_mov_b32 s5, 0x88f000
	s_nop 0
	v_addc_co_u32_e32 v83, vcc, 0, v3, vcc
	global_load_dword v80, v[80:81], off offset:448
	s_nop 0
	global_load_dword v81, v[82:83], off offset:512
	v_add_co_u32_e32 v82, vcc, s5, v2
	s_mov_b32 s5, 0x8ad000
	s_nop 0
	v_addc_co_u32_e32 v83, vcc, 0, v3, vcc
	v_add_co_u32_e32 v84, vcc, s5, v2
	s_mov_b32 s5, 0x8cb000
	s_nop 0
	v_addc_co_u32_e32 v85, vcc, 0, v3, vcc
	global_load_dword v82, v[82:83], off offset:576
	s_nop 0
	global_load_dword v83, v[84:85], off offset:640
	v_add_co_u32_e32 v84, vcc, s5, v2
	s_mov_b32 s5, 0x8e9000
	s_nop 0
	v_addc_co_u32_e32 v85, vcc, 0, v3, vcc
	v_add_co_u32_e32 v86, vcc, s5, v2
	s_mov_b32 s5, 0x907000
	s_nop 0
	v_addc_co_u32_e32 v87, vcc, 0, v3, vcc
	global_load_dword v84, v[84:85], off offset:704
	s_nop 0
	global_load_dword v85, v[86:87], off offset:768
	v_add_co_u32_e32 v86, vcc, s5, v2
	s_mov_b32 s5, 0x925000
	s_nop 0
	v_addc_co_u32_e32 v87, vcc, 0, v3, vcc
	v_add_co_u32_e32 v88, vcc, s5, v2
	s_mov_b32 s5, 0x943000
	s_nop 0
	v_addc_co_u32_e32 v89, vcc, 0, v3, vcc
	global_load_dword v86, v[86:87], off offset:832
	s_nop 0
	global_load_dword v87, v[88:89], off offset:896
	v_add_co_u32_e32 v88, vcc, s5, v2
	s_mov_b32 s5, 0x961000
	s_nop 0
	v_addc_co_u32_e32 v89, vcc, 0, v3, vcc
	v_add_co_u32_e32 v90, vcc, s5, v2
	s_mov_b32 s5, 0x97f000
	s_nop 0
	v_addc_co_u32_e32 v91, vcc, 0, v3, vcc
	global_load_dword v88, v[88:89], off offset:960
	s_nop 0
	global_load_dword v89, v[90:91], off offset:1024
	v_add_co_u32_e32 v90, vcc, s5, v2
	s_mov_b32 s5, 0x99d000
	s_nop 0
	v_addc_co_u32_e32 v91, vcc, 0, v3, vcc
	v_add_co_u32_e32 v92, vcc, s5, v2
	s_mov_b32 s5, 0x9bb000
	s_nop 0
	v_addc_co_u32_e32 v93, vcc, 0, v3, vcc
	global_load_dword v90, v[90:91], off offset:1088
	s_nop 0
	global_load_dword v91, v[92:93], off offset:1152
	v_add_co_u32_e32 v92, vcc, s5, v2
	s_mov_b32 s5, 0x9d9000
	s_nop 0
	v_addc_co_u32_e32 v93, vcc, 0, v3, vcc
	v_add_co_u32_e32 v94, vcc, s5, v2
	s_mov_b32 s5, 0x9f7000
	s_nop 0
	v_addc_co_u32_e32 v95, vcc, 0, v3, vcc
	global_load_dword v92, v[92:93], off offset:1216
	s_nop 0
	global_load_dword v93, v[94:95], off offset:1280
	v_add_co_u32_e32 v94, vcc, s5, v2
	s_mov_b32 s5, 0xa15000
	s_nop 0
	v_addc_co_u32_e32 v95, vcc, 0, v3, vcc
	v_add_co_u32_e32 v96, vcc, s5, v2
	s_mov_b32 s5, 0xa33000
	s_nop 0
	v_addc_co_u32_e32 v97, vcc, 0, v3, vcc
	global_load_dword v94, v[94:95], off offset:1344
	s_nop 0
	global_load_dword v95, v[96:97], off offset:1408
	v_add_co_u32_e32 v96, vcc, s5, v2
	s_mov_b32 s5, 0xa51000
	s_nop 0
	v_addc_co_u32_e32 v97, vcc, 0, v3, vcc
	v_add_co_u32_e32 v98, vcc, s5, v2
	s_mov_b32 s5, 0xa6f000
	s_nop 0
	v_addc_co_u32_e32 v99, vcc, 0, v3, vcc
	global_load_dword v96, v[96:97], off offset:1472
	s_nop 0
	global_load_dword v97, v[98:99], off offset:1536
	v_add_co_u32_e32 v98, vcc, s5, v2
	s_mov_b32 s5, 0xa8d000
	s_nop 0
	v_addc_co_u32_e32 v99, vcc, 0, v3, vcc
	v_add_co_u32_e32 v100, vcc, s5, v2
	s_mov_b32 s5, 0xaab000
	s_nop 0
	v_addc_co_u32_e32 v101, vcc, 0, v3, vcc
	global_load_dword v98, v[98:99], off offset:1600
	s_nop 0
	global_load_dword v99, v[100:101], off offset:1664
	v_add_co_u32_e32 v100, vcc, s5, v2
	s_mov_b32 s5, 0xac9000
	s_nop 0
	v_addc_co_u32_e32 v101, vcc, 0, v3, vcc
	v_add_co_u32_e32 v102, vcc, s5, v2
	s_mov_b32 s5, 0xae7000
	s_nop 0
	v_addc_co_u32_e32 v103, vcc, 0, v3, vcc
	global_load_dword v100, v[100:101], off offset:1728
	s_nop 0
	global_load_dword v101, v[102:103], off offset:1792
	v_add_co_u32_e32 v102, vcc, s5, v2
	s_mov_b32 s5, 0xb05000
	s_nop 0
	v_addc_co_u32_e32 v103, vcc, 0, v3, vcc
	v_add_co_u32_e32 v104, vcc, s5, v2
	s_mov_b32 s5, 0xb23000
	s_nop 0
	v_addc_co_u32_e32 v105, vcc, 0, v3, vcc
	global_load_dword v102, v[102:103], off offset:1856
	s_nop 0
	global_load_dword v103, v[104:105], off offset:1920
	v_add_co_u32_e32 v104, vcc, s5, v2
	s_mov_b32 s5, 0xb41000
	s_nop 0
	v_addc_co_u32_e32 v105, vcc, 0, v3, vcc
	global_load_dword v1, v[104:105], off offset:1984
	v_add_co_u32_e32 v104, vcc, s5, v2
	s_mov_b32 s5, 0xb5f000
	s_nop 0
	v_addc_co_u32_e32 v105, vcc, 0, v3, vcc
	global_load_dword v106, v[104:105], off offset:2048
	v_add_co_u32_e32 v104, vcc, s5, v2
	s_mov_b32 s5, 0xb7d000
	s_nop 0
	v_addc_co_u32_e32 v105, vcc, 0, v3, vcc
	global_load_dword v107, v[104:105], off offset:2112
	v_add_co_u32_e32 v104, vcc, s5, v2
	s_mov_b32 s5, 0xb9b000
	s_nop 0
	v_addc_co_u32_e32 v105, vcc, 0, v3, vcc
	global_load_dword v108, v[104:105], off offset:2176
	v_add_co_u32_e32 v104, vcc, s5, v2
	s_mov_b32 s5, 0xbb9000
	s_nop 0
	v_addc_co_u32_e32 v105, vcc, 0, v3, vcc
	global_load_dword v109, v[104:105], off offset:2240
	v_add_co_u32_e32 v104, vcc, s5, v2
	s_mov_b32 s5, 0xbd7000
	s_nop 0
	v_addc_co_u32_e32 v105, vcc, 0, v3, vcc
	global_load_dword v110, v[104:105], off offset:2304
	v_add_co_u32_e32 v104, vcc, s5, v2
	s_mov_b32 s5, 0xbf5000
	s_nop 0
	v_addc_co_u32_e32 v105, vcc, 0, v3, vcc
	global_load_dword v111, v[104:105], off offset:2368
	v_add_co_u32_e32 v104, vcc, s5, v2
	s_mov_b32 s5, 0xc13000
	s_nop 0
	v_addc_co_u32_e32 v105, vcc, 0, v3, vcc
	global_load_dword v112, v[104:105], off offset:2432
	v_add_co_u32_e32 v104, vcc, s5, v2
	s_mov_b32 s5, 0xc31000
	s_nop 0
	v_addc_co_u32_e32 v105, vcc, 0, v3, vcc
	global_load_dword v113, v[104:105], off offset:2496
	v_add_co_u32_e32 v104, vcc, s5, v2
	s_mov_b32 s5, 0xc4f000
	s_nop 0
	v_addc_co_u32_e32 v105, vcc, 0, v3, vcc
	global_load_dword v114, v[104:105], off offset:2560
	v_add_co_u32_e32 v104, vcc, s5, v2
	s_mov_b32 s5, 0xc6d000
	s_nop 0
	v_addc_co_u32_e32 v105, vcc, 0, v3, vcc
	global_load_dword v115, v[104:105], off offset:2624
	v_add_co_u32_e32 v104, vcc, s5, v2
	s_mov_b32 s5, 0xc8b000
	s_nop 0
	v_addc_co_u32_e32 v105, vcc, 0, v3, vcc
	global_load_dword v116, v[104:105], off offset:2688
	v_add_co_u32_e32 v104, vcc, s5, v2
	s_mov_b32 s5, 0xca9000
	s_nop 0
	v_addc_co_u32_e32 v105, vcc, 0, v3, vcc
	global_load_dword v117, v[104:105], off offset:2752
	v_add_co_u32_e32 v104, vcc, s5, v2
	s_mov_b32 s5, 0xcc7000
	s_nop 0
	v_addc_co_u32_e32 v105, vcc, 0, v3, vcc
	global_load_dword v118, v[104:105], off offset:2816
	v_add_co_u32_e32 v104, vcc, s5, v2
	s_mov_b32 s5, 0xce5000
	s_nop 0
	v_addc_co_u32_e32 v105, vcc, 0, v3, vcc
	global_load_dword v119, v[104:105], off offset:2880
	v_add_co_u32_e32 v104, vcc, s5, v2
	s_mov_b32 s5, 0xd03000
	s_nop 0
	v_addc_co_u32_e32 v105, vcc, 0, v3, vcc
	global_load_dword v120, v[104:105], off offset:2944
	v_add_co_u32_e32 v104, vcc, s5, v2
	s_mov_b32 s5, 0xd21000
	s_nop 0
	v_addc_co_u32_e32 v105, vcc, 0, v3, vcc
	global_load_dword v121, v[104:105], off offset:3008
	v_add_co_u32_e32 v104, vcc, s5, v2
	s_mov_b32 s5, 0xd3f000
	s_nop 0
	v_addc_co_u32_e32 v105, vcc, 0, v3, vcc
	global_load_dword v122, v[104:105], off offset:3072
	v_add_co_u32_e32 v104, vcc, s5, v2
	s_mov_b32 s5, 0xd5d000
	s_nop 0
	v_addc_co_u32_e32 v105, vcc, 0, v3, vcc
	global_load_dword v123, v[104:105], off offset:3136
	v_add_co_u32_e32 v104, vcc, s5, v2
	s_mov_b32 s5, 0xd7b000
	s_nop 0
	v_addc_co_u32_e32 v105, vcc, 0, v3, vcc
	global_load_dword v124, v[104:105], off offset:3200
	v_add_co_u32_e32 v104, vcc, s5, v2
	s_mov_b32 s5, 0xd99000
	s_nop 0
	v_addc_co_u32_e32 v105, vcc, 0, v3, vcc
	global_load_dword v125, v[104:105], off offset:3264
	v_add_co_u32_e32 v104, vcc, s5, v2
	s_mov_b32 s5, 0xdb7000
	s_nop 0
	v_addc_co_u32_e32 v105, vcc, 0, v3, vcc
	global_load_dword v126, v[104:105], off offset:3328
	v_add_co_u32_e32 v104, vcc, s5, v2
	s_mov_b32 s5, 0xdd5000
	s_nop 0
	v_addc_co_u32_e32 v105, vcc, 0, v3, vcc
	global_load_dword v127, v[104:105], off offset:3392
	v_add_co_u32_e32 v104, vcc, s5, v2
	s_mov_b32 s5, 0xdf3000
	s_nop 0
	v_addc_co_u32_e32 v105, vcc, 0, v3, vcc
	global_load_dword v128, v[104:105], off offset:3456
	v_add_co_u32_e32 v104, vcc, s5, v2
	s_mov_b32 s5, 0xe11000
	s_nop 0
	v_addc_co_u32_e32 v105, vcc, 0, v3, vcc
	global_load_dword v129, v[104:105], off offset:3520
	v_add_co_u32_e32 v104, vcc, s5, v2
	s_mov_b32 s5, 0xe2f000
	s_nop 0
	v_addc_co_u32_e32 v105, vcc, 0, v3, vcc
	global_load_dword v130, v[104:105], off offset:3584
	v_add_co_u32_e32 v104, vcc, s5, v2
	s_mov_b32 s5, 0xe4d000
	s_nop 0
	v_addc_co_u32_e32 v105, vcc, 0, v3, vcc
	global_load_dword v131, v[104:105], off offset:3648
	v_add_co_u32_e32 v104, vcc, s5, v2
	s_mov_b32 s5, 0xe6b000
	s_nop 0
	v_addc_co_u32_e32 v105, vcc, 0, v3, vcc
	global_load_dword v132, v[104:105], off offset:3712
	v_add_co_u32_e32 v104, vcc, s5, v2
	s_mov_b32 s5, 0xe89000
	s_nop 0
	v_addc_co_u32_e32 v105, vcc, 0, v3, vcc
	global_load_dword v133, v[104:105], off offset:3776
	v_add_co_u32_e32 v104, vcc, s5, v2
	s_mov_b32 s5, 0xea7000
	s_nop 0
	v_addc_co_u32_e32 v105, vcc, 0, v3, vcc
	global_load_dword v134, v[104:105], off offset:3840
	v_add_co_u32_e32 v104, vcc, s5, v2
	s_mov_b32 s5, 0xec5000
	s_nop 0
	v_addc_co_u32_e32 v105, vcc, 0, v3, vcc
	global_load_dword v135, v[104:105], off offset:3904
	v_add_co_u32_e32 v104, vcc, s5, v2
	s_mov_b32 s5, 0xee3000
	s_nop 0
	v_addc_co_u32_e32 v105, vcc, 0, v3, vcc
	v_add_co_u32_e32 v2, vcc, s5, v2
	global_load_dword v104, v[104:105], off offset:3968
	s_nop 0
	v_addc_co_u32_e32 v3, vcc, 0, v3, vcc
	global_load_dword v105, v[2:3], off offset:4032
	s_waitcnt vmcnt(62)
	v_mul_f32_e32 v3, 0x42800000, v4
	v_mul_f32_e32 v4, 0x42800000, v5
	v_mov_b32_e32 v2, v34
	v_cvt_pk_fp8_f32 v2, v3, v4
	v_mul_f32_e32 v5, 0x42800000, v9
	v_mul_f32_e32 v9, 0x42800000, v10
	v_mul_f32_e32 v4, 0x42800000, v11
	v_cvt_pk_fp8_f32 v2, v5, v9 op_sel:[0,0,1]
	v_mul_f32_e32 v5, 0x42800000, v12
	v_mov_b32_e32 v3, v34
	v_cvt_pk_fp8_f32 v3, v4, v5
	v_mul_f32_e32 v9, 0x42800000, v13
	v_mul_f32_e32 v10, 0x42800000, v14
	v_mul_f32_e32 v5, 0x42800000, v15
	v_cvt_pk_fp8_f32 v3, v9, v10 op_sel:[0,0,1]
	v_mul_f32_e32 v9, 0x42800000, v16
	v_mov_b32_e32 v4, v34
	v_cvt_pk_fp8_f32 v4, v5, v9
	v_mul_f32_e32 v10, 0x42800000, v17
	v_mul_f32_e32 v11, 0x42800000, v18
	v_mul_f32_e32 v9, 0x42800000, v19
	v_cvt_pk_fp8_f32 v4, v10, v11 op_sel:[0,0,1]
	v_mul_f32_e32 v10, 0x42800000, v20
	v_mov_b32_e32 v5, v34
	v_cvt_pk_fp8_f32 v5, v9, v10
	v_readfirstlane_b32 s5, v0
	v_mul_f32_e32 v11, 0x42800000, v21
	v_mul_f32_e32 v12, 0x42800000, v22
	s_lshl_b32 s5, s5, 8
	v_cvt_pk_fp8_f32 v5, v11, v12 op_sel:[0,0,1]
	s_and_b32 s5, s5, 0x7fffc000
	s_add_i32 s5, s5, 0
	v_add_u32_e32 v141, s5, v35
	ds_write_b128 v141, v[2:5]
	v_mul_f32_e32 v3, 0x42800000, v23
	v_mul_f32_e32 v4, 0x42800000, v24
	v_mov_b32_e32 v2, v34
	v_cvt_pk_fp8_f32 v2, v3, v4
	v_mul_f32_e32 v5, 0x42800000, v25
	v_mul_f32_e32 v9, 0x42800000, v26
	v_mul_f32_e32 v4, 0x42800000, v27
	v_cvt_pk_fp8_f32 v2, v5, v9 op_sel:[0,0,1]
	v_mul_f32_e32 v5, 0x42800000, v28
	v_mov_b32_e32 v3, v34
	v_cvt_pk_fp8_f32 v3, v4, v5
	v_mul_f32_e32 v9, 0x42800000, v29
	v_mul_f32_e32 v10, 0x42800000, v30
	v_mul_f32_e32 v5, 0x42800000, v31
	v_cvt_pk_fp8_f32 v3, v9, v10 op_sel:[0,0,1]
	v_mul_f32_e32 v9, 0x42800000, v32
	v_mov_b32_e32 v4, v34
	v_cvt_pk_fp8_f32 v4, v5, v9
	v_mul_f32_e32 v10, 0x42800000, v33
	v_mul_f32_e32 v11, 0x42800000, v36
	v_mul_f32_e32 v9, 0x42800000, v37
	v_cvt_pk_fp8_f32 v4, v10, v11 op_sel:[0,0,1]
	v_mul_f32_e32 v10, 0x42800000, v38
	v_mov_b32_e32 v5, v34
	v_cvt_pk_fp8_f32 v5, v9, v10
	v_mul_f32_e32 v11, 0x42800000, v39
	v_mul_f32_e32 v12, 0x42800000, v40
	v_mul_f32_e32 v9, 0x42800000, v44
	v_cvt_pk_fp8_f32 v5, v11, v12 op_sel:[0,0,1]
	v_mul_f32_e32 v10, 0x42800000, v48
	v_mul_f32_e32 v11, 0x42800000, v52
	v_mul_f32_e32 v12, 0x42800000, v56
	ds_write_b128 v141, v[2:5] offset:16
	v_mul_f32_e32 v3, 0x42800000, v41
	v_mul_f32_e32 v4, 0x42800000, v42
	v_mov_b32_e32 v2, v34
	v_cvt_pk_fp8_f32 v2, v3, v4
	v_mul_f32_e32 v5, 0x42800000, v43
	v_mul_f32_e32 v4, 0x42800000, v45
	v_mov_b32_e32 v3, v34
	v_cvt_pk_fp8_f32 v2, v5, v9 op_sel:[0,0,1]
	v_mul_f32_e32 v5, 0x42800000, v46
	v_cvt_pk_fp8_f32 v3, v4, v5
	v_mul_f32_e32 v9, 0x42800000, v47
	v_mul_f32_e32 v5, 0x42800000, v49
	v_mov_b32_e32 v4, v34
	v_cvt_pk_fp8_f32 v3, v9, v10 op_sel:[0,0,1]
	v_mul_f32_e32 v9, 0x42800000, v50
	v_cvt_pk_fp8_f32 v4, v5, v9
	v_mul_f32_e32 v10, 0x42800000, v51
	v_mul_f32_e32 v9, 0x42800000, v53
	v_mov_b32_e32 v5, v34
	v_cvt_pk_fp8_f32 v4, v10, v11 op_sel:[0,0,1]
	v_mul_f32_e32 v10, 0x42800000, v54
	v_cvt_pk_fp8_f32 v5, v9, v10
	v_mul_f32_e32 v11, 0x42800000, v55
	v_mul_f32_e32 v9, 0x42800000, v60
	v_mul_f32_e32 v10, 0x42800000, v64
	v_cvt_pk_fp8_f32 v5, v11, v12 op_sel:[0,0,1]
	v_mul_f32_e32 v11, 0x42800000, v68
	v_mul_f32_e32 v12, 0x42800000, v72
	s_waitcnt vmcnt(32)
	v_mul_f32_e32 v1, 0x42800000, v1
	ds_write_b128 v141, v[2:5] offset:32
	v_mul_f32_e32 v3, 0x42800000, v57
	v_mul_f32_e32 v4, 0x42800000, v58
	v_mov_b32_e32 v2, v34
	v_cvt_pk_fp8_f32 v2, v3, v4
	v_mul_f32_e32 v5, 0x42800000, v59
	v_mul_f32_e32 v4, 0x42800000, v61
	v_mov_b32_e32 v3, v34
	v_cvt_pk_fp8_f32 v2, v5, v9 op_sel:[0,0,1]
	v_mul_f32_e32 v5, 0x42800000, v62
	v_cvt_pk_fp8_f32 v3, v4, v5
	v_mul_f32_e32 v9, 0x42800000, v63
	v_mul_f32_e32 v5, 0x42800000, v65
	v_mov_b32_e32 v4, v34
	v_cvt_pk_fp8_f32 v3, v9, v10 op_sel:[0,0,1]
	v_mul_f32_e32 v9, 0x42800000, v66
	v_cvt_pk_fp8_f32 v4, v5, v9
	v_mul_f32_e32 v10, 0x42800000, v67
	v_mul_f32_e32 v9, 0x42800000, v69
	v_mov_b32_e32 v5, v34
	v_cvt_pk_fp8_f32 v4, v10, v11 op_sel:[0,0,1]
	v_mul_f32_e32 v10, 0x42800000, v70
	v_cvt_pk_fp8_f32 v5, v9, v10
	v_mul_f32_e32 v11, 0x42800000, v71
	v_mul_f32_e32 v9, 0x42800000, v76
	v_mul_f32_e32 v10, 0x42800000, v80
	v_cvt_pk_fp8_f32 v5, v11, v12 op_sel:[0,0,1]
	v_mul_f32_e32 v11, 0x42800000, v84
	v_mul_f32_e32 v12, 0x42800000, v88
	ds_write_b128 v141, v[2:5] offset:48
	v_mul_f32_e32 v3, 0x42800000, v73
	v_mul_f32_e32 v4, 0x42800000, v74
	v_mov_b32_e32 v2, v34
	v_cvt_pk_fp8_f32 v2, v3, v4
	v_mul_f32_e32 v5, 0x42800000, v75
	v_mul_f32_e32 v4, 0x42800000, v77
	v_mov_b32_e32 v3, v34
	v_cvt_pk_fp8_f32 v2, v5, v9 op_sel:[0,0,1]
	v_mul_f32_e32 v5, 0x42800000, v78
	v_cvt_pk_fp8_f32 v3, v4, v5
	v_mul_f32_e32 v9, 0x42800000, v79
	v_mul_f32_e32 v5, 0x42800000, v81
	v_mov_b32_e32 v4, v34
	v_cvt_pk_fp8_f32 v3, v9, v10 op_sel:[0,0,1]
	v_mul_f32_e32 v9, 0x42800000, v82
	v_cvt_pk_fp8_f32 v4, v5, v9
	v_mul_f32_e32 v10, 0x42800000, v83
	v_mul_f32_e32 v9, 0x42800000, v85
	v_mov_b32_e32 v5, v34
	v_cvt_pk_fp8_f32 v4, v10, v11 op_sel:[0,0,1]
	v_mul_f32_e32 v10, 0x42800000, v86
	v_cvt_pk_fp8_f32 v5, v9, v10
	v_mul_f32_e32 v11, 0x42800000, v87
	v_mul_f32_e32 v9, 0x42800000, v92
	v_mul_f32_e32 v10, 0x42800000, v96
	v_cvt_pk_fp8_f32 v5, v11, v12 op_sel:[0,0,1]
	v_mul_f32_e32 v11, 0x42800000, v100
	ds_write_b128 v141, v[2:5] offset:64
	v_mul_f32_e32 v3, 0x42800000, v89
	v_mul_f32_e32 v4, 0x42800000, v90
	v_mov_b32_e32 v2, v34
	v_cvt_pk_fp8_f32 v2, v3, v4
	v_mul_f32_e32 v5, 0x42800000, v91
	v_mul_f32_e32 v4, 0x42800000, v93
	v_mov_b32_e32 v3, v34
	v_cvt_pk_fp8_f32 v2, v5, v9 op_sel:[0,0,1]
	v_mul_f32_e32 v5, 0x42800000, v94
	v_cvt_pk_fp8_f32 v3, v4, v5
	v_mul_f32_e32 v9, 0x42800000, v95
	v_mul_f32_e32 v5, 0x42800000, v97
	v_mov_b32_e32 v4, v34
	v_cvt_pk_fp8_f32 v3, v9, v10 op_sel:[0,0,1]
	v_mul_f32_e32 v9, 0x42800000, v98
	v_cvt_pk_fp8_f32 v4, v5, v9
	v_mul_f32_e32 v10, 0x42800000, v99
	v_mul_f32_e32 v9, 0x42800000, v101
	v_mov_b32_e32 v5, v34
	v_cvt_pk_fp8_f32 v4, v10, v11 op_sel:[0,0,1]
	v_mul_f32_e32 v10, 0x42800000, v102
	v_cvt_pk_fp8_f32 v5, v9, v10
	v_mul_f32_e32 v11, 0x42800000, v103
	s_waitcnt vmcnt(24)
	v_mul_f32_e32 v9, 0x42800000, v113
	s_waitcnt vmcnt(20)
	v_mul_f32_e32 v10, 0x42800000, v117
	v_cvt_pk_fp8_f32 v5, v11, v1 op_sel:[0,0,1]
	v_mul_f32_e32 v1, 0x42800000, v106
	s_waitcnt vmcnt(16)
	v_mul_f32_e32 v11, 0x42800000, v121
	ds_write_b128 v141, v[2:5] offset:80
	v_mul_f32_e32 v3, 0x42800000, v107
	v_mov_b32_e32 v2, v34
	v_cvt_pk_fp8_f32 v2, v1, v3
	v_mul_f32_e32 v4, 0x42800000, v108
	v_mul_f32_e32 v5, 0x42800000, v109
	v_mul_f32_e32 v1, 0x42800000, v110
	v_cvt_pk_fp8_f32 v2, v4, v5 op_sel:[0,0,1]
	v_mul_f32_e32 v4, 0x42800000, v111
	v_mov_b32_e32 v3, v34
	v_cvt_pk_fp8_f32 v3, v1, v4
	v_mul_f32_e32 v5, 0x42800000, v112
	v_mul_f32_e32 v1, 0x42800000, v114
	v_mov_b32_e32 v4, v34
	v_cvt_pk_fp8_f32 v3, v5, v9 op_sel:[0,0,1]
	v_mul_f32_e32 v5, 0x42800000, v115
	v_cvt_pk_fp8_f32 v4, v1, v5
	v_mul_f32_e32 v9, 0x42800000, v116
	v_mul_f32_e32 v1, 0x42800000, v118
	v_mov_b32_e32 v5, v34
	v_cvt_pk_fp8_f32 v4, v9, v10 op_sel:[0,0,1]
	v_mul_f32_e32 v9, 0x42800000, v119
	v_cvt_pk_fp8_f32 v5, v1, v9
	v_mul_f32_e32 v10, 0x42800000, v120
	s_waitcnt vmcnt(15)
	v_mul_f32_e32 v1, 0x42800000, v122
	s_waitcnt vmcnt(8)
	v_mul_f32_e32 v9, 0x42800000, v129
	v_cvt_pk_fp8_f32 v5, v10, v11 op_sel:[0,0,1]
	s_waitcnt vmcnt(4)
	v_mul_f32_e32 v10, 0x42800000, v133
	s_waitcnt vmcnt(0)
	v_mul_f32_e32 v11, 0x42800000, v105
	ds_write_b128 v141, v[2:5] offset:96
	v_mul_f32_e32 v3, 0x42800000, v123
	v_mov_b32_e32 v2, v34
	v_cvt_pk_fp8_f32 v2, v1, v3
	v_mul_f32_e32 v4, 0x42800000, v124
	v_mul_f32_e32 v5, 0x42800000, v125
	v_mul_f32_e32 v1, 0x42800000, v126
	v_cvt_pk_fp8_f32 v2, v4, v5 op_sel:[0,0,1]
	v_mul_f32_e32 v4, 0x42800000, v127
	v_mov_b32_e32 v3, v34
	v_cvt_pk_fp8_f32 v3, v1, v4
	v_mul_f32_e32 v5, 0x42800000, v128
	v_mul_f32_e32 v1, 0x42800000, v130
	v_mov_b32_e32 v4, v34
	v_cvt_pk_fp8_f32 v3, v5, v9 op_sel:[0,0,1]
	v_mul_f32_e32 v5, 0x42800000, v131
	v_cvt_pk_fp8_f32 v4, v1, v5
	v_mul_f32_e32 v9, 0x42800000, v132
	v_mul_f32_e32 v1, 0x42800000, v134
	v_mov_b32_e32 v5, v34
	v_cvt_pk_fp8_f32 v4, v9, v10 op_sel:[0,0,1]
	v_mul_f32_e32 v9, 0x42800000, v135
	v_cvt_pk_fp8_f32 v5, v1, v9
	v_mul_f32_e32 v10, 0x42800000, v104
	v_add_u32_e32 v1, s5, v139
	v_cvt_pk_fp8_f32 v5, v10, v11 op_sel:[0,0,1]
	ds_write_b128 v141, v[2:5] offset:112
	v_add_u32_e32 v2, s4, v138
	v_ashrrev_i32_e32 v3, 31, v2
	v_lshlrev_b64 v[2:3], 12, v[2:3]
	v_lshl_add_u64 v[2:3], s[6:7], 0, v[2:3]
	v_lshl_add_u64 v[2:3], v[2:3], 0, s[12:13]
	v_lshl_add_u64 v[10:11], v[2:3], 0, v[6:7]
	ds_read_b128 v[2:5], v1
	s_mov_b32 s4, 0x8000
	v_add_co_u32_e32 v12, vcc, s4, v10
	s_mov_b32 s4, 0x10000
	s_waitcnt lgkmcnt(0)
	global_store_dwordx4 v[10:11], v[2:5], off
	ds_read_b128 v[2:5], v1 offset:1024
	v_addc_co_u32_e32 v13, vcc, 0, v11, vcc
	s_mov_b32 s7, s13
	v_writelane_b32 v252, s6, 15
	s_waitcnt lgkmcnt(0)
	global_store_dwordx4 v[12:13], v[2:5], off
	ds_read_b128 v[2:5], v1 offset:2048
	v_add_co_u32_e32 v12, vcc, s4, v10
	s_mov_b32 s4, 0x18000
	s_nop 0
	v_addc_co_u32_e32 v13, vcc, 0, v11, vcc
	s_waitcnt lgkmcnt(0)
	global_store_dwordx4 v[12:13], v[2:5], off
	ds_read_b128 v[2:5], v1 offset:3072
	v_add_co_u32_e32 v12, vcc, s4, v10
	s_mov_b32 s4, 0x20000
	s_nop 0
	v_addc_co_u32_e32 v13, vcc, 0, v11, vcc
	s_waitcnt lgkmcnt(0)
	global_store_dwordx4 v[12:13], v[2:5], off
	ds_read_b128 v[2:5], v1 offset:4096
	v_add_co_u32_e32 v12, vcc, s4, v10
	v_writelane_b32 v252, s7, 16
	s_nop 0
	v_addc_co_u32_e32 v13, vcc, 0, v11, vcc
	s_waitcnt lgkmcnt(0)
	global_store_dwordx4 v[12:13], v[2:5], off
	ds_read_b128 v[2:5], v1 offset:5120
	v_add_co_u32_e32 v12, vcc, 0x28000, v10
	s_mov_b64 s[4:5], 0
	s_nop 0
	v_addc_co_u32_e32 v13, vcc, 0, v11, vcc
	s_waitcnt lgkmcnt(0)
	global_store_dwordx4 v[12:13], v[2:5], off
	ds_read_b128 v[2:5], v1 offset:6144
	v_add_co_u32_e32 v12, vcc, 0x30000, v10
	s_nop 1
	v_addc_co_u32_e32 v13, vcc, 0, v11, vcc
	s_waitcnt lgkmcnt(0)
	global_store_dwordx4 v[12:13], v[2:5], off
	ds_read_b128 v[2:5], v1 offset:7168
	v_add_co_u32_e32 v10, vcc, 0x38000, v10
	s_nop 1
	v_addc_co_u32_e32 v11, vcc, 0, v11, vcc
	s_waitcnt lgkmcnt(0)
	global_store_dwordx4 v[10:11], v[2:5], off
